# plus: ln_rows split-K partial sums with 7 (ln2) or 4 (ln1) loads in flight, hgprep loads 3 steps ahead, EpiBranch previous-value words 2 ahead
# speedup vs baseline: 1.0375x; 1.0092x over previous
; __device__ __forceinline__ float bflo(unsigned u) { return __uint_as_float(u << 16); }
; __device__ __forceinline__ float bfhi(unsigned u) { return __uint_as_float(u & 0xffff0000u); }
; __device__ __forceinline__ float sigm(float x) { return __builtin_amdgcn_rcpf(1.f + __expf(-x)); }
; __device__ __forceinline__ float silu(float x) { return x * sigm(x); }
; __device__ __forceinline__ void hgprep_phase(const Params& P, int l, LAS unsigned char* lds) {
;     ...
;         const int c = task % NCHUNK, grp = task / NCHUNK, dir = grp & 1, h = (grp >> 1) & 7, b = grp >> 4;
;         const int n0 = c * 16, plo = dir ? (n0 < 256 ? 240 - n0 : TPB + 240 - n0) : n0;
;         const size_t prow = (size_t)b * TPB + (dir ? plo + 15 - t : plo + t);
;         const bf16_t* hp = H + prow * NPAD + h * 128 + 4 * kq;
;         const float* lbp = (const float*)(ws + WS_LB) + ((size_t)l * 2 + dir) * 1024 + h * 128 + 4 * kq;
;         float L[32], kk[32], q[32];
; #pragma unroll
;         for (int j = 0; j < 4; ++j)
; #pragma unroll
;             for (int hh = 0; hh < 2; ++hh) { const int ko = 32 * j + 16 * hh;
;                 const u32x2 fr = *(const u32x2*)(hp + (dir ? C_HGFB : C_HGFF) + ko), qr = *(const u32x2*)(hp + C_HGQ + ko); const f32x4 lb = *(const f32x4*)(lbp + ko);
;                 const float fx[4] = {bflo(fr[0]), bfhi(fr[0]), bflo(fr[1]), bfhi(fr[1])}, qx[4] = {bflo(qr[0]), bfhi(qr[0]), bflo(qr[1]), bfhi(qr[1])};
; #pragma unroll
;                 for (int e = 0; e < 4; ++e) { const int ix = 8 * j + 4 * hh + e; const float f = lb[e] + (1.f - lb[e]) * sigm(fx[e]);
;                     L[ix] = __logf(fmaxf(f, 1e-30f)); kk[ix] = 1.f - f; q[ix] = silu(qx[e]); } }
.LBB0_588:
	v_mul_hi_i32 v1, v0, s78
	v_lshrrev_b32_e32 v2, 31, v1
	v_ashrrev_i32_e32 v1, 7, v1
	v_add_u32_e32 v1, v1, v2
	v_mul_i32_i24_e32 v2, 0x110, v1
	v_sub_u32_e32 v4, v0, v2
	v_cmp_gt_i32_e64 s[14:15], 16, v4
	v_and_b32_e32 v8, 1, v1
	v_lshlrev_b32_e32 v2, 4, v2
	v_cndmask_b32_e64 v4, v230, v231, s[14:15]
	v_sub_u32_e32 v7, v55, v2
	v_cmp_eq_u32_e64 s[12:13], 0, v8
	v_add3_u32 v2, v4, v2, v56
	v_lshrrev_b32_e32 v6, 4, v1
	v_cndmask_b32_e64 v2, v2, v7, s[12:13]
	v_mul_hi_i32_i24_e32 v5, 0x1100, v6
	v_mul_i32_i24_e32 v4, 0x1100, v6
	v_bitop3_b32 v2, v2, 15, v37 bitop3:0x36
	v_add_u32_e32 v6, v7, v37
	v_cndmask_b32_e64 v6, v2, v6, s[12:13]
	v_ashrrev_i32_e32 v7, 31, v6
	v_lshl_add_u64 v[4:5], v[4:5], 0, v[6:7]
	v_mov_b64_e32 v[6:7], s[60:61]
	v_mad_u64_u32 v[6:7], s[12:13], v4, s43, v[6:7]
	v_mov_b32_e32 v2, v7
	v_lshlrev_b32_e32 v1, 6, v1
	v_mad_u64_u32 v[4:5], s[12:13], v5, s43, v[2:3]
	v_and_b32_e32 v1, 0x380, v1
	v_mov_b32_e32 v7, v4
	v_lshlrev_b32_e32 v2, 1, v1
	v_lshl_add_u64 v[4:5], v[6:7], 0, v[2:3]
	v_lshlrev_b32_e32 v2, 1, v36
	v_readlane_b32 s12, v250, 30
	v_lshl_add_u64 v[4:5], v[4:5], 0, v[2:3]
	v_readlane_b32 s13, v250, 31
	v_lshl_or_b32 v2, v8, 10, s12
	v_lshl_add_u64 v[6:7], v[2:3], 2, s[40:41]
	v_lshlrev_b32_e32 v2, 2, v1
	v_lshl_add_u64 v[6:7], v[6:7], 0, v[2:3]
	v_lshlrev_b32_e32 v2, 2, v36
	v_lshl_add_u64 v[32:33], v[6:7], 0, v[2:3]
	v_lshlrev_b32_e32 v6, 11, v8
	v_mov_b32_e32 v7, v3
	v_lshl_add_u64 v[34:35], v[4:5], 0, v[6:7]
	global_load_dwordx2 v[8:9], v[34:35], off
	s_movk_i32 s3, 0x2000
	v_add_co_u32_e64 v48, s[12:13], s3, v4
	s_waitcnt vmcnt(0)
	v_lshlrev_b32_e32 v1, 16, v8
	v_addc_co_u32_e64 v49, s[12:13], 0, v5, s[12:13]
	global_load_dwordx2 v[44:45], v[48:49], off offset:1088
	global_load_dwordx4 v[4:7], v[32:33], off
	global_load_dwordx2 v[206:207], v[34:35], off offset:32
	global_load_dwordx2 v[208:209], v[48:49], off offset:1120
	global_load_dwordx4 v[210:213], v[32:33], off offset:64
	global_load_dwordx2 v[214:215], v[34:35], off offset:64
	global_load_dwordx2 v[216:217], v[48:49], off offset:1152
	global_load_dwordx4 v[234:237], v[32:33], off offset:128
	global_load_dwordx2 v[238:239], v[34:35], off offset:96
	global_load_dwordx2 v[240:241], v[48:49], off offset:1184
	global_load_dwordx4 v[244:247], v[32:33], off offset:192
	v_mul_f32_e32 v1, 0xbfb8aa3b, v1
	v_exp_f32_e32 v1, v1
	v_and_b32_e32 v8, 0xffff0000, v8
	v_lshlrev_b32_e32 v10, 16, v9
	v_and_b32_e32 v9, 0xffff0000, v9
	v_add_f32_e32 v1, 1.0, v1
	v_rcp_f32_e32 v1, v1
	s_waitcnt vmcnt(9)
	v_sub_f32_e32 v11, 1.0, v4
	v_fma_f32 v58, v11, v1, v4
	v_max_f32_e32 v1, 0xda24260, v58
	v_cmp_gt_f32_e64 s[12:13], s58, v1
	s_nop 1
	v_cndmask_b32_e64 v4, 0, 32, s[12:13]
	v_ldexp_f32 v1, v1, v4
	v_log_f32_e32 v1, v1
	s_nop 0
	v_mul_f32_e32 v4, 0x3f317217, v1
	v_fma_f32 v4, v1, s23, -v4
	v_fmac_f32_e32 v4, 0x3377d1cf, v1
	v_fmac_f32_e32 v4, 0x3f317217, v1
	v_cmp_lt_f32_e64 s[14:15], |v1|, s31
	s_nop 1
	v_cndmask_b32_e64 v1, v1, v4, s[14:15]
	v_cndmask_b32_e64 v4, 0, v227, s[12:13]
	v_sub_f32_e32 v46, v1, v4
	v_mul_f32_e32 v4, 0xbfb8aa3b, v8
	v_exp_f32_e32 v4, v4
	v_sub_f32_e32 v1, 1.0, v5
	v_add_f32_e32 v4, 1.0, v4
	v_rcp_f32_e32 v4, v4
	s_nop 0
	v_fma_f32 v59, v1, v4, v5
	v_max_f32_e32 v1, 0xda24260, v59
	v_cmp_gt_f32_e64 s[12:13], s58, v1
	v_mul_f32_e32 v5, 0xbfb8aa3b, v10
	v_exp_f32_e32 v5, v5
	v_cndmask_b32_e64 v4, 0, 32, s[12:13]
	v_ldexp_f32 v1, v1, v4
	v_log_f32_e32 v1, v1
	v_add_f32_e32 v5, 1.0, v5
	v_rcp_f32_e32 v5, v5
	v_mul_f32_e32 v4, 0x3f317217, v1
	v_fma_f32 v4, v1, s23, -v4
	v_fmac_f32_e32 v4, 0x3377d1cf, v1
	v_fmac_f32_e32 v4, 0x3f317217, v1
	v_cmp_lt_f32_e64 s[14:15], |v1|, s31
	s_nop 1
	v_cndmask_b32_e64 v1, v1, v4, s[14:15]
	v_cndmask_b32_e64 v4, 0, v227, s[12:13]
	v_sub_f32_e32 v1, v1, v4
	v_sub_f32_e32 v4, 1.0, v6
	v_fma_f32 v6, v4, v5, v6
	v_max_f32_e32 v4, 0xda24260, v6
	v_cmp_gt_f32_e64 s[12:13], s58, v4
	s_nop 1
	v_cndmask_b32_e64 v5, 0, 32, s[12:13]
	v_ldexp_f32 v4, v4, v5
	v_log_f32_e32 v4, v4
	s_nop 0
	v_mul_f32_e32 v5, 0x3f317217, v4
	v_fma_f32 v5, v4, s23, -v5
	v_fmac_f32_e32 v5, 0x3377d1cf, v4
	v_fmac_f32_e32 v5, 0x3f317217, v4
	v_cmp_lt_f32_e64 s[14:15], |v4|, s31
	s_nop 1
	v_cndmask_b32_e64 v4, v4, v5, s[14:15]
	v_cndmask_b32_e64 v5, 0, v227, s[12:13]
	v_sub_f32_e32 v47, v4, v5
	v_mul_f32_e32 v5, 0xbfb8aa3b, v9
	v_exp_f32_e32 v5, v5
	v_sub_f32_e32 v4, 1.0, v7
	v_add_f32_e32 v5, 1.0, v5
	v_rcp_f32_e32 v5, v5
	s_nop 0
	v_fmac_f32_e32 v7, v4, v5
	v_max_f32_e32 v4, 0xda24260, v7
	v_cmp_gt_f32_e64 s[12:13], s58, v4
	s_nop 1
	v_cndmask_b32_e64 v5, 0, 32, s[12:13]
	v_ldexp_f32 v4, v4, v5
	v_log_f32_e32 v4, v4
	s_nop 0
	v_mul_f32_e32 v5, 0x3f317217, v4
	v_fma_f32 v5, v4, s23, -v5
	v_fmac_f32_e32 v5, 0x3377d1cf, v4
	v_fmac_f32_e32 v5, 0x3f317217, v4
	v_cmp_lt_f32_e64 s[14:15], |v4|, s31
	s_nop 1
	v_cndmask_b32_e64 v4, v4, v5, s[14:15]
	v_cndmask_b32_e64 v5, 0, v227, s[12:13]
	v_sub_f32_e32 v62, v4, v5
	s_waitcnt vmcnt(6)
; __device__ __forceinline__ float bflo(unsigned u) { return __uint_as_float(u << 16); }
; __device__ __forceinline__ float bfhi(unsigned u) { return __uint_as_float(u & 0xffff0000u); }
; __device__ __forceinline__ float sigm(float x) { return __builtin_amdgcn_rcpf(1.f + __expf(-x)); }
; __device__ __forceinline__ float silu(float x) { return x * sigm(x); }
; __device__ __forceinline__ void hgprep_phase(const Params& P, int l, LAS unsigned char* lds) {
;     ...
;         for (int j = 0; j < 4; ++j)
; #pragma unroll
;             for (int hh = 0; hh < 2; ++hh) { const int ko = 32 * j + 16 * hh;
;                 const u32x2 fr = *(const u32x2*)(hp + (dir ? C_HGFB : C_HGFF) + ko), qr = *(const u32x2*)(hp + C_HGQ + ko); const f32x4 lb = *(const f32x4*)(lbp + ko);
;                 const float fx[4] = {bflo(fr[0]), bfhi(fr[0]), bflo(fr[1]), bfhi(fr[1])}, qx[4] = {bflo(qr[0]), bfhi(qr[0]), bflo(qr[1]), bfhi(qr[1])};
; #pragma unroll
;                 for (int e = 0; e < 4; ++e) { const int ix = 8 * j + 4 * hh + e; const float f = lb[e] + (1.f - lb[e]) * sigm(fx[e]);
;                     L[ix] = __logf(fmaxf(f, 1e-30f)); kk[ix] = 1.f - f; q[ix] = silu(qx[e]); } }
	v_mov_b64_e32 v[12:13], v[206:207]
	v_mov_b64_e32 v[4:5], v[208:209]
	v_mov_b64_e32 v[8:9], v[210:211]
	v_mov_b64_e32 v[10:11], v[212:213]
	global_load_dwordx2 v[206:207], v[34:35], off offset:128
	global_load_dwordx2 v[208:209], v[48:49], off offset:1216
	global_load_dwordx4 v[210:213], v[32:33], off offset:256
	v_lshlrev_b32_e32 v14, 16, v12
	v_mul_f32_e32 v14, 0xbfb8aa3b, v14
	v_exp_f32_e32 v14, v14
	v_sub_f32_e32 v16, 1.0, v8
	v_and_b32_e32 v12, 0xffff0000, v12
	v_mul_f32_e32 v12, 0xbfb8aa3b, v12
	v_add_f32_e32 v14, 1.0, v14
	v_rcp_f32_e32 v14, v14
	v_exp_f32_e32 v12, v12
	v_lshlrev_b32_e32 v15, 16, v13
	v_and_b32_e32 v13, 0xffff0000, v13
	v_fma_f32 v60, v16, v14, v8
	v_max_f32_e32 v8, 0xda24260, v60
	v_cmp_gt_f32_e64 s[12:13], s58, v8
	v_add_f32_e32 v12, 1.0, v12
	v_rcp_f32_e32 v12, v12
	v_cndmask_b32_e64 v14, 0, 32, s[12:13]
	v_ldexp_f32 v8, v8, v14
	v_log_f32_e32 v8, v8
	s_nop 0
	v_mul_f32_e32 v14, 0x3f317217, v8
	v_fma_f32 v14, v8, s23, -v14
	v_fmac_f32_e32 v14, 0x3377d1cf, v8
	v_fmac_f32_e32 v14, 0x3f317217, v8
	v_cmp_lt_f32_e64 s[14:15], |v8|, s31
	s_nop 1
	v_cndmask_b32_e64 v8, v8, v14, s[14:15]
	v_cndmask_b32_e64 v14, 0, v227, s[12:13]
	v_sub_f32_e32 v65, v8, v14
	v_sub_f32_e32 v8, 1.0, v9
	v_fma_f32 v61, v8, v12, v9
	v_max_f32_e32 v8, 0xda24260, v61
	v_cmp_gt_f32_e64 s[12:13], s58, v8
	s_nop 1
	v_cndmask_b32_e64 v9, 0, 32, s[12:13]
	v_ldexp_f32 v8, v8, v9
	v_log_f32_e32 v8, v8
	s_nop 0
	v_mul_f32_e32 v9, 0x3f317217, v8
	v_fma_f32 v9, v8, s23, -v9
	v_fmac_f32_e32 v9, 0x3377d1cf, v8
	v_fmac_f32_e32 v9, 0x3f317217, v8
	v_cmp_lt_f32_e64 s[14:15], |v8|, s31
	s_nop 1
	v_cndmask_b32_e64 v8, v8, v9, s[14:15]
	v_cndmask_b32_e64 v9, 0, v227, s[12:13]
	v_sub_f32_e32 v66, v8, v9
	v_mul_f32_e32 v9, 0xbfb8aa3b, v15
	v_exp_f32_e32 v9, v9
	v_sub_f32_e32 v8, 1.0, v10
	v_add_f32_e32 v9, 1.0, v9
	v_rcp_f32_e32 v9, v9
	s_nop 0
	v_fma_f32 v10, v8, v9, v10
	v_max_f32_e32 v8, 0xda24260, v10
	v_cmp_gt_f32_e64 s[12:13], s58, v8
	s_nop 1
	v_cndmask_b32_e64 v9, 0, 32, s[12:13]
	v_ldexp_f32 v8, v8, v9
	v_log_f32_e32 v8, v8
	s_nop 0
	v_mul_f32_e32 v9, 0x3f317217, v8
	v_fma_f32 v9, v8, s23, -v9
	v_fmac_f32_e32 v9, 0x3377d1cf, v8
	v_fmac_f32_e32 v9, 0x3f317217, v8
	v_cmp_lt_f32_e64 s[14:15], |v8|, s31
	s_nop 1
	v_cndmask_b32_e64 v8, v8, v9, s[14:15]
	v_cndmask_b32_e64 v9, 0, v227, s[12:13]
	v_sub_f32_e32 v67, v8, v9
	v_mul_f32_e32 v9, 0xbfb8aa3b, v13
	v_exp_f32_e32 v9, v9
	v_sub_f32_e32 v8, 1.0, v11
	v_add_f32_e32 v9, 1.0, v9
	v_rcp_f32_e32 v9, v9
	s_nop 0
	v_fmac_f32_e32 v11, v8, v9
	v_max_f32_e32 v8, 0xda24260, v11
	v_cmp_gt_f32_e64 s[12:13], s58, v8
	s_nop 1
	v_cndmask_b32_e64 v9, 0, 32, s[12:13]
	v_ldexp_f32 v8, v8, v9
	v_log_f32_e32 v8, v8
	s_nop 0
	v_mul_f32_e32 v9, 0x3f317217, v8
	v_fma_f32 v9, v8, s23, -v9
	v_fmac_f32_e32 v9, 0x3377d1cf, v8
	v_fmac_f32_e32 v9, 0x3f317217, v8
	v_cmp_lt_f32_e64 s[14:15], |v8|, s31
	s_nop 1
	v_cndmask_b32_e64 v8, v8, v9, s[14:15]
	v_cndmask_b32_e64 v9, 0, v227, s[12:13]
	v_sub_f32_e32 v68, v8, v9
	s_waitcnt vmcnt(6)
	v_mov_b64_e32 v[16:17], v[214:215]
	v_mov_b64_e32 v[8:9], v[216:217]
	v_mov_b64_e32 v[12:13], v[234:235]
	v_mov_b64_e32 v[14:15], v[236:237]
	global_load_dwordx2 v[214:215], v[34:35], off offset:160
	global_load_dwordx2 v[216:217], v[48:49], off offset:1248
	global_load_dwordx4 v[234:237], v[32:33], off offset:320
	v_lshlrev_b32_e32 v18, 16, v16
	v_mul_f32_e32 v18, 0xbfb8aa3b, v18
	v_exp_f32_e32 v18, v18
	v_sub_f32_e32 v20, 1.0, v12
	v_and_b32_e32 v16, 0xffff0000, v16
	v_mul_f32_e32 v16, 0xbfb8aa3b, v16
	v_add_f32_e32 v18, 1.0, v18
	v_rcp_f32_e32 v18, v18
	v_exp_f32_e32 v16, v16
	v_lshlrev_b32_e32 v19, 16, v17
	v_and_b32_e32 v17, 0xffff0000, v17
	v_fma_f32 v63, v20, v18, v12
	v_max_f32_e32 v12, 0xda24260, v63
	v_cmp_gt_f32_e64 s[12:13], s58, v12
	v_add_f32_e32 v16, 1.0, v16
	v_rcp_f32_e32 v16, v16
	v_cndmask_b32_e64 v18, 0, 32, s[12:13]
	v_ldexp_f32 v12, v12, v18
	v_log_f32_e32 v12, v12
	s_nop 0
	v_mul_f32_e32 v18, 0x3f317217, v12
	v_fma_f32 v18, v12, s23, -v18
	v_fmac_f32_e32 v18, 0x3377d1cf, v12
	v_fmac_f32_e32 v18, 0x3f317217, v12
	v_cmp_lt_f32_e64 s[14:15], |v12|, s31
	s_nop 1
	v_cndmask_b32_e64 v12, v12, v18, s[14:15]
	v_cndmask_b32_e64 v18, 0, v227, s[12:13]
	v_sub_f32_e32 v69, v12, v18
	v_sub_f32_e32 v12, 1.0, v13
	v_fma_f32 v64, v12, v16, v13
	v_max_f32_e32 v12, 0xda24260, v64
	v_cmp_gt_f32_e64 s[12:13], s58, v12
	s_nop 1
	v_cndmask_b32_e64 v13, 0, 32, s[12:13]
	v_ldexp_f32 v12, v12, v13
	v_log_f32_e32 v12, v12
	s_nop 0
	v_mul_f32_e32 v13, 0x3f317217, v12
	v_fma_f32 v13, v12, s23, -v13
	v_fmac_f32_e32 v13, 0x3377d1cf, v12
	v_fmac_f32_e32 v13, 0x3f317217, v12
	v_cmp_lt_f32_e64 s[14:15], |v12|, s31
	s_nop 1
	v_cndmask_b32_e64 v12, v12, v13, s[14:15]
	v_cndmask_b32_e64 v13, 0, v227, s[12:13]
	v_sub_f32_e32 v70, v12, v13
	v_mul_f32_e32 v13, 0xbfb8aa3b, v19
	v_exp_f32_e32 v13, v13
	v_sub_f32_e32 v12, 1.0, v14
	v_add_f32_e32 v13, 1.0, v13
	v_rcp_f32_e32 v13, v13
	s_nop 0
	v_fma_f32 v14, v12, v13, v14
	v_max_f32_e32 v12, 0xda24260, v14
	v_cmp_gt_f32_e64 s[12:13], s58, v12
	s_nop 1
	v_cndmask_b32_e64 v13, 0, 32, s[12:13]
	v_ldexp_f32 v12, v12, v13
	v_log_f32_e32 v12, v12
	s_nop 0
	v_mul_f32_e32 v13, 0x3f317217, v12
	v_fma_f32 v13, v12, s23, -v13
	v_fmac_f32_e32 v13, 0x3377d1cf, v12
	v_fmac_f32_e32 v13, 0x3f317217, v12
	v_cmp_lt_f32_e64 s[14:15], |v12|, s31
	s_nop 1
	v_cndmask_b32_e64 v12, v12, v13, s[14:15]
	v_cndmask_b32_e64 v13, 0, v227, s[12:13]
	v_sub_f32_e32 v71, v12, v13
	v_mul_f32_e32 v13, 0xbfb8aa3b, v17
	v_exp_f32_e32 v13, v13
	v_sub_f32_e32 v12, 1.0, v15
	v_add_f32_e32 v13, 1.0, v13
	v_rcp_f32_e32 v13, v13
	s_nop 0
	v_fmac_f32_e32 v15, v12, v13
	v_max_f32_e32 v12, 0xda24260, v15
	v_cmp_gt_f32_e64 s[12:13], s58, v12
	s_nop 1
	v_cndmask_b32_e64 v13, 0, 32, s[12:13]
	v_ldexp_f32 v12, v12, v13
	v_log_f32_e32 v12, v12
	s_nop 0
	v_mul_f32_e32 v13, 0x3f317217, v12
	v_fma_f32 v13, v12, s23, -v13
	v_fmac_f32_e32 v13, 0x3377d1cf, v12
	v_fmac_f32_e32 v13, 0x3f317217, v12
	v_cmp_lt_f32_e64 s[14:15], |v12|, s31
	s_nop 1
	v_cndmask_b32_e64 v12, v12, v13, s[14:15]
	v_cndmask_b32_e64 v13, 0, v227, s[12:13]
	v_sub_f32_e32 v72, v12, v13
	s_waitcnt vmcnt(6)
; __device__ __forceinline__ float bflo(unsigned u) { return __uint_as_float(u << 16); }
; __device__ __forceinline__ float bfhi(unsigned u) { return __uint_as_float(u & 0xffff0000u); }
; __device__ __forceinline__ float sigm(float x) { return __builtin_amdgcn_rcpf(1.f + __expf(-x)); }
; __device__ __forceinline__ float silu(float x) { return x * sigm(x); }
; __device__ __forceinline__ void hgprep_phase(const Params& P, int l, LAS unsigned char* lds) {
;     ...
;         for (int j = 0; j < 4; ++j)
; #pragma unroll
;             for (int hh = 0; hh < 2; ++hh) { const int ko = 32 * j + 16 * hh;
;                 const u32x2 fr = *(const u32x2*)(hp + (dir ? C_HGFB : C_HGFF) + ko), qr = *(const u32x2*)(hp + C_HGQ + ko); const f32x4 lb = *(const f32x4*)(lbp + ko);
;                 const float fx[4] = {bflo(fr[0]), bfhi(fr[0]), bflo(fr[1]), bfhi(fr[1])}, qx[4] = {bflo(qr[0]), bfhi(qr[0]), bflo(qr[1]), bfhi(qr[1])};
; #pragma unroll
;                 for (int e = 0; e < 4; ++e) { const int ix = 8 * j + 4 * hh + e; const float f = lb[e] + (1.f - lb[e]) * sigm(fx[e]);
;                     L[ix] = __logf(fmaxf(f, 1e-30f)); kk[ix] = 1.f - f; q[ix] = silu(qx[e]); } }
	v_mov_b64_e32 v[20:21], v[238:239]
	v_mov_b64_e32 v[12:13], v[240:241]
	v_mov_b64_e32 v[16:17], v[244:245]
	v_mov_b64_e32 v[18:19], v[246:247]
	global_load_dwordx2 v[238:239], v[34:35], off offset:192
	global_load_dwordx2 v[240:241], v[48:49], off offset:1280
	global_load_dwordx4 v[244:247], v[32:33], off offset:384
	v_lshlrev_b32_e32 v22, 16, v20
	v_mul_f32_e32 v22, 0xbfb8aa3b, v22
	v_exp_f32_e32 v22, v22
	v_sub_f32_e32 v24, 1.0, v16
	v_and_b32_e32 v20, 0xffff0000, v20
	v_mul_f32_e32 v20, 0xbfb8aa3b, v20
	v_add_f32_e32 v22, 1.0, v22
	v_rcp_f32_e32 v22, v22
	v_exp_f32_e32 v20, v20
	v_lshlrev_b32_e32 v23, 16, v21
	v_and_b32_e32 v21, 0xffff0000, v21
	v_fma_f32 v73, v24, v22, v16
	v_max_f32_e32 v16, 0xda24260, v73
	v_cmp_gt_f32_e64 s[12:13], s58, v16
	v_add_f32_e32 v20, 1.0, v20
	v_rcp_f32_e32 v20, v20
	v_cndmask_b32_e64 v22, 0, 32, s[12:13]
	v_ldexp_f32 v16, v16, v22
	v_log_f32_e32 v16, v16
	s_nop 0
	v_mul_f32_e32 v22, 0x3f317217, v16
	v_fma_f32 v22, v16, s23, -v22
	v_fmac_f32_e32 v22, 0x3377d1cf, v16
	v_fmac_f32_e32 v22, 0x3f317217, v16
	v_cmp_lt_f32_e64 s[14:15], |v16|, s31
	s_nop 1
	v_cndmask_b32_e64 v16, v16, v22, s[14:15]
	v_cndmask_b32_e64 v22, 0, v227, s[12:13]
	v_sub_f32_e32 v77, v16, v22
	v_sub_f32_e32 v16, 1.0, v17
	v_fma_f32 v74, v16, v20, v17
	v_max_f32_e32 v16, 0xda24260, v74
	v_cmp_gt_f32_e64 s[12:13], s58, v16
	s_nop 1
	v_cndmask_b32_e64 v17, 0, 32, s[12:13]
	v_ldexp_f32 v16, v16, v17
	v_log_f32_e32 v16, v16
	s_nop 0
	v_mul_f32_e32 v17, 0x3f317217, v16
	v_fma_f32 v17, v16, s23, -v17
	v_fmac_f32_e32 v17, 0x3377d1cf, v16
	v_fmac_f32_e32 v17, 0x3f317217, v16
	v_cmp_lt_f32_e64 s[14:15], |v16|, s31
	s_nop 1
	v_cndmask_b32_e64 v16, v16, v17, s[14:15]
	v_cndmask_b32_e64 v17, 0, v227, s[12:13]
	v_sub_f32_e32 v78, v16, v17
	v_mul_f32_e32 v17, 0xbfb8aa3b, v23
	v_exp_f32_e32 v17, v17
	v_sub_f32_e32 v16, 1.0, v18
	v_add_f32_e32 v17, 1.0, v17
	v_rcp_f32_e32 v17, v17
	s_nop 0
	v_fma_f32 v76, v16, v17, v18
	v_max_f32_e32 v16, 0xda24260, v76
	v_cmp_gt_f32_e64 s[12:13], s58, v16
	s_nop 1
	v_cndmask_b32_e64 v17, 0, 32, s[12:13]
	v_ldexp_f32 v16, v16, v17
	v_log_f32_e32 v16, v16
	s_nop 0
	v_mul_f32_e32 v17, 0x3f317217, v16
	v_fma_f32 v17, v16, s23, -v17
	v_fmac_f32_e32 v17, 0x3377d1cf, v16
	v_fmac_f32_e32 v17, 0x3f317217, v16
	v_cmp_lt_f32_e64 s[14:15], |v16|, s31
	s_nop 1
	v_cndmask_b32_e64 v16, v16, v17, s[14:15]
	v_cndmask_b32_e64 v17, 0, v227, s[12:13]
	v_sub_f32_e32 v79, v16, v17
	v_mul_f32_e32 v17, 0xbfb8aa3b, v21
	v_exp_f32_e32 v17, v17
	v_sub_f32_e32 v16, 1.0, v19
	v_add_f32_e32 v17, 1.0, v17
	v_rcp_f32_e32 v17, v17
	s_nop 0
	v_fmac_f32_e32 v19, v16, v17
	v_max_f32_e32 v16, 0xda24260, v19
	v_cmp_gt_f32_e64 s[12:13], s58, v16
	s_nop 1
	v_cndmask_b32_e64 v17, 0, 32, s[12:13]
	v_ldexp_f32 v16, v16, v17
	v_log_f32_e32 v16, v16
	s_nop 0
	v_mul_f32_e32 v17, 0x3f317217, v16
	v_fma_f32 v17, v16, s23, -v17
	v_fmac_f32_e32 v17, 0x3377d1cf, v16
	v_fmac_f32_e32 v17, 0x3f317217, v16
	v_cmp_lt_f32_e64 s[14:15], |v16|, s31
	s_nop 1
	v_cndmask_b32_e64 v16, v16, v17, s[14:15]
	v_cndmask_b32_e64 v17, 0, v227, s[12:13]
	v_sub_f32_e32 v80, v16, v17
	s_waitcnt vmcnt(6)
	v_mov_b64_e32 v[24:25], v[206:207]
	v_mov_b64_e32 v[16:17], v[208:209]
	v_mov_b64_e32 v[20:21], v[210:211]
	v_mov_b64_e32 v[22:23], v[212:213]
	global_load_dwordx2 v[206:207], v[34:35], off offset:224
	global_load_dwordx2 v[208:209], v[48:49], off offset:1312
	global_load_dwordx4 v[210:213], v[32:33], off offset:448
	v_lshlrev_b32_e32 v18, 16, v24
	v_mul_f32_e32 v18, 0xbfb8aa3b, v18
	v_exp_f32_e32 v18, v18
	v_sub_f32_e32 v27, 1.0, v20
	v_and_b32_e32 v24, 0xffff0000, v24
	v_mul_f32_e32 v24, 0xbfb8aa3b, v24
	v_add_f32_e32 v18, 1.0, v18
	v_rcp_f32_e32 v18, v18
	v_exp_f32_e32 v24, v24
	v_lshlrev_b32_e32 v26, 16, v25
	v_and_b32_e32 v25, 0xffff0000, v25
	v_fma_f32 v18, v27, v18, v20
	v_max_f32_e32 v20, 0xda24260, v18
	v_cmp_gt_f32_e64 s[12:13], s58, v20
	v_add_f32_e32 v24, 1.0, v24
	v_rcp_f32_e32 v24, v24
	v_cndmask_b32_e64 v27, 0, 32, s[12:13]
	v_ldexp_f32 v20, v20, v27
	v_log_f32_e32 v20, v20
	s_nop 0
	v_mul_f32_e32 v27, 0x3f317217, v20
	v_fma_f32 v27, v20, s23, -v27
	v_fmac_f32_e32 v27, 0x3377d1cf, v20
	v_fmac_f32_e32 v27, 0x3f317217, v20
	v_cmp_lt_f32_e64 s[14:15], |v20|, s31
	s_nop 1
	v_cndmask_b32_e64 v20, v20, v27, s[14:15]
	v_cndmask_b32_e64 v27, 0, v227, s[12:13]
	v_sub_f32_e32 v85, v20, v27
	v_sub_f32_e32 v20, 1.0, v21
	v_fma_f32 v75, v20, v24, v21
	v_max_f32_e32 v20, 0xda24260, v75
	v_cmp_gt_f32_e64 s[12:13], s58, v20
	s_nop 1
	v_cndmask_b32_e64 v21, 0, 32, s[12:13]
	v_ldexp_f32 v20, v20, v21
	v_log_f32_e32 v20, v20
	s_nop 0
	v_mul_f32_e32 v21, 0x3f317217, v20
	v_fma_f32 v21, v20, s23, -v21
	v_fmac_f32_e32 v21, 0x3377d1cf, v20
	v_fmac_f32_e32 v21, 0x3f317217, v20
	v_cmp_lt_f32_e64 s[14:15], |v20|, s31
	s_nop 1
	v_cndmask_b32_e64 v20, v20, v21, s[14:15]
	v_cndmask_b32_e64 v21, 0, v227, s[12:13]
	v_sub_f32_e32 v86, v20, v21
	v_mul_f32_e32 v21, 0xbfb8aa3b, v26
	v_exp_f32_e32 v21, v21
	v_sub_f32_e32 v20, 1.0, v22
	v_add_f32_e32 v21, 1.0, v21
	v_rcp_f32_e32 v21, v21
	s_nop 0
	v_fma_f32 v22, v20, v21, v22
	v_max_f32_e32 v20, 0xda24260, v22
	v_cmp_gt_f32_e64 s[12:13], s58, v20
	s_nop 1
	v_cndmask_b32_e64 v21, 0, 32, s[12:13]
	v_ldexp_f32 v20, v20, v21
	v_log_f32_e32 v20, v20
	s_nop 0
	v_mul_f32_e32 v21, 0x3f317217, v20
	v_fma_f32 v21, v20, s23, -v21
	v_fmac_f32_e32 v21, 0x3377d1cf, v20
	v_fmac_f32_e32 v21, 0x3f317217, v20
	v_cmp_lt_f32_e64 s[14:15], |v20|, s31
	s_nop 1
	v_cndmask_b32_e64 v20, v20, v21, s[14:15]
	v_cndmask_b32_e64 v21, 0, v227, s[12:13]
	v_sub_f32_e32 v87, v20, v21
	v_mul_f32_e32 v21, 0xbfb8aa3b, v25
	v_exp_f32_e32 v21, v21
	v_sub_f32_e32 v20, 1.0, v23
	v_add_f32_e32 v21, 1.0, v21
	v_rcp_f32_e32 v21, v21
	s_nop 0
	v_fmac_f32_e32 v23, v20, v21
	v_max_f32_e32 v20, 0xda24260, v23
	v_cmp_gt_f32_e64 s[12:13], s58, v20
	s_nop 1
	v_cndmask_b32_e64 v21, 0, 32, s[12:13]
	v_ldexp_f32 v20, v20, v21
	v_log_f32_e32 v20, v20
	s_nop 0
	v_mul_f32_e32 v21, 0x3f317217, v20
	v_fma_f32 v21, v20, s23, -v21
	v_fmac_f32_e32 v21, 0x3377d1cf, v20
	v_fmac_f32_e32 v21, 0x3f317217, v20
	v_cmp_lt_f32_e64 s[14:15], |v20|, s31
	s_nop 1
	v_cndmask_b32_e64 v20, v20, v21, s[14:15]
	v_cndmask_b32_e64 v21, 0, v227, s[12:13]
	v_sub_f32_e32 v88, v20, v21
	s_waitcnt vmcnt(6)
; __device__ __forceinline__ float bflo(unsigned u) { return __uint_as_float(u << 16); }
; __device__ __forceinline__ float bfhi(unsigned u) { return __uint_as_float(u & 0xffff0000u); }
; __device__ __forceinline__ float sigm(float x) { return __builtin_amdgcn_rcpf(1.f + __expf(-x)); }
; __device__ __forceinline__ float silu(float x) { return x * sigm(x); }
; __device__ __forceinline__ void hgprep_phase(const Params& P, int l, LAS unsigned char* lds) {
;     ...
;         for (int j = 0; j < 4; ++j)
; #pragma unroll
;             for (int hh = 0; hh < 2; ++hh) { const int ko = 32 * j + 16 * hh;
;                 const u32x2 fr = *(const u32x2*)(hp + (dir ? C_HGFB : C_HGFF) + ko), qr = *(const u32x2*)(hp + C_HGQ + ko); const f32x4 lb = *(const f32x4*)(lbp + ko);
;                 const float fx[4] = {bflo(fr[0]), bfhi(fr[0]), bflo(fr[1]), bfhi(fr[1])}, qx[4] = {bflo(qr[0]), bfhi(qr[0]), bflo(qr[1]), bfhi(qr[1])};
; #pragma unroll
;                 for (int e = 0; e < 4; ++e) { const int ix = 8 * j + 4 * hh + e; const float f = lb[e] + (1.f - lb[e]) * sigm(fx[e]);
;                     L[ix] = __logf(fmaxf(f, 1e-30f)); kk[ix] = 1.f - f; q[ix] = silu(qx[e]); } }
	v_mov_b64_e32 v[28:29], v[214:215]
	v_mov_b64_e32 v[20:21], v[216:217]
	v_mov_b64_e32 v[24:25], v[234:235]
	v_mov_b64_e32 v[26:27], v[236:237]
	v_lshlrev_b32_e32 v30, 16, v28
	v_mul_f32_e32 v30, 0xbfb8aa3b, v30
	v_exp_f32_e32 v30, v30
	v_sub_f32_e32 v50, 1.0, v24
	v_and_b32_e32 v28, 0xffff0000, v28
	v_mul_f32_e32 v28, 0xbfb8aa3b, v28
	v_add_f32_e32 v30, 1.0, v30
	v_rcp_f32_e32 v30, v30
	v_exp_f32_e32 v28, v28
	v_lshlrev_b32_e32 v31, 16, v29
	v_and_b32_e32 v29, 0xffff0000, v29
	v_fma_f32 v81, v50, v30, v24
	v_max_f32_e32 v24, 0xda24260, v81
	v_cmp_gt_f32_e64 s[12:13], s58, v24
	v_add_f32_e32 v28, 1.0, v28
	v_rcp_f32_e32 v28, v28
	v_cndmask_b32_e64 v30, 0, 32, s[12:13]
	v_ldexp_f32 v24, v24, v30
	v_log_f32_e32 v24, v24
	s_nop 0
	v_mul_f32_e32 v30, 0x3f317217, v24
	v_fma_f32 v30, v24, s23, -v30
	v_fmac_f32_e32 v30, 0x3377d1cf, v24
	v_fmac_f32_e32 v30, 0x3f317217, v24
	v_cmp_lt_f32_e64 s[14:15], |v24|, s31
	s_nop 1
	v_cndmask_b32_e64 v24, v24, v30, s[14:15]
	v_cndmask_b32_e64 v30, 0, v227, s[12:13]
	v_sub_f32_e32 v89, v24, v30
	v_sub_f32_e32 v24, 1.0, v25
	v_fma_f32 v82, v24, v28, v25
	v_max_f32_e32 v24, 0xda24260, v82
	v_cmp_gt_f32_e64 s[12:13], s58, v24
	s_nop 1
	v_cndmask_b32_e64 v25, 0, 32, s[12:13]
	v_ldexp_f32 v24, v24, v25
	v_log_f32_e32 v24, v24
	s_nop 0
	v_mul_f32_e32 v25, 0x3f317217, v24
	v_fma_f32 v25, v24, s23, -v25
	v_fmac_f32_e32 v25, 0x3377d1cf, v24
	v_fmac_f32_e32 v25, 0x3f317217, v24
	v_cmp_lt_f32_e64 s[14:15], |v24|, s31
	s_nop 1
	v_cndmask_b32_e64 v24, v24, v25, s[14:15]
	v_cndmask_b32_e64 v25, 0, v227, s[12:13]
	v_sub_f32_e32 v90, v24, v25
	v_mul_f32_e32 v25, 0xbfb8aa3b, v31
	v_exp_f32_e32 v25, v25
	v_sub_f32_e32 v24, 1.0, v26
	v_add_f32_e32 v25, 1.0, v25
	v_rcp_f32_e32 v25, v25
	s_nop 0
	v_fma_f32 v26, v24, v25, v26
	v_max_f32_e32 v24, 0xda24260, v26
	v_cmp_gt_f32_e64 s[12:13], s58, v24
	s_nop 1
	v_cndmask_b32_e64 v25, 0, 32, s[12:13]
	v_ldexp_f32 v24, v24, v25
	v_log_f32_e32 v24, v24
	s_nop 0
	v_mul_f32_e32 v25, 0x3f317217, v24
	v_fma_f32 v25, v24, s23, -v25
	v_fmac_f32_e32 v25, 0x3377d1cf, v24
	v_fmac_f32_e32 v25, 0x3f317217, v24
	v_cmp_lt_f32_e64 s[14:15], |v24|, s31
	s_nop 1
	v_cndmask_b32_e64 v24, v24, v25, s[14:15]
	v_cndmask_b32_e64 v25, 0, v227, s[12:13]
	v_sub_f32_e32 v91, v24, v25
	v_mul_f32_e32 v25, 0xbfb8aa3b, v29
	v_exp_f32_e32 v25, v25
	v_sub_f32_e32 v24, 1.0, v27
	v_add_f32_e32 v25, 1.0, v25
	v_rcp_f32_e32 v25, v25
	s_nop 0
	v_fmac_f32_e32 v27, v24, v25
	v_max_f32_e32 v24, 0xda24260, v27
	v_cmp_gt_f32_e64 s[12:13], s58, v24
	s_nop 1
	v_cndmask_b32_e64 v25, 0, 32, s[12:13]
	v_ldexp_f32 v24, v24, v25
	v_log_f32_e32 v24, v24
	s_nop 0
	v_mul_f32_e32 v25, 0x3f317217, v24
	v_fma_f32 v25, v24, s23, -v25
	v_fmac_f32_e32 v25, 0x3377d1cf, v24
	v_fmac_f32_e32 v25, 0x3f317217, v24
	v_cmp_lt_f32_e64 s[14:15], |v24|, s31
	s_nop 1
	v_cndmask_b32_e64 v24, v24, v25, s[14:15]
	v_cndmask_b32_e64 v25, 0, v227, s[12:13]
	v_sub_f32_e32 v92, v24, v25
	s_waitcnt vmcnt(3)
	v_mov_b64_e32 v[50:51], v[238:239]
	v_mov_b64_e32 v[24:25], v[240:241]
	v_mov_b64_e32 v[28:29], v[244:245]
	v_mov_b64_e32 v[30:31], v[246:247]
	v_lshlrev_b32_e32 v83, 16, v50
	v_mul_f32_e32 v83, 0xbfb8aa3b, v83
	v_exp_f32_e32 v83, v83
	v_sub_f32_e32 v84, 1.0, v28
	v_and_b32_e32 v50, 0xffff0000, v50
	v_mul_f32_e32 v50, 0xbfb8aa3b, v50
	v_add_f32_e32 v83, 1.0, v83
	v_rcp_f32_e32 v83, v83
	v_exp_f32_e32 v50, v50
	v_lshlrev_b32_e32 v95, 16, v51
	v_and_b32_e32 v51, 0xffff0000, v51
	v_fma_f32 v83, v84, v83, v28
	v_max_f32_e32 v28, 0xda24260, v83
	v_cmp_gt_f32_e64 s[12:13], s58, v28
	v_add_f32_e32 v50, 1.0, v50
	v_rcp_f32_e32 v50, v50
	v_cndmask_b32_e64 v84, 0, 32, s[12:13]
	v_ldexp_f32 v28, v28, v84
	v_log_f32_e32 v28, v28
	s_nop 0
	v_mul_f32_e32 v84, 0x3f317217, v28
	v_fma_f32 v84, v28, s23, -v84
	v_fmac_f32_e32 v84, 0x3377d1cf, v28
	v_fmac_f32_e32 v84, 0x3f317217, v28
	v_cmp_lt_f32_e64 s[14:15], |v28|, s31
	s_nop 1
	v_cndmask_b32_e64 v28, v28, v84, s[14:15]
	v_cndmask_b32_e64 v84, 0, v227, s[12:13]
	v_sub_f32_e32 v93, v28, v84
	v_sub_f32_e32 v28, 1.0, v29
	v_fma_f32 v84, v28, v50, v29
	v_max_f32_e32 v28, 0xda24260, v84
	v_cmp_gt_f32_e64 s[12:13], s58, v28
	s_nop 1
	v_cndmask_b32_e64 v29, 0, 32, s[12:13]
	v_ldexp_f32 v28, v28, v29
	v_log_f32_e32 v28, v28
	s_nop 0
	v_mul_f32_e32 v29, 0x3f317217, v28
	v_fma_f32 v29, v28, s23, -v29
	v_fmac_f32_e32 v29, 0x3377d1cf, v28
	v_fmac_f32_e32 v29, 0x3f317217, v28
	v_cmp_lt_f32_e64 s[14:15], |v28|, s31
	s_nop 1
	v_cndmask_b32_e64 v28, v28, v29, s[14:15]
	v_cndmask_b32_e64 v29, 0, v227, s[12:13]
	v_sub_f32_e32 v94, v28, v29
	v_mul_f32_e32 v29, 0xbfb8aa3b, v95
	v_exp_f32_e32 v29, v29
	v_sub_f32_e32 v28, 1.0, v30
	v_add_f32_e32 v29, 1.0, v29
	v_rcp_f32_e32 v29, v29
	s_nop 0
	v_fma_f32 v30, v28, v29, v30
	v_max_f32_e32 v28, 0xda24260, v30
	v_cmp_gt_f32_e64 s[12:13], s58, v28
	s_nop 1
	v_cndmask_b32_e64 v29, 0, 32, s[12:13]
	v_ldexp_f32 v28, v28, v29
	v_log_f32_e32 v28, v28
	s_nop 0
	v_mul_f32_e32 v29, 0x3f317217, v28
	v_fma_f32 v29, v28, s23, -v29
	v_fmac_f32_e32 v29, 0x3377d1cf, v28
	v_fmac_f32_e32 v29, 0x3f317217, v28
	v_cmp_lt_f32_e64 s[14:15], |v28|, s31
	s_nop 1
	v_cndmask_b32_e64 v28, v28, v29, s[14:15]
	v_cndmask_b32_e64 v29, 0, v227, s[12:13]
	v_sub_f32_e32 v95, v28, v29
	v_mul_f32_e32 v29, 0xbfb8aa3b, v51
	v_exp_f32_e32 v29, v29
	v_sub_f32_e32 v28, 1.0, v31
	v_add_f32_e32 v29, 1.0, v29
	v_rcp_f32_e32 v29, v29
	s_nop 0
	v_fmac_f32_e32 v31, v28, v29
	v_max_f32_e32 v28, 0xda24260, v31
	v_cmp_gt_f32_e64 s[12:13], s58, v28
	s_nop 1
	v_cndmask_b32_e64 v29, 0, 32, s[12:13]
	v_ldexp_f32 v28, v28, v29
	v_log_f32_e32 v28, v28
	s_nop 0
	v_mul_f32_e32 v29, 0x3f317217, v28
	v_fma_f32 v29, v28, s23, -v29
	v_fmac_f32_e32 v29, 0x3377d1cf, v28
	v_fmac_f32_e32 v29, 0x3f317217, v28
	v_cmp_lt_f32_e64 s[14:15], |v28|, s31
	s_nop 1
	v_cndmask_b32_e64 v28, v28, v29, s[14:15]
	v_cndmask_b32_e64 v29, 0, v227, s[12:13]
	v_sub_f32_e32 v96, v28, v29
	s_waitcnt vmcnt(0)
; __device__ __forceinline__ float bflo(unsigned u) { return __uint_as_float(u << 16); }
; __device__ __forceinline__ float bfhi(unsigned u) { return __uint_as_float(u & 0xffff0000u); }
; __device__ __forceinline__ float sigm(float x) { return __builtin_amdgcn_rcpf(1.f + __expf(-x)); }
; __device__ __forceinline__ float silu(float x) { return x * sigm(x); }
; template <int CTRL> __device__ __forceinline__ float dppf(float x) { return __builtin_bit_cast(float, __builtin_amdgcn_update_dpp(0, __builtin_bit_cast(int, x), CTRL, 0xf, 0xf, true)); }
; __device__ __forceinline__ void hgprep_phase(const Params& P, int l, LAS unsigned char* lds) {
;     ...
;         for (int j = 0; j < 4; ++j)
; #pragma unroll
;             for (int hh = 0; hh < 2; ++hh) { const int ko = 32 * j + 16 * hh;
;                 const u32x2 fr = *(const u32x2*)(hp + (dir ? C_HGFB : C_HGFF) + ko), qr = *(const u32x2*)(hp + C_HGQ + ko); const f32x4 lb = *(const f32x4*)(lbp + ko);
;                 const float fx[4] = {bflo(fr[0]), bfhi(fr[0]), bflo(fr[1]), bfhi(fr[1])}, qx[4] = {bflo(qr[0]), bfhi(qr[0]), bflo(qr[1]), bfhi(qr[1])};
; #pragma unroll
;                 for (int e = 0; e < 4; ++e) { const int ix = 8 * j + 4 * hh + e; const float f = lb[e] + (1.f - lb[e]) * sigm(fx[e]);
;                     L[ix] = __logf(fmaxf(f, 1e-30f)); kk[ix] = 1.f - f; q[ix] = silu(qx[e]); } }
;         float Lt15[32];
; #pragma unroll
;         for (int ix = 0; ix < 32; ++ix) { float x = L[ix]; Lt15[ix] = row_sum16(x); x += dppf<0x111>(x); x += dppf<0x112>(x); x += dppf<0x114>(x); x += dppf<0x118>(x); L[ix] = x; }
	v_mov_b64_e32 v[50:51], v[206:207]
	v_mov_b64_e32 v[28:29], v[208:209]
	v_mov_b64_e32 v[32:33], v[210:211]
	v_mov_b64_e32 v[34:35], v[212:213]
	s_nop 0
	v_lshlrev_b32_e32 v48, 16, v50
	v_mul_f32_e32 v48, 0xbfb8aa3b, v48
	v_exp_f32_e32 v48, v48
	v_and_b32_e32 v49, 0xffff0000, v50
	v_sub_f32_e32 v50, 1.0, v32
	v_mul_f32_e32 v49, 0xbfb8aa3b, v49
	v_add_f32_e32 v48, 1.0, v48
	v_rcp_f32_e32 v48, v48
	v_exp_f32_e32 v49, v49
	v_lshlrev_b32_e32 v97, 16, v51
	v_and_b32_e32 v98, 0xffff0000, v51
	v_fma_f32 v50, v50, v48, v32
	v_max_f32_e32 v32, 0xda24260, v50
	v_cmp_gt_f32_e64 s[12:13], s58, v32
	v_add_f32_e32 v49, 1.0, v49
	v_rcp_f32_e32 v49, v49
	v_cndmask_b32_e64 v48, 0, 32, s[12:13]
	v_ldexp_f32 v32, v32, v48
	v_log_f32_e32 v32, v32
	s_nop 0
	v_mul_f32_e32 v48, 0x3f317217, v32
	v_fma_f32 v48, v32, s23, -v48
	v_fmac_f32_e32 v48, 0x3377d1cf, v32
	v_fmac_f32_e32 v48, 0x3f317217, v32
	v_cmp_lt_f32_e64 s[14:15], |v32|, s31
	s_nop 1
	v_cndmask_b32_e64 v32, v32, v48, s[14:15]
	v_cndmask_b32_e64 v48, 0, v227, s[12:13]
	v_sub_f32_e32 v32, v32, v48
	v_sub_f32_e32 v48, 1.0, v33
	v_fma_f32 v51, v48, v49, v33
	v_max_f32_e32 v33, 0xda24260, v51
	v_cmp_gt_f32_e64 s[12:13], s58, v33
	v_mul_f32_e32 v49, 0xbfb8aa3b, v97
	v_exp_f32_e32 v49, v49
	v_cndmask_b32_e64 v48, 0, 32, s[12:13]
	v_ldexp_f32 v33, v33, v48
	v_log_f32_e32 v33, v33
	v_add_f32_e32 v49, 1.0, v49
	v_rcp_f32_e32 v49, v49
	v_mul_f32_e32 v48, 0x3f317217, v33
	v_fma_f32 v48, v33, s23, -v48
	v_fmac_f32_e32 v48, 0x3377d1cf, v33
	v_fmac_f32_e32 v48, 0x3f317217, v33
	v_cmp_lt_f32_e64 s[14:15], |v33|, s31
	s_nop 1
	v_cndmask_b32_e64 v33, v33, v48, s[14:15]
	v_cndmask_b32_e64 v48, 0, v227, s[12:13]
	v_sub_f32_e32 v33, v33, v48
	v_sub_f32_e32 v48, 1.0, v34
	v_fma_f32 v34, v48, v49, v34
	v_max_f32_e32 v48, 0xda24260, v34
	v_cmp_gt_f32_e64 s[12:13], s58, v48
	s_nop 1
	v_cndmask_b32_e64 v49, 0, 32, s[12:13]
	v_ldexp_f32 v48, v48, v49
	v_log_f32_e32 v48, v48
	s_nop 0
	v_mul_f32_e32 v49, 0x3f317217, v48
	v_fma_f32 v49, v48, s23, -v49
	v_fmac_f32_e32 v49, 0x3377d1cf, v48
	v_fmac_f32_e32 v49, 0x3f317217, v48
	v_cmp_lt_f32_e64 s[14:15], |v48|, s31
	s_nop 1
	v_cndmask_b32_e64 v48, v48, v49, s[14:15]
	v_cndmask_b32_e64 v49, 0, v227, s[12:13]
	v_sub_f32_e32 v190, v48, v49
	v_mul_f32_e32 v49, 0xbfb8aa3b, v98
	v_exp_f32_e32 v49, v49
	v_sub_f32_e32 v48, 1.0, v35
	v_add_f32_e32 v49, 1.0, v49
	v_rcp_f32_e32 v49, v49
	s_nop 0
	v_fmac_f32_e32 v35, v48, v49
	v_max_f32_e32 v48, 0xda24260, v35
	v_cmp_gt_f32_e64 s[12:13], s58, v48
	s_nop 1
	v_cndmask_b32_e64 v49, 0, 32, s[12:13]
	v_ldexp_f32 v48, v48, v49
	v_log_f32_e32 v48, v48
	s_nop 0
	v_mul_f32_e32 v49, 0x3f317217, v48
	v_fma_f32 v49, v48, s23, -v49
	v_fmac_f32_e32 v49, 0x3377d1cf, v48
	v_fmac_f32_e32 v49, 0x3f317217, v48
	v_cmp_lt_f32_e64 s[14:15], |v48|, s31
	s_nop 1
	v_cndmask_b32_e64 v48, v48, v49, s[14:15]
	v_cndmask_b32_e64 v49, 0, v227, s[12:13]
	v_sub_f32_e32 v203, v48, v49
	v_mov_b32_dpp v48, v46 row_shr:1 row_mask:0xf bank_mask:0xf bound_ctrl:1
	v_mov_b32_dpp v49, v46 row_ror:8 row_mask:0xf bank_mask:0xf bound_ctrl:1
	v_pk_add_f32 v[48:49], v[46:47], v[48:49] op_sel_hi:[0,1]
	v_add_f32_dpp v46, v1, v1 row_ror:8 row_mask:0xf bank_mask:0xf bound_ctrl:1
	v_add_f32_dpp v1, v1, v1 row_shr:1 row_mask:0xf bank_mask:0xf bound_ctrl:1
	v_mov_b32_dpp v99, v49 row_ror:4 row_mask:0xf bank_mask:0xf bound_ctrl:1
	v_mov_b32_dpp v98, v48 row_shr:2 row_mask:0xf bank_mask:0xf bound_ctrl:1
	v_add_f32_dpp v1, v1, v1 row_shr:2 row_mask:0xf bank_mask:0xf bound_ctrl:1
	v_pk_add_f32 v[48:49], v[48:49], v[98:99]
	v_readlane_b32 s12, v252, 2
	v_add_f32_dpp v195, v1, v1 row_shr:4 row_mask:0xf bank_mask:0xf bound_ctrl:1
	v_add_f32_dpp v1, v47, v47 row_ror:8 row_mask:0xf bank_mask:0xf bound_ctrl:1
	v_mov_b32_dpp v99, v49 row_ror:2 row_mask:0xf bank_mask:0xf bound_ctrl:1
	v_mov_b32_dpp v98, v48 row_shr:4 row_mask:0xf bank_mask:0xf bound_ctrl:1
	v_add_f32_dpp v1, v1, v1 row_ror:4 row_mask:0xf bank_mask:0xf bound_ctrl:1
	v_pk_add_f32 v[48:49], v[48:49], v[98:99]
	v_add_f32_dpp v46, v46, v46 row_ror:4 row_mask:0xf bank_mask:0xf bound_ctrl:1
	v_add_f32_dpp v170, v1, v1 row_ror:2 row_mask:0xf bank_mask:0xf bound_ctrl:1
	v_add_f32_dpp v1, v47, v47 row_shr:1 row_mask:0xf bank_mask:0xf bound_ctrl:1
	v_mov_b32_dpp v99, v49 row_ror:1 row_mask:0xf bank_mask:0xf bound_ctrl:1
	v_mov_b32_dpp v98, v48 row_shr:8 row_mask:0xf bank_mask:0xf bound_ctrl:1
	v_add_f32_dpp v1, v1, v1 row_shr:2 row_mask:0xf bank_mask:0xf bound_ctrl:1
	v_pk_add_f32 v[48:49], v[48:49], v[98:99]
	v_readlane_b32 s13, v252, 3
	v_add_f32_dpp v193, v1, v1 row_shr:4 row_mask:0xf bank_mask:0xf bound_ctrl:1
	v_add_f32_dpp v1, v62, v62 row_ror:8 row_mask:0xf bank_mask:0xf bound_ctrl:1
	v_add_f32_dpp v172, v46, v46 row_ror:2 row_mask:0xf bank_mask:0xf bound_ctrl:1
	v_mov_b32_dpp v202, v195 row_shr:8 row_mask:0xf bank_mask:0xf bound_ctrl:1
	v_add_f32_dpp v1, v1, v1 row_ror:4 row_mask:0xf bank_mask:0xf bound_ctrl:1
	v_mov_b32_dpp v173, v172 row_ror:1 row_mask:0xf bank_mask:0xf bound_ctrl:1
	v_mov_b32_dpp v171, v170 row_ror:1 row_mask:0xf bank_mask:0xf bound_ctrl:1
	v_add_f32_dpp v168, v1, v1 row_ror:2 row_mask:0xf bank_mask:0xf bound_ctrl:1
	v_add_f32_dpp v1, v62, v62 row_shr:1 row_mask:0xf bank_mask:0xf bound_ctrl:1
	v_mov_b32_dpp v194, v193 row_shr:8 row_mask:0xf bank_mask:0xf bound_ctrl:1
	v_mov_b32_dpp v169, v168 row_ror:1 row_mask:0xf bank_mask:0xf bound_ctrl:1
	v_add_f32_dpp v1, v1, v1 row_shr:2 row_mask:0xf bank_mask:0xf bound_ctrl:1
	s_nop 1
	v_add_f32_dpp v191, v1, v1 row_shr:4 row_mask:0xf bank_mask:0xf bound_ctrl:1
	v_add_f32_dpp v1, v65, v65 row_ror:8 row_mask:0xf bank_mask:0xf bound_ctrl:1
	s_nop 0
; template <int CTRL> __device__ __forceinline__ float dppf(float x) { return __builtin_bit_cast(float, __builtin_amdgcn_update_dpp(0, __builtin_bit_cast(int, x), CTRL, 0xf, 0xf, true)); }
; __device__ __forceinline__ float row_sum16(float x) {
;     x += dppf<0x128>(x); x += dppf<0x124>(x); x += dppf<0x122>(x); x += dppf<0x121>(x); return x;
; }
; __device__ __forceinline__ void hgprep_phase(const Params& P, int l, LAS unsigned char* lds) {
;     ...
;         float Lt15[32];
; #pragma unroll
;         for (int ix = 0; ix < 32; ++ix) { float x = L[ix]; Lt15[ix] = row_sum16(x); x += dppf<0x111>(x); x += dppf<0x112>(x); x += dppf<0x114>(x); x += dppf<0x118>(x); L[ix] = x; }
	v_mov_b32_dpp v192, v191 row_shr:8 row_mask:0xf bank_mask:0xf bound_ctrl:1
	v_add_f32_dpp v1, v1, v1 row_ror:4 row_mask:0xf bank_mask:0xf bound_ctrl:1
	s_nop 1
	v_add_f32_dpp v178, v1, v1 row_ror:2 row_mask:0xf bank_mask:0xf bound_ctrl:1
	v_add_f32_dpp v1, v65, v65 row_shr:1 row_mask:0xf bank_mask:0xf bound_ctrl:1
	s_nop 0
	v_mov_b32_dpp v180, v178 row_ror:1 row_mask:0xf bank_mask:0xf bound_ctrl:1
	v_add_f32_dpp v1, v1, v1 row_shr:2 row_mask:0xf bank_mask:0xf bound_ctrl:1
	s_nop 1
	v_add_f32_dpp v188, v1, v1 row_shr:4 row_mask:0xf bank_mask:0xf bound_ctrl:1
	v_add_f32_dpp v1, v66, v66 row_ror:8 row_mask:0xf bank_mask:0xf bound_ctrl:1
	s_nop 0
	v_mov_b32_dpp v189, v188 row_shr:8 row_mask:0xf bank_mask:0xf bound_ctrl:1
	v_add_f32_dpp v1, v1, v1 row_ror:4 row_mask:0xf bank_mask:0xf bound_ctrl:1
	s_nop 1
	v_add_f32_dpp v179, v1, v1 row_ror:2 row_mask:0xf bank_mask:0xf bound_ctrl:1
	v_add_f32_dpp v1, v66, v66 row_shr:1 row_mask:0xf bank_mask:0xf bound_ctrl:1
	s_nop 0
	v_mov_b32_dpp v181, v179 row_ror:1 row_mask:0xf bank_mask:0xf bound_ctrl:1
	v_add_f32_dpp v1, v1, v1 row_shr:2 row_mask:0xf bank_mask:0xf bound_ctrl:1
	s_nop 1
	v_add_f32_dpp v186, v1, v1 row_shr:4 row_mask:0xf bank_mask:0xf bound_ctrl:1
	v_add_f32_dpp v1, v67, v67 row_ror:8 row_mask:0xf bank_mask:0xf bound_ctrl:1
	s_nop 0
	v_mov_b32_dpp v187, v186 row_shr:8 row_mask:0xf bank_mask:0xf bound_ctrl:1
	v_add_f32_dpp v1, v1, v1 row_ror:4 row_mask:0xf bank_mask:0xf bound_ctrl:1
	s_nop 1
	v_add_f32_dpp v176, v1, v1 row_ror:2 row_mask:0xf bank_mask:0xf bound_ctrl:1
	v_add_f32_dpp v1, v67, v67 row_shr:1 row_mask:0xf bank_mask:0xf bound_ctrl:1
	s_nop 0
	v_mov_b32_dpp v177, v176 row_ror:1 row_mask:0xf bank_mask:0xf bound_ctrl:1
	v_add_f32_dpp v1, v1, v1 row_shr:2 row_mask:0xf bank_mask:0xf bound_ctrl:1
	s_nop 1
	v_add_f32_dpp v184, v1, v1 row_shr:4 row_mask:0xf bank_mask:0xf bound_ctrl:1
	v_add_f32_dpp v1, v68, v68 row_ror:8 row_mask:0xf bank_mask:0xf bound_ctrl:1
	s_nop 0
	v_mov_b32_dpp v185, v184 row_shr:8 row_mask:0xf bank_mask:0xf bound_ctrl:1
	v_add_f32_dpp v1, v1, v1 row_ror:4 row_mask:0xf bank_mask:0xf bound_ctrl:1
	s_nop 1
	v_add_f32_dpp v174, v1, v1 row_ror:2 row_mask:0xf bank_mask:0xf bound_ctrl:1
	v_add_f32_dpp v1, v68, v68 row_shr:1 row_mask:0xf bank_mask:0xf bound_ctrl:1
	s_nop 0
	v_mov_b32_dpp v175, v174 row_ror:1 row_mask:0xf bank_mask:0xf bound_ctrl:1
	v_add_f32_dpp v1, v1, v1 row_shr:2 row_mask:0xf bank_mask:0xf bound_ctrl:1
	s_nop 1
	v_add_f32_dpp v182, v1, v1 row_shr:4 row_mask:0xf bank_mask:0xf bound_ctrl:1
	v_add_f32_dpp v1, v69, v69 row_ror:8 row_mask:0xf bank_mask:0xf bound_ctrl:1
	s_nop 0
	v_mov_b32_dpp v183, v182 row_shr:8 row_mask:0xf bank_mask:0xf bound_ctrl:1
	v_add_f32_dpp v1, v1, v1 row_ror:4 row_mask:0xf bank_mask:0xf bound_ctrl:1
	s_nop 1
	v_add_f32_dpp v142, v1, v1 row_ror:2 row_mask:0xf bank_mask:0xf bound_ctrl:1
	v_add_f32_dpp v1, v69, v69 row_shr:1 row_mask:0xf bank_mask:0xf bound_ctrl:1
	s_nop 0
	v_mov_b32_dpp v143, v142 row_ror:1 row_mask:0xf bank_mask:0xf bound_ctrl:1
	v_add_f32_dpp v1, v1, v1 row_shr:2 row_mask:0xf bank_mask:0xf bound_ctrl:1
	s_nop 1
	v_add_f32_dpp v166, v1, v1 row_shr:4 row_mask:0xf bank_mask:0xf bound_ctrl:1
	v_add_f32_dpp v1, v70, v70 row_ror:8 row_mask:0xf bank_mask:0xf bound_ctrl:1
	s_nop 0
	v_mov_b32_dpp v167, v166 row_shr:8 row_mask:0xf bank_mask:0xf bound_ctrl:1
	v_add_f32_dpp v1, v1, v1 row_ror:4 row_mask:0xf bank_mask:0xf bound_ctrl:1
	s_nop 1
	v_add_f32_dpp v140, v1, v1 row_ror:2 row_mask:0xf bank_mask:0xf bound_ctrl:1
	v_add_f32_dpp v1, v70, v70 row_shr:1 row_mask:0xf bank_mask:0xf bound_ctrl:1
	s_nop 0
	v_mov_b32_dpp v141, v140 row_ror:1 row_mask:0xf bank_mask:0xf bound_ctrl:1
	v_add_f32_dpp v1, v1, v1 row_shr:2 row_mask:0xf bank_mask:0xf bound_ctrl:1
	s_nop 1
	v_add_f32_dpp v164, v1, v1 row_shr:4 row_mask:0xf bank_mask:0xf bound_ctrl:1
	v_add_f32_dpp v1, v71, v71 row_ror:8 row_mask:0xf bank_mask:0xf bound_ctrl:1
	s_nop 0
	v_mov_b32_dpp v165, v164 row_shr:8 row_mask:0xf bank_mask:0xf bound_ctrl:1
	v_add_f32_dpp v1, v1, v1 row_ror:4 row_mask:0xf bank_mask:0xf bound_ctrl:1
	s_nop 1
	v_add_f32_dpp v138, v1, v1 row_ror:2 row_mask:0xf bank_mask:0xf bound_ctrl:1
	v_add_f32_dpp v1, v71, v71 row_shr:1 row_mask:0xf bank_mask:0xf bound_ctrl:1
	s_nop 0
	v_mov_b32_dpp v139, v138 row_ror:1 row_mask:0xf bank_mask:0xf bound_ctrl:1
	v_add_f32_dpp v1, v1, v1 row_shr:2 row_mask:0xf bank_mask:0xf bound_ctrl:1
	s_nop 1
	v_add_f32_dpp v162, v1, v1 row_shr:4 row_mask:0xf bank_mask:0xf bound_ctrl:1
	v_add_f32_dpp v1, v72, v72 row_ror:8 row_mask:0xf bank_mask:0xf bound_ctrl:1
	s_nop 0
	v_mov_b32_dpp v163, v162 row_shr:8 row_mask:0xf bank_mask:0xf bound_ctrl:1
	v_add_f32_dpp v1, v1, v1 row_ror:4 row_mask:0xf bank_mask:0xf bound_ctrl:1
	s_nop 1
	v_add_f32_dpp v136, v1, v1 row_ror:2 row_mask:0xf bank_mask:0xf bound_ctrl:1
	v_add_f32_dpp v1, v72, v72 row_shr:1 row_mask:0xf bank_mask:0xf bound_ctrl:1
	s_nop 0
	v_mov_b32_dpp v137, v136 row_ror:1 row_mask:0xf bank_mask:0xf bound_ctrl:1
	v_add_f32_dpp v1, v1, v1 row_shr:2 row_mask:0xf bank_mask:0xf bound_ctrl:1
	s_nop 1
	v_add_f32_dpp v160, v1, v1 row_shr:4 row_mask:0xf bank_mask:0xf bound_ctrl:1
	v_add_f32_dpp v1, v77, v77 row_ror:8 row_mask:0xf bank_mask:0xf bound_ctrl:1
	s_nop 0
	v_mov_b32_dpp v161, v160 row_shr:8 row_mask:0xf bank_mask:0xf bound_ctrl:1
	v_add_f32_dpp v1, v1, v1 row_ror:4 row_mask:0xf bank_mask:0xf bound_ctrl:1
	s_nop 1
	v_add_f32_dpp v148, v1, v1 row_ror:2 row_mask:0xf bank_mask:0xf bound_ctrl:1
	v_add_f32_dpp v1, v77, v77 row_shr:1 row_mask:0xf bank_mask:0xf bound_ctrl:1
	s_nop 0
	v_mov_b32_dpp v150, v148 row_ror:1 row_mask:0xf bank_mask:0xf bound_ctrl:1
; template <int CTRL> __device__ __forceinline__ float dppf(float x) { return __builtin_bit_cast(float, __builtin_amdgcn_update_dpp(0, __builtin_bit_cast(int, x), CTRL, 0xf, 0xf, true)); }
; __device__ __forceinline__ void hgprep_phase(const Params& P, int l, LAS unsigned char* lds) {
;     ...
;         for (int ix = 0; ix < 32; ++ix) { float x = L[ix]; Lt15[ix] = row_sum16(x); x += dppf<0x111>(x); x += dppf<0x112>(x); x += dppf<0x114>(x); x += dppf<0x118>(x); L[ix] = x; }
	v_add_f32_dpp v1, v1, v1 row_shr:2 row_mask:0xf bank_mask:0xf bound_ctrl:1
	s_nop 1
	v_add_f32_dpp v158, v1, v1 row_shr:4 row_mask:0xf bank_mask:0xf bound_ctrl:1
	v_add_f32_dpp v1, v78, v78 row_ror:8 row_mask:0xf bank_mask:0xf bound_ctrl:1
	s_nop 0
	v_mov_b32_dpp v159, v158 row_shr:8 row_mask:0xf bank_mask:0xf bound_ctrl:1
	v_add_f32_dpp v1, v1, v1 row_ror:4 row_mask:0xf bank_mask:0xf bound_ctrl:1
	s_nop 1
	v_add_f32_dpp v149, v1, v1 row_ror:2 row_mask:0xf bank_mask:0xf bound_ctrl:1
	v_add_f32_dpp v1, v78, v78 row_shr:1 row_mask:0xf bank_mask:0xf bound_ctrl:1
	s_nop 0
	v_mov_b32_dpp v151, v149 row_ror:1 row_mask:0xf bank_mask:0xf bound_ctrl:1
	v_add_f32_dpp v1, v1, v1 row_shr:2 row_mask:0xf bank_mask:0xf bound_ctrl:1
	s_nop 1
	v_add_f32_dpp v156, v1, v1 row_shr:4 row_mask:0xf bank_mask:0xf bound_ctrl:1
	v_add_f32_dpp v1, v79, v79 row_ror:8 row_mask:0xf bank_mask:0xf bound_ctrl:1
	s_nop 0
	v_mov_b32_dpp v157, v156 row_shr:8 row_mask:0xf bank_mask:0xf bound_ctrl:1
	v_add_f32_dpp v1, v1, v1 row_ror:4 row_mask:0xf bank_mask:0xf bound_ctrl:1
	s_nop 1
	v_add_f32_dpp v146, v1, v1 row_ror:2 row_mask:0xf bank_mask:0xf bound_ctrl:1
	v_add_f32_dpp v1, v79, v79 row_shr:1 row_mask:0xf bank_mask:0xf bound_ctrl:1
	s_nop 0
	v_mov_b32_dpp v147, v146 row_ror:1 row_mask:0xf bank_mask:0xf bound_ctrl:1
	v_add_f32_dpp v1, v1, v1 row_shr:2 row_mask:0xf bank_mask:0xf bound_ctrl:1
	s_nop 1
	v_add_f32_dpp v154, v1, v1 row_shr:4 row_mask:0xf bank_mask:0xf bound_ctrl:1
	v_add_f32_dpp v1, v80, v80 row_ror:8 row_mask:0xf bank_mask:0xf bound_ctrl:1
	s_nop 0
	v_mov_b32_dpp v155, v154 row_shr:8 row_mask:0xf bank_mask:0xf bound_ctrl:1
	v_add_f32_dpp v1, v1, v1 row_ror:4 row_mask:0xf bank_mask:0xf bound_ctrl:1
	s_nop 1
	v_add_f32_dpp v144, v1, v1 row_ror:2 row_mask:0xf bank_mask:0xf bound_ctrl:1
	v_add_f32_dpp v1, v80, v80 row_shr:1 row_mask:0xf bank_mask:0xf bound_ctrl:1
	s_nop 0
	v_mov_b32_dpp v145, v144 row_ror:1 row_mask:0xf bank_mask:0xf bound_ctrl:1
	v_add_f32_dpp v1, v1, v1 row_shr:2 row_mask:0xf bank_mask:0xf bound_ctrl:1
	s_nop 1
	v_add_f32_dpp v152, v1, v1 row_shr:4 row_mask:0xf bank_mask:0xf bound_ctrl:1
	v_add_f32_dpp v1, v85, v85 row_ror:8 row_mask:0xf bank_mask:0xf bound_ctrl:1
	s_nop 0
	v_mov_b32_dpp v153, v152 row_shr:8 row_mask:0xf bank_mask:0xf bound_ctrl:1
	v_add_f32_dpp v1, v1, v1 row_ror:4 row_mask:0xf bank_mask:0xf bound_ctrl:1
	s_nop 1
	v_add_f32_dpp v110, v1, v1 row_ror:2 row_mask:0xf bank_mask:0xf bound_ctrl:1
	v_add_f32_dpp v1, v85, v85 row_shr:1 row_mask:0xf bank_mask:0xf bound_ctrl:1
	s_nop 0
	v_mov_b32_dpp v111, v110 row_ror:1 row_mask:0xf bank_mask:0xf bound_ctrl:1
	v_add_f32_dpp v1, v1, v1 row_shr:2 row_mask:0xf bank_mask:0xf bound_ctrl:1
	s_nop 1
	v_add_f32_dpp v134, v1, v1 row_shr:4 row_mask:0xf bank_mask:0xf bound_ctrl:1
	v_add_f32_dpp v1, v86, v86 row_ror:8 row_mask:0xf bank_mask:0xf bound_ctrl:1
	s_nop 0
	v_mov_b32_dpp v135, v134 row_shr:8 row_mask:0xf bank_mask:0xf bound_ctrl:1
	v_add_f32_dpp v1, v1, v1 row_ror:4 row_mask:0xf bank_mask:0xf bound_ctrl:1
	s_nop 1
	v_add_f32_dpp v108, v1, v1 row_ror:2 row_mask:0xf bank_mask:0xf bound_ctrl:1
	v_add_f32_dpp v1, v86, v86 row_shr:1 row_mask:0xf bank_mask:0xf bound_ctrl:1
	s_nop 0
	v_mov_b32_dpp v109, v108 row_ror:1 row_mask:0xf bank_mask:0xf bound_ctrl:1
	v_add_f32_dpp v1, v1, v1 row_shr:2 row_mask:0xf bank_mask:0xf bound_ctrl:1
	s_nop 1
	v_add_f32_dpp v132, v1, v1 row_shr:4 row_mask:0xf bank_mask:0xf bound_ctrl:1
	v_add_f32_dpp v1, v87, v87 row_ror:8 row_mask:0xf bank_mask:0xf bound_ctrl:1
	s_nop 0
	v_mov_b32_dpp v133, v132 row_shr:8 row_mask:0xf bank_mask:0xf bound_ctrl:1
	v_add_f32_dpp v1, v1, v1 row_ror:4 row_mask:0xf bank_mask:0xf bound_ctrl:1
	s_nop 1
	v_add_f32_dpp v106, v1, v1 row_ror:2 row_mask:0xf bank_mask:0xf bound_ctrl:1
	v_add_f32_dpp v1, v87, v87 row_shr:1 row_mask:0xf bank_mask:0xf bound_ctrl:1
	s_nop 0
	v_mov_b32_dpp v107, v106 row_ror:1 row_mask:0xf bank_mask:0xf bound_ctrl:1
	v_add_f32_dpp v1, v1, v1 row_shr:2 row_mask:0xf bank_mask:0xf bound_ctrl:1
	s_nop 1
	v_add_f32_dpp v130, v1, v1 row_shr:4 row_mask:0xf bank_mask:0xf bound_ctrl:1
	v_add_f32_dpp v1, v88, v88 row_ror:8 row_mask:0xf bank_mask:0xf bound_ctrl:1
	s_nop 0
	v_mov_b32_dpp v131, v130 row_shr:8 row_mask:0xf bank_mask:0xf bound_ctrl:1
	v_add_f32_dpp v1, v1, v1 row_ror:4 row_mask:0xf bank_mask:0xf bound_ctrl:1
	s_nop 1
	v_add_f32_dpp v104, v1, v1 row_ror:2 row_mask:0xf bank_mask:0xf bound_ctrl:1
	v_add_f32_dpp v1, v88, v88 row_shr:1 row_mask:0xf bank_mask:0xf bound_ctrl:1
	s_nop 0
	v_mov_b32_dpp v105, v104 row_ror:1 row_mask:0xf bank_mask:0xf bound_ctrl:1
	v_add_f32_dpp v1, v1, v1 row_shr:2 row_mask:0xf bank_mask:0xf bound_ctrl:1
	s_nop 1
	v_add_f32_dpp v128, v1, v1 row_shr:4 row_mask:0xf bank_mask:0xf bound_ctrl:1
	v_add_f32_dpp v1, v89, v89 row_ror:8 row_mask:0xf bank_mask:0xf bound_ctrl:1
	s_nop 0
	v_mov_b32_dpp v129, v128 row_shr:8 row_mask:0xf bank_mask:0xf bound_ctrl:1
	v_add_f32_dpp v1, v1, v1 row_ror:4 row_mask:0xf bank_mask:0xf bound_ctrl:1
	s_nop 1
	v_add_f32_dpp v116, v1, v1 row_ror:2 row_mask:0xf bank_mask:0xf bound_ctrl:1
	v_add_f32_dpp v1, v89, v89 row_shr:1 row_mask:0xf bank_mask:0xf bound_ctrl:1
	s_nop 0
	v_mov_b32_dpp v118, v116 row_ror:1 row_mask:0xf bank_mask:0xf bound_ctrl:1
	v_add_f32_dpp v1, v1, v1 row_shr:2 row_mask:0xf bank_mask:0xf bound_ctrl:1
	s_nop 1
	v_add_f32_dpp v126, v1, v1 row_shr:4 row_mask:0xf bank_mask:0xf bound_ctrl:1
	v_add_f32_dpp v1, v90, v90 row_ror:8 row_mask:0xf bank_mask:0xf bound_ctrl:1
	s_nop 0
	v_mov_b32_dpp v127, v126 row_shr:8 row_mask:0xf bank_mask:0xf bound_ctrl:1
	v_add_f32_dpp v1, v1, v1 row_ror:4 row_mask:0xf bank_mask:0xf bound_ctrl:1
	s_nop 1
; template <int CTRL> __device__ __forceinline__ float dppf(float x) { return __builtin_bit_cast(float, __builtin_amdgcn_update_dpp(0, __builtin_bit_cast(int, x), CTRL, 0xf, 0xf, true)); }
; __device__ __forceinline__ void hgprep_phase(const Params& P, int l, LAS unsigned char* lds) {
;     ...
;         for (int ix = 0; ix < 32; ++ix) { float x = L[ix]; Lt15[ix] = row_sum16(x); x += dppf<0x111>(x); x += dppf<0x112>(x); x += dppf<0x114>(x); x += dppf<0x118>(x); L[ix] = x; }
	v_add_f32_dpp v117, v1, v1 row_ror:2 row_mask:0xf bank_mask:0xf bound_ctrl:1
	v_add_f32_dpp v1, v90, v90 row_shr:1 row_mask:0xf bank_mask:0xf bound_ctrl:1
	s_nop 0
	v_mov_b32_dpp v119, v117 row_ror:1 row_mask:0xf bank_mask:0xf bound_ctrl:1
	v_add_f32_dpp v1, v1, v1 row_shr:2 row_mask:0xf bank_mask:0xf bound_ctrl:1
	s_nop 1
	v_add_f32_dpp v124, v1, v1 row_shr:4 row_mask:0xf bank_mask:0xf bound_ctrl:1
	v_add_f32_dpp v1, v91, v91 row_ror:8 row_mask:0xf bank_mask:0xf bound_ctrl:1
	s_nop 0
	v_mov_b32_dpp v125, v124 row_shr:8 row_mask:0xf bank_mask:0xf bound_ctrl:1
	v_add_f32_dpp v1, v1, v1 row_ror:4 row_mask:0xf bank_mask:0xf bound_ctrl:1
	s_nop 1
	v_add_f32_dpp v114, v1, v1 row_ror:2 row_mask:0xf bank_mask:0xf bound_ctrl:1
	v_add_f32_dpp v1, v91, v91 row_shr:1 row_mask:0xf bank_mask:0xf bound_ctrl:1
	s_nop 0
	v_mov_b32_dpp v115, v114 row_ror:1 row_mask:0xf bank_mask:0xf bound_ctrl:1
	v_add_f32_dpp v1, v1, v1 row_shr:2 row_mask:0xf bank_mask:0xf bound_ctrl:1
	s_nop 1
	v_add_f32_dpp v122, v1, v1 row_shr:4 row_mask:0xf bank_mask:0xf bound_ctrl:1
	v_add_f32_dpp v1, v92, v92 row_ror:8 row_mask:0xf bank_mask:0xf bound_ctrl:1
	s_nop 0
	v_mov_b32_dpp v123, v122 row_shr:8 row_mask:0xf bank_mask:0xf bound_ctrl:1
	v_add_f32_dpp v1, v1, v1 row_ror:4 row_mask:0xf bank_mask:0xf bound_ctrl:1
	s_nop 1
	v_add_f32_dpp v112, v1, v1 row_ror:2 row_mask:0xf bank_mask:0xf bound_ctrl:1
	v_add_f32_dpp v1, v92, v92 row_shr:1 row_mask:0xf bank_mask:0xf bound_ctrl:1
	s_nop 0
	v_mov_b32_dpp v113, v112 row_ror:1 row_mask:0xf bank_mask:0xf bound_ctrl:1
	v_add_f32_dpp v1, v1, v1 row_shr:2 row_mask:0xf bank_mask:0xf bound_ctrl:1
	s_nop 1
	v_add_f32_dpp v120, v1, v1 row_shr:4 row_mask:0xf bank_mask:0xf bound_ctrl:1
	v_add_f32_dpp v1, v93, v93 row_ror:8 row_mask:0xf bank_mask:0xf bound_ctrl:1
	s_nop 0
	v_mov_b32_dpp v121, v120 row_shr:8 row_mask:0xf bank_mask:0xf bound_ctrl:1
	v_add_f32_dpp v1, v1, v1 row_ror:4 row_mask:0xf bank_mask:0xf bound_ctrl:1
	s_nop 1
	v_add_f32_dpp v70, v1, v1 row_ror:2 row_mask:0xf bank_mask:0xf bound_ctrl:1
	v_add_f32_dpp v1, v93, v93 row_shr:1 row_mask:0xf bank_mask:0xf bound_ctrl:1
	s_nop 0
	v_mov_b32_dpp v71, v70 row_ror:1 row_mask:0xf bank_mask:0xf bound_ctrl:1
	v_add_f32_dpp v1, v1, v1 row_shr:2 row_mask:0xf bank_mask:0xf bound_ctrl:1
	s_nop 1
	v_add_f32_dpp v102, v1, v1 row_shr:4 row_mask:0xf bank_mask:0xf bound_ctrl:1
	v_add_f32_dpp v1, v94, v94 row_ror:8 row_mask:0xf bank_mask:0xf bound_ctrl:1
	s_nop 0
	v_mov_b32_dpp v103, v102 row_shr:8 row_mask:0xf bank_mask:0xf bound_ctrl:1
	v_add_f32_dpp v1, v1, v1 row_ror:4 row_mask:0xf bank_mask:0xf bound_ctrl:1
	s_nop 1
	v_add_f32_dpp v68, v1, v1 row_ror:2 row_mask:0xf bank_mask:0xf bound_ctrl:1
	v_add_f32_dpp v1, v94, v94 row_shr:1 row_mask:0xf bank_mask:0xf bound_ctrl:1
	s_nop 0
	v_mov_b32_dpp v69, v68 row_ror:1 row_mask:0xf bank_mask:0xf bound_ctrl:1
	v_add_f32_dpp v1, v1, v1 row_shr:2 row_mask:0xf bank_mask:0xf bound_ctrl:1
	s_nop 1
	v_add_f32_dpp v100, v1, v1 row_shr:4 row_mask:0xf bank_mask:0xf bound_ctrl:1
	v_add_f32_dpp v1, v95, v95 row_ror:8 row_mask:0xf bank_mask:0xf bound_ctrl:1
	s_nop 0
	v_mov_b32_dpp v101, v100 row_shr:8 row_mask:0xf bank_mask:0xf bound_ctrl:1
	v_add_f32_dpp v1, v1, v1 row_ror:4 row_mask:0xf bank_mask:0xf bound_ctrl:1
	s_nop 1
	v_add_f32_dpp v66, v1, v1 row_ror:2 row_mask:0xf bank_mask:0xf bound_ctrl:1
	v_add_f32_dpp v1, v95, v95 row_shr:1 row_mask:0xf bank_mask:0xf bound_ctrl:1
	s_nop 0
	v_mov_b32_dpp v67, v66 row_ror:1 row_mask:0xf bank_mask:0xf bound_ctrl:1
	v_add_f32_dpp v1, v1, v1 row_shr:2 row_mask:0xf bank_mask:0xf bound_ctrl:1
	s_nop 1
	v_add_f32_dpp v98, v1, v1 row_shr:4 row_mask:0xf bank_mask:0xf bound_ctrl:1
; template <int CTRL> __device__ __forceinline__ float dppf(float x) { return __builtin_bit_cast(float, __builtin_amdgcn_update_dpp(0, __builtin_bit_cast(int, x), CTRL, 0xf, 0xf, true)); }
; __device__ __forceinline__ void hgprep_phase(const Params& P, int l, LAS unsigned char* lds) {
;     ...
;         for (int ix = 0; ix < 32; ++ix) { float x = L[ix]; Lt15[ix] = row_sum16(x); x += dppf<0x111>(x); x += dppf<0x112>(x); x += dppf<0x114>(x); x += dppf<0x118>(x); L[ix] = x; }
;         f32x4 Att = {0.f, 0.f, 0.f, 0.f};
; #pragma unroll
;         for (int j = 0; j < 4; ++j) {
;             u32x4 fqv, qp, kp; float khat[8];
; #pragma unroll
;             for (int e2 = 0; e2 < 4; ++e2) {
;                 float qt[2], qq[2], kx[2];
; #pragma unroll
;                 for (int z = 0; z < 2; ++z) { const int ix = 8 * j + 2 * e2 + z; const float Lt = L[ix];
;                     const float L15 = Lt15[ix];
;                     qt[z] = q[ix] * __expf(Lt);
;                     const float d = fminf(Lt - L15, 80.f);
;                     qq[z] = q[ix] * __expf(d); kx[z] = kk[ix] * __expf(-d);
;                     khat[2 * e2 + z] = kx[z];
;                     if (t == 15) ((float*)(ws + WS_HGA + (size_t)task * 1024 + 512))[32 * j + 16 * ((2 * e2 + z) >> 2) + 4 * kq + ((2 * e2 + z) & 3)] = __expf(Lt); }
	v_add_f32_dpp v1, v96, v96 row_ror:8 row_mask:0xf bank_mask:0xf bound_ctrl:1
	s_nop 0
	v_mov_b32_dpp v99, v98 row_shr:8 row_mask:0xf bank_mask:0xf bound_ctrl:1
	v_add_f32_dpp v1, v1, v1 row_ror:4 row_mask:0xf bank_mask:0xf bound_ctrl:1
	s_nop 1
	v_add_f32_dpp v62, v1, v1 row_ror:2 row_mask:0xf bank_mask:0xf bound_ctrl:1
	v_add_f32_dpp v1, v96, v96 row_shr:1 row_mask:0xf bank_mask:0xf bound_ctrl:1
	s_nop 0
	v_mov_b32_dpp v65, v62 row_ror:1 row_mask:0xf bank_mask:0xf bound_ctrl:1
	v_add_f32_dpp v1, v1, v1 row_shr:2 row_mask:0xf bank_mask:0xf bound_ctrl:1
	s_nop 1
	v_add_f32_dpp v96, v1, v1 row_shr:4 row_mask:0xf bank_mask:0xf bound_ctrl:1
	v_add_f32_dpp v1, v32, v32 row_ror:8 row_mask:0xf bank_mask:0xf bound_ctrl:1
	s_nop 0
	v_mov_b32_dpp v97, v96 row_shr:8 row_mask:0xf bank_mask:0xf bound_ctrl:1
	v_add_f32_dpp v1, v1, v1 row_ror:4 row_mask:0xf bank_mask:0xf bound_ctrl:1
	s_nop 1
	v_add_f32_dpp v80, v1, v1 row_ror:2 row_mask:0xf bank_mask:0xf bound_ctrl:1
	v_add_f32_dpp v1, v32, v32 row_shr:1 row_mask:0xf bank_mask:0xf bound_ctrl:1
	s_nop 0
	v_mov_b32_dpp v86, v80 row_ror:1 row_mask:0xf bank_mask:0xf bound_ctrl:1
	v_add_f32_dpp v1, v1, v1 row_shr:2 row_mask:0xf bank_mask:0xf bound_ctrl:1
	s_nop 1
	v_add_f32_dpp v94, v1, v1 row_shr:4 row_mask:0xf bank_mask:0xf bound_ctrl:1
	v_add_f32_dpp v1, v33, v33 row_ror:8 row_mask:0xf bank_mask:0xf bound_ctrl:1
	s_nop 0
	v_mov_b32_dpp v95, v94 row_shr:8 row_mask:0xf bank_mask:0xf bound_ctrl:1
	v_add_f32_dpp v1, v1, v1 row_ror:4 row_mask:0xf bank_mask:0xf bound_ctrl:1
	s_nop 1
	v_add_f32_dpp v85, v1, v1 row_ror:2 row_mask:0xf bank_mask:0xf bound_ctrl:1
	v_add_f32_dpp v1, v33, v33 row_shr:1 row_mask:0xf bank_mask:0xf bound_ctrl:1
	s_nop 0
	v_mov_b32_dpp v87, v85 row_ror:1 row_mask:0xf bank_mask:0xf bound_ctrl:1
	v_add_f32_dpp v1, v1, v1 row_shr:2 row_mask:0xf bank_mask:0xf bound_ctrl:1
	s_nop 1
	v_add_f32_dpp v92, v1, v1 row_shr:4 row_mask:0xf bank_mask:0xf bound_ctrl:1
	v_add_f32_dpp v1, v190, v190 row_ror:8 row_mask:0xf bank_mask:0xf bound_ctrl:1
	s_nop 0
	v_mov_b32_dpp v93, v92 row_shr:8 row_mask:0xf bank_mask:0xf bound_ctrl:1
	v_add_f32_dpp v1, v1, v1 row_ror:4 row_mask:0xf bank_mask:0xf bound_ctrl:1
	s_nop 1
	v_add_f32_dpp v78, v1, v1 row_ror:2 row_mask:0xf bank_mask:0xf bound_ctrl:1
	v_add_f32_dpp v1, v190, v190 row_shr:1 row_mask:0xf bank_mask:0xf bound_ctrl:1
	v_mul_f32_e32 v190, 0x3fb8aa3b, v48
	v_exp_f32_e32 v190, v190
	v_add_f32_dpp v1, v1, v1 row_shr:2 row_mask:0xf bank_mask:0xf bound_ctrl:1
	v_mov_b32_dpp v79, v78 row_ror:1 row_mask:0xf bank_mask:0xf bound_ctrl:1
	s_nop 0
	v_add_f32_dpp v90, v1, v1 row_shr:4 row_mask:0xf bank_mask:0xf bound_ctrl:1
	v_add_f32_dpp v1, v203, v203 row_ror:8 row_mask:0xf bank_mask:0xf bound_ctrl:1
	s_nop 0
	v_mov_b32_dpp v91, v90 row_shr:8 row_mask:0xf bank_mask:0xf bound_ctrl:1
	v_add_f32_dpp v1, v1, v1 row_ror:4 row_mask:0xf bank_mask:0xf bound_ctrl:1
	s_nop 1
	v_add_f32_dpp v72, v1, v1 row_ror:2 row_mask:0xf bank_mask:0xf bound_ctrl:1
	v_add_f32_dpp v1, v203, v203 row_shr:1 row_mask:0xf bank_mask:0xf bound_ctrl:1
	s_nop 0
	v_mov_b32_dpp v77, v72 row_ror:1 row_mask:0xf bank_mask:0xf bound_ctrl:1
	v_add_f32_dpp v1, v1, v1 row_shr:2 row_mask:0xf bank_mask:0xf bound_ctrl:1
	s_nop 1
	v_add_f32_dpp v88, v1, v1 row_shr:4 row_mask:0xf bank_mask:0xf bound_ctrl:1
	v_ashrrev_i32_e32 v1, 31, v0
	v_lshlrev_b64 v[32:33], 10, v[0:1]
	v_lshl_add_u64 v[46:47], s[12:13], 0, v[32:33]
	s_mov_b64 s[12:13], 0x3cf60200
	v_mov_b32_dpp v89, v88 row_shr:8 row_mask:0xf bank_mask:0xf bound_ctrl:1
	v_lshl_add_u64 v[46:47], v[46:47], 0, s[12:13]
	s_and_saveexec_b64 s[12:13], vcc
	s_cbranch_execz .LBB0_590
	v_lshl_add_u64 v[204:205], v[46:47], 0, v[2:3]
	global_store_dword v[204:205], v190, off

; __device__ __forceinline__ unsigned pk2(float lo, float hi) { unsigned r; asm("v_cvt_pk_bf16_f32 %0, %1, %2" : "=v"(r) : "v"(lo), "v"(hi)); return r; }
; __device__ __forceinline__ float sigm(float x) { return __builtin_amdgcn_rcpf(1.f + __expf(-x)); }
;     __device__ __forceinline__ void operator()(const f32x4 (&acc)[2][2][4][2], const Unit& u, int wr, int wc, int fr, int fq) const {
;     ...
;             for (int m = 0; m < 4; ++m) { const int row = row0 + ai * HALF + m * 16;
; #pragma unroll
;                 for (int bj = 0; bj < 2; ++bj) { const int col = col0 + bj * HALF;
;                     float gt[8]; unpack8(*(const u32x4*)(H + (size_t)row * NPAD + C_GATE + g * D + col), gt);
;                     float v[8];
; #pragma unroll
;                     for (int e = 0; e < 4; ++e) { v[e] = sigm(gt[e]) * acc[ai][bj][m][0][e]; v[4 + e] = sigm(gt[4 + e]) * acc[ai][bj][m][1][e]; }
;                     if (u.split) { float* cp = SCTX + ((size_t)u.slot * 512 + (row - u.pm * BM + (u.pm ? 256 : 0))) * D + col;
;                         *(f32x4*)cp = (f32x4){v[0], v[1], v[2], v[3]}; *(f32x4*)(cp + 4) = (f32x4){v[4], v[5], v[6], v[7]}; }
;                     else {
;                         bf16_t* sp = SB + (size_t)row * D + col;
;                         if (g > 0) { float pv[8]; unpack8(*(const u32x4*)sp, pv);
; #pragma unroll
;                             for (int e = 0; e < 8; ++e) v[e] += pv[e]; }
;                         u32x4 o; o.x = pk2(v[0], v[1]); o.y = pk2(v[2], v[3]); o.z = pk2(v[4], v[5]); o.w = pk2(v[6], v[7]); *(u32x4*)sp = o; } } }
.LBB0_883:
	s_lshl_b32 s11, s48, 8
	v_add_u32_e32 v142, s11, v148
	s_lshl_b32 s20, s4, 11
	v_mov_b64_e32 v[144:145], s[60:61]
	v_lshl_or_b32 v140, s6, 8, v150
	s_ashr_i32 s21, s20, 31
	v_mad_i64_i32 v[144:145], s[6:7], v142, s43, v[144:145]
	v_lshl_add_u64 v[144:145], s[20:21], 1, v[144:145]
	v_ashrrev_i32_e32 v141, 31, v140
	v_lshl_add_u64 v[146:147], v[140:141], 1, v[144:145]
	v_mov_b64_e32 v[214:215], v[146:147]
	s_mov_b64 s[6:7], 0x5840
	v_lshl_add_u64 v[216:217], v[146:147], 0, s[6:7]
	global_load_dwordx4 v[164:167], v[216:217], off
	global_load_dwordx4 v[168:171], v[216:217], off offset:256
	s_mov_b64 s[6:7], 0x8f840
	v_lshl_add_u64 v[216:217], v[146:147], 0, s[6:7]
	global_load_dwordx4 v[172:175], v[216:217], off
	global_load_dwordx4 v[176:179], v[216:217], off offset:256
	s_mov_b64 s[6:7], 0x119840
	v_lshl_add_u64 v[216:217], v[146:147], 0, s[6:7]
	global_load_dwordx4 v[180:183], v[216:217], off
	global_load_dwordx4 v[184:187], v[216:217], off offset:256
	s_mov_b64 s[6:7], 0x1a3840
	v_lshl_add_u64 v[216:217], v[146:147], 0, s[6:7]
	global_load_dwordx4 v[188:191], v[216:217], off
	global_load_dwordx4 v[192:195], v[216:217], off offset:256
	v_ashrrev_i32_e32 v211, 31, v142
	v_mov_b32_e32 v210, v142
	v_lshlrev_b64 v[210:211], 12, v[210:211]
	v_lshl_add_u64 v[210:211], s[38:39], 0, v[210:211]
	v_lshl_add_u64 v[210:211], v[140:141], 1, v[210:211]
	global_load_dwordx4 v[202:205], v[210:211], off
	global_load_dwordx4 v[206:209], v[210:211], off offset:256
	v_add_co_u32_e32 v144, vcc, s66, v146
	s_cmp_gt_i32 s4, 0
	s_nop 0
	v_addc_co_u32_e32 v145, vcc, 0, v147, vcc
	s_cselect_b64 s[4:5], -1, 0
	s_cmp_lg_u32 s9, 0
	s_cselect_b64 s[22:23], -1, 0
	s_cmp_eq_u32 s9, 0
	s_waitcnt vmcnt(9)
	v_mov_b64_e32 v[152:153], v[164:165]
	v_mov_b64_e32 v[154:155], v[166:167]
	v_lshlrev_b32_e32 v143, 16, v152
	v_and_b32_e32 v144, 0xffff0000, v152
	v_lshlrev_b32_e32 v145, 16, v153
	v_and_b32_e32 v152, 0xffff0000, v153
	v_lshlrev_b32_e32 v153, 16, v154
	v_and_b32_e32 v154, 0xffff0000, v154
	v_lshlrev_b32_e32 v156, 16, v155
	v_and_b32_e32 v155, 0xffff0000, v155
	v_mul_f32_e32 v143, 0xbfb8aa3b, v143
	v_mul_f32_e32 v153, 0xbfb8aa3b, v153
	v_mul_f32_e32 v144, 0xbfb8aa3b, v144
	v_mul_f32_e32 v154, 0xbfb8aa3b, v154
	v_mul_f32_e32 v145, 0xbfb8aa3b, v145
	v_mul_f32_e32 v156, 0xbfb8aa3b, v156
	v_mul_f32_e32 v152, 0xbfb8aa3b, v152
	v_mul_f32_e32 v155, 0xbfb8aa3b, v155
	v_exp_f32_e32 v143, v143
	v_exp_f32_e32 v153, v153
	v_exp_f32_e32 v144, v144
	v_exp_f32_e32 v154, v154
	v_exp_f32_e32 v145, v145
	v_exp_f32_e32 v156, v156
	v_exp_f32_e32 v152, v152
	v_exp_f32_e32 v155, v155
	v_add_f32_e32 v143, 1.0, v143
	v_add_f32_e32 v153, 1.0, v153
	v_add_f32_e32 v157, 1.0, v144
	v_add_f32_e32 v154, 1.0, v154
	v_add_f32_e32 v158, 1.0, v145
	v_add_f32_e32 v156, 1.0, v156
	v_add_f32_e32 v159, 1.0, v152
	v_add_f32_e32 v160, 1.0, v155
	v_rcp_f32_e32 v144, v143
	v_rcp_f32_e32 v152, v153
	v_rcp_f32_e32 v145, v157
	v_rcp_f32_e32 v153, v154
	v_rcp_f32_e32 v154, v158
	v_rcp_f32_e32 v156, v156
	v_rcp_f32_e32 v155, v159
	v_rcp_f32_e32 v157, v160
	v_pk_mul_f32 v[128:129], v[128:129], v[144:145]
	v_pk_mul_f32 v[124:125], v[124:125], v[152:153]
	v_pk_mul_f32 v[130:131], v[130:131], v[154:155]
	v_pk_mul_f32 v[126:127], v[126:127], v[156:157]
	s_cbranch_scc1 .LBB0_885
	s_ashr_i32 s9, s8, 31
	s_cmp_eq_u32 s48, 0
	s_cselect_b32 s6, 0, 0x100
	v_add_u32_e32 v144, s6, v148
	s_lshl_b64 s[6:7], s[8:9], 22
	v_ashrrev_i32_e32 v145, 31, v144
	s_add_u32 s6, s28, s6
	s_addc_u32 s7, s29, s7
	v_lshlrev_b64 v[144:145], 13, v[144:145]
	v_lshl_add_u64 v[144:145], s[6:7], 0, v[144:145]
	v_lshl_add_u64 v[144:145], v[140:141], 2, v[144:145]
	s_mov_b64 s[6:7], 0
	global_store_dwordx4 v[144:145], v[128:131], off
	global_store_dwordx4 v[144:145], v[124:127], off offset:16
	s_branch .LBB0_886

;     __device__ __forceinline__ void operator()(const f32x4 (&acc)[2][2][4][2], const Unit& u, int wr, int wc, int fr, int fq) const {
;     ...
;                         if (g > 0) { float pv[8]; unpack8(*(const u32x4*)sp, pv);
; #pragma unroll
;                             for (int e = 0; e < 8; ++e) v[e] += pv[e]; }
.LBB0_886:
	v_ashrrev_i32_e32 v143, 31, v142
	v_lshlrev_b64 v[144:145], 12, v[142:143]
	v_lshl_add_u64 v[144:145], s[38:39], 0, v[144:145]
	v_cndmask_b32_e64 v143, 0, 1, s[4:5]
	s_andn2_b64 vcc, exec, s[6:7]
	v_lshl_add_u64 v[144:145], v[140:141], 1, v[144:145]
	v_cmp_ne_u32_e64 s[4:5], 1, v143
	s_cbranch_vccnz .LBB0_890
	s_and_b64 vcc, exec, s[4:5]
	s_cbranch_vccnz .LBB0_889
	s_waitcnt vmcnt(1)
	v_mov_b64_e32 v[152:153], v[202:203]
	v_mov_b64_e32 v[154:155], v[204:205]
	v_lshlrev_b32_e32 v156, 16, v152
	v_and_b32_e32 v157, 0xffff0000, v152
	v_lshlrev_b32_e32 v152, 16, v153
	v_and_b32_e32 v153, 0xffff0000, v153
	v_pk_add_f32 v[130:131], v[130:131], v[152:153]
	v_lshlrev_b32_e32 v152, 16, v154
	v_and_b32_e32 v153, 0xffff0000, v154
	v_pk_add_f32 v[124:125], v[124:125], v[152:153]
	v_lshlrev_b32_e32 v152, 16, v155
	v_and_b32_e32 v153, 0xffff0000, v155
	v_pk_add_f32 v[128:129], v[128:129], v[156:157]
	v_pk_add_f32 v[126:127], v[126:127], v[152:153]

; __device__ __forceinline__ float sigm(float x) { return __builtin_amdgcn_rcpf(1.f + __expf(-x)); }
;     __device__ __forceinline__ void operator()(const f32x4 (&acc)[2][2][4][2], const Unit& u, int wr, int wc, int fr, int fq) const {
;     ...
;                     float gt[8]; unpack8(*(const u32x4*)(H + (size_t)row * NPAD + C_GATE + g * D + col), gt);
;                     float v[8];
; #pragma unroll
;                     for (int e = 0; e < 4; ++e) { v[e] = sigm(gt[e]) * acc[ai][bj][m][0][e]; v[4 + e] = sigm(gt[4 + e]) * acc[ai][bj][m][1][e]; }
;                     if (u.split) { float* cp = SCTX + ((size_t)u.slot * 512 + (row - u.pm * BM + (u.pm ? 256 : 0))) * D + col;
;                         *(f32x4*)cp = (f32x4){v[0], v[1], v[2], v[3]}; *(f32x4*)(cp + 4) = (f32x4){v[4], v[5], v[6], v[7]}; }
;                     else {
;                         bf16_t* sp = SB + (size_t)row * D + col;
;                         if (g > 0) { float pv[8]; unpack8(*(const u32x4*)sp, pv);
; #pragma unroll
;                             for (int e = 0; e < 8; ++e) v[e] += pv[e]; }
.LBB0_890:
	s_mov_b64 s[6:7], 0x5840
	v_lshl_add_u64 v[124:125], v[146:147], 0, s[6:7]
	s_andn2_b64 vcc, exec, s[22:23]
	v_mov_b32_e32 v212, 0x10000
	v_mov_b32_e32 v213, 0
	v_lshl_add_u64 v[212:213], v[210:211], 0, v[212:213]
	global_load_dwordx4 v[202:205], v[212:213], off
	s_waitcnt vmcnt(9)
	v_mov_b64_e32 v[124:125], v[168:169]
	v_mov_b64_e32 v[126:127], v[170:171]
	v_lshlrev_b32_e32 v130, 16, v125
	v_and_b32_e32 v131, 0xffff0000, v125
	v_lshlrev_b32_e32 v125, 16, v126
	v_mul_f32_e32 v125, 0xbfb8aa3b, v125
	v_exp_f32_e32 v125, v125
	v_lshlrev_b32_e32 v128, 16, v124
	v_and_b32_e32 v129, 0xffff0000, v124
	v_and_b32_e32 v143, 0xffff0000, v126
	v_add_f32_e32 v125, 1.0, v125
	v_mul_f32_e32 v124, 0xbfb8aa3b, v128
	v_rcp_f32_e32 v126, v125
	v_mul_f32_e32 v125, 0xbfb8aa3b, v129
	v_exp_f32_e32 v124, v124
	v_exp_f32_e32 v125, v125
	v_lshlrev_b32_e32 v146, 16, v127
	v_and_b32_e32 v147, 0xffff0000, v127
	v_add_f32_e32 v124, 1.0, v124
	v_add_f32_e32 v125, 1.0, v125
	v_rcp_f32_e32 v124, v124
	v_rcp_f32_e32 v125, v125
	s_nop 0
	v_pk_mul_f32 v[120:121], v[120:121], v[124:125]
	v_mul_f32_e32 v124, 0xbfb8aa3b, v143
	v_exp_f32_e32 v124, v124
	v_mul_f32_e32 v125, 0xbfb8aa3b, v146
	v_exp_f32_e32 v125, v125
	v_add_f32_e32 v124, 1.0, v124
	v_rcp_f32_e32 v127, v124
	v_add_f32_e32 v125, 1.0, v125
	v_mul_f32_e32 v124, 0xbfb8aa3b, v130
	v_exp_f32_e32 v124, v124
	v_pk_mul_f32 v[116:117], v[116:117], v[126:127]
	v_rcp_f32_e32 v126, v125
	v_mul_f32_e32 v125, 0xbfb8aa3b, v131
	v_exp_f32_e32 v125, v125
	v_add_f32_e32 v124, 1.0, v124
	v_rcp_f32_e32 v124, v124
	v_add_f32_e32 v125, 1.0, v125
	v_rcp_f32_e32 v125, v125
	s_nop 0
	v_pk_mul_f32 v[122:123], v[122:123], v[124:125]
	v_mul_f32_e32 v124, 0xbfb8aa3b, v147
	v_exp_f32_e32 v124, v124
	s_nop 0
	v_add_f32_e32 v124, 1.0, v124
	v_rcp_f32_e32 v127, v124
	v_cndmask_b32_e64 v124, 0, 1, s[22:23]
	v_cmp_ne_u32_e64 s[6:7], 1, v124
	v_pk_mul_f32 v[118:119], v[118:119], v[126:127]
	s_cbranch_vccnz .LBB0_892
	s_ashr_i32 s9, s8, 31
	s_cmp_eq_u32 s48, 0
	s_cselect_b32 s13, 0, 0x100
	v_add_u32_e32 v124, s13, v148
	s_lshl_b64 s[22:23], s[8:9], 22
	v_ashrrev_i32_e32 v125, 31, v124
	s_add_u32 s22, s28, s22
	s_addc_u32 s23, s29, s23
	v_lshlrev_b64 v[124:125], 13, v[124:125]
	v_lshl_add_u64 v[124:125], s[22:23], 0, v[124:125]
	v_lshl_add_u64 v[124:125], v[140:141], 2, v[124:125]
	global_store_dwordx4 v[124:125], v[120:123], off offset:512
	global_store_dwordx4 v[124:125], v[116:119], off offset:528
	s_cbranch_execz .LBB0_893
	s_branch .LBB0_896
.LBB0_892:
.LBB0_893:
	s_and_b64 vcc, exec, s[4:5]
	s_cbranch_vccnz .LBB0_895
	s_waitcnt vmcnt(1)
	v_mov_b64_e32 v[124:125], v[206:207]
	v_mov_b64_e32 v[126:127], v[208:209]
	v_lshlrev_b32_e32 v128, 16, v124
	v_and_b32_e32 v129, 0xffff0000, v124
	v_lshlrev_b32_e32 v124, 16, v125
	v_and_b32_e32 v125, 0xffff0000, v125
	v_pk_add_f32 v[122:123], v[122:123], v[124:125]
	v_lshlrev_b32_e32 v124, 16, v126
	v_and_b32_e32 v125, 0xffff0000, v126
	v_pk_add_f32 v[116:117], v[116:117], v[124:125]
	v_lshlrev_b32_e32 v124, 16, v127
	v_and_b32_e32 v125, 0xffff0000, v127
	v_pk_add_f32 v[120:121], v[120:121], v[128:129]
	v_pk_add_f32 v[118:119], v[118:119], v[124:125]

; __device__ __forceinline__ float sigm(float x) { return __builtin_amdgcn_rcpf(1.f + __expf(-x)); }
;     __device__ __forceinline__ void operator()(const f32x4 (&acc)[2][2][4][2], const Unit& u, int wr, int wc, int fr, int fq) const {
;     ...
;             for (int m = 0; m < 4; ++m) { const int row = row0 + ai * HALF + m * 16;
; #pragma unroll
;                 for (int bj = 0; bj < 2; ++bj) { const int col = col0 + bj * HALF;
;                     float gt[8]; unpack8(*(const u32x4*)(H + (size_t)row * NPAD + C_GATE + g * D + col), gt);
;                     float v[8];
; #pragma unroll
;                     for (int e = 0; e < 4; ++e) { v[e] = sigm(gt[e]) * acc[ai][bj][m][0][e]; v[4 + e] = sigm(gt[4 + e]) * acc[ai][bj][m][1][e]; }
;                     if (u.split) { float* cp = SCTX + ((size_t)u.slot * 512 + (row - u.pm * BM + (u.pm ? 256 : 0))) * D + col;
;                         *(f32x4*)cp = (f32x4){v[0], v[1], v[2], v[3]}; *(f32x4*)(cp + 4) = (f32x4){v[4], v[5], v[6], v[7]}; }
.LBB0_896:
	v_or_b32_e32 v116, 16, v142
	v_mov_b64_e32 v[118:119], s[60:61]
	v_mad_i64_i32 v[118:119], s[22:23], v116, s43, v[118:119]
	v_lshl_add_u64 v[118:119], s[20:21], 1, v[118:119]
	v_lshl_add_u64 v[120:121], v[140:141], 1, v[118:119]
	v_add_co_u32_e32 v118, vcc, 0x5000, v120
	s_nop 1
	v_addc_co_u32_e32 v119, vcc, 0, v121, vcc
	s_and_b64 vcc, exec, s[6:7]
	v_mov_b32_e32 v212, 0x10000
	v_mov_b32_e32 v213, 0
	v_lshl_add_u64 v[212:213], v[210:211], 0, v[212:213]
	global_load_dwordx4 v[206:209], v[212:213], off offset:256
	s_waitcnt vmcnt(9)
	v_mov_b64_e32 v[122:123], v[172:173]
	v_mov_b64_e32 v[124:125], v[174:175]
	v_lshlrev_b32_e32 v117, 16, v122
	v_mul_f32_e32 v117, 0xbfb8aa3b, v117
	v_exp_f32_e32 v117, v117
	v_and_b32_e32 v119, 0xffff0000, v122
	v_lshlrev_b32_e32 v122, 16, v124
	v_lshlrev_b32_e32 v126, 16, v123
	v_add_f32_e32 v117, 1.0, v117
	v_rcp_f32_e32 v118, v117
	v_mul_f32_e32 v117, 0xbfb8aa3b, v122
	v_exp_f32_e32 v117, v117
	v_and_b32_e32 v127, 0xffff0000, v123
	v_and_b32_e32 v123, 0xffff0000, v124
	v_lshlrev_b32_e32 v124, 16, v125
	v_add_f32_e32 v117, 1.0, v117
	v_rcp_f32_e32 v122, v117
	v_mul_f32_e32 v117, 0xbfb8aa3b, v119
	v_exp_f32_e32 v117, v117
	v_and_b32_e32 v125, 0xffff0000, v125
	v_add_f32_e32 v117, 1.0, v117
	v_rcp_f32_e32 v119, v117
	v_mul_f32_e32 v117, 0xbfb8aa3b, v123
	v_exp_f32_e32 v117, v117
	v_pk_mul_f32 v[112:113], v[112:113], v[118:119]
	v_add_f32_e32 v117, 1.0, v117
	v_rcp_f32_e32 v123, v117
	v_mul_f32_e32 v117, 0xbfb8aa3b, v126
	v_exp_f32_e32 v117, v117
	v_pk_mul_f32 v[108:109], v[108:109], v[122:123]
	v_add_f32_e32 v117, 1.0, v117
	v_rcp_f32_e32 v118, v117
	v_mul_f32_e32 v117, 0xbfb8aa3b, v124
	v_exp_f32_e32 v117, v117
	s_nop 0
	v_add_f32_e32 v117, 1.0, v117
	v_rcp_f32_e32 v122, v117
	v_mul_f32_e32 v117, 0xbfb8aa3b, v127
	v_exp_f32_e32 v117, v117
	s_nop 0
	v_add_f32_e32 v117, 1.0, v117
	v_rcp_f32_e32 v119, v117
	v_mul_f32_e32 v117, 0xbfb8aa3b, v125
	v_exp_f32_e32 v117, v117
	v_pk_mul_f32 v[114:115], v[114:115], v[118:119]
	v_add_f32_e32 v117, 1.0, v117
	v_rcp_f32_e32 v123, v117
	s_nop 0
	v_pk_mul_f32 v[110:111], v[110:111], v[122:123]
	s_cbranch_vccnz .LBB0_898
	s_ashr_i32 s9, s8, 31
	s_cmp_eq_u32 s48, 0
	s_cselect_b32 s13, 0, 0x100
	s_sub_i32 s13, s13, s11
	v_add_u32_e32 v118, s13, v116
	s_lshl_b64 s[22:23], s[8:9], 22
	v_ashrrev_i32_e32 v119, 31, v118
	s_add_u32 s22, s28, s22
	s_addc_u32 s23, s29, s23
	v_lshlrev_b64 v[118:119], 13, v[118:119]
	v_lshl_add_u64 v[118:119], s[22:23], 0, v[118:119]
	v_lshl_add_u64 v[118:119], v[140:141], 2, v[118:119]
	s_mov_b64 s[22:23], 0
	global_store_dwordx4 v[118:119], v[112:115], off
	global_store_dwordx4 v[118:119], v[108:111], off offset:16
	s_branch .LBB0_899

;     __device__ __forceinline__ void operator()(const f32x4 (&acc)[2][2][4][2], const Unit& u, int wr, int wc, int fr, int fq) const {
;     ...
;                         if (g > 0) { float pv[8]; unpack8(*(const u32x4*)sp, pv);
; #pragma unroll
;                             for (int e = 0; e < 8; ++e) v[e] += pv[e]; }
.LBB0_899:
	v_ashrrev_i32_e32 v117, 31, v116
	v_lshlrev_b64 v[118:119], 12, v[116:117]
	v_lshl_add_u64 v[118:119], s[38:39], 0, v[118:119]
	s_andn2_b64 vcc, exec, s[22:23]
	v_lshl_add_u64 v[118:119], v[140:141], 1, v[118:119]
	s_cbranch_vccnz .LBB0_903
	s_and_b64 vcc, exec, s[4:5]
	s_cbranch_vccnz .LBB0_902
	s_waitcnt vmcnt(1)
	v_mov_b64_e32 v[122:123], v[202:203]
	v_mov_b64_e32 v[124:125], v[204:205]
	v_lshlrev_b32_e32 v126, 16, v122
	v_and_b32_e32 v127, 0xffff0000, v122
	v_lshlrev_b32_e32 v122, 16, v123
	v_and_b32_e32 v123, 0xffff0000, v123
	v_pk_add_f32 v[114:115], v[114:115], v[122:123]
	v_lshlrev_b32_e32 v122, 16, v124
	v_and_b32_e32 v123, 0xffff0000, v124
	v_pk_add_f32 v[108:109], v[108:109], v[122:123]
	v_lshlrev_b32_e32 v122, 16, v125
	v_and_b32_e32 v123, 0xffff0000, v125
	v_pk_add_f32 v[112:113], v[112:113], v[126:127]
	v_pk_add_f32 v[110:111], v[110:111], v[122:123]

; __device__ __forceinline__ float sigm(float x) { return __builtin_amdgcn_rcpf(1.f + __expf(-x)); }
;     __device__ __forceinline__ void operator()(const f32x4 (&acc)[2][2][4][2], const Unit& u, int wr, int wc, int fr, int fq) const {
;     ...
;                     float gt[8]; unpack8(*(const u32x4*)(H + (size_t)row * NPAD + C_GATE + g * D + col), gt);
;                     float v[8];
; #pragma unroll
;                     for (int e = 0; e < 4; ++e) { v[e] = sigm(gt[e]) * acc[ai][bj][m][0][e]; v[4 + e] = sigm(gt[4 + e]) * acc[ai][bj][m][1][e]; }
;                     if (u.split) { float* cp = SCTX + ((size_t)u.slot * 512 + (row - u.pm * BM + (u.pm ? 256 : 0))) * D + col;
;                         *(f32x4*)cp = (f32x4){v[0], v[1], v[2], v[3]}; *(f32x4*)(cp + 4) = (f32x4){v[4], v[5], v[6], v[7]}; }
;                     else {
;                         bf16_t* sp = SB + (size_t)row * D + col;
;                         if (g > 0) { float pv[8]; unpack8(*(const u32x4*)sp, pv);
; #pragma unroll
;                             for (int e = 0; e < 8; ++e) v[e] += pv[e]; }
.LBB0_903:
	s_mov_b64 s[22:23], 0x5840
	v_lshl_add_u64 v[108:109], v[120:121], 0, s[22:23]
	s_and_b64 vcc, exec, s[6:7]
	v_mov_b32_e32 v212, 0x20000
	v_mov_b32_e32 v213, 0
	v_lshl_add_u64 v[212:213], v[210:211], 0, v[212:213]
	global_load_dwordx4 v[202:205], v[212:213], off
	s_waitcnt vmcnt(9)
	v_mov_b64_e32 v[108:109], v[176:177]
	v_mov_b64_e32 v[110:111], v[178:179]
	v_lshlrev_b32_e32 v114, 16, v109
	v_and_b32_e32 v115, 0xffff0000, v109
	v_lshlrev_b32_e32 v109, 16, v110
	v_mul_f32_e32 v109, 0xbfb8aa3b, v109
	v_exp_f32_e32 v109, v109
	v_lshlrev_b32_e32 v112, 16, v108
	v_and_b32_e32 v113, 0xffff0000, v108
	v_and_b32_e32 v117, 0xffff0000, v110
	v_add_f32_e32 v109, 1.0, v109
	v_mul_f32_e32 v108, 0xbfb8aa3b, v112
	v_rcp_f32_e32 v110, v109
	v_mul_f32_e32 v109, 0xbfb8aa3b, v113
	v_exp_f32_e32 v108, v108
	v_exp_f32_e32 v109, v109
	v_lshlrev_b32_e32 v120, 16, v111
	v_and_b32_e32 v121, 0xffff0000, v111
	v_add_f32_e32 v108, 1.0, v108
	v_add_f32_e32 v109, 1.0, v109
	v_rcp_f32_e32 v108, v108
	v_rcp_f32_e32 v109, v109
	s_nop 0
	v_pk_mul_f32 v[104:105], v[104:105], v[108:109]
	v_mul_f32_e32 v108, 0xbfb8aa3b, v117
	v_exp_f32_e32 v108, v108
	v_mul_f32_e32 v109, 0xbfb8aa3b, v120
	v_exp_f32_e32 v109, v109
	v_add_f32_e32 v108, 1.0, v108
	v_rcp_f32_e32 v111, v108
	v_add_f32_e32 v109, 1.0, v109
	v_mul_f32_e32 v108, 0xbfb8aa3b, v114
	v_exp_f32_e32 v108, v108
	v_pk_mul_f32 v[100:101], v[100:101], v[110:111]
	v_rcp_f32_e32 v110, v109
	v_mul_f32_e32 v109, 0xbfb8aa3b, v115
	v_exp_f32_e32 v109, v109
	v_add_f32_e32 v108, 1.0, v108
	v_rcp_f32_e32 v108, v108
	v_add_f32_e32 v109, 1.0, v109
	v_rcp_f32_e32 v109, v109
	s_nop 0
	v_pk_mul_f32 v[106:107], v[106:107], v[108:109]
	v_mul_f32_e32 v108, 0xbfb8aa3b, v121
	v_exp_f32_e32 v108, v108
	s_nop 0
	v_add_f32_e32 v108, 1.0, v108
	v_rcp_f32_e32 v111, v108
	s_nop 0
	v_pk_mul_f32 v[102:103], v[102:103], v[110:111]
	s_cbranch_vccnz .LBB0_905
	s_ashr_i32 s9, s8, 31
	s_cmp_eq_u32 s48, 0
	s_cselect_b32 s13, 0, 0x100
	s_sub_i32 s13, s13, s11
	v_add_u32_e32 v108, s13, v116
	s_lshl_b64 s[22:23], s[8:9], 22
	v_ashrrev_i32_e32 v109, 31, v108
	s_add_u32 s22, s28, s22
	s_addc_u32 s23, s29, s23
	v_lshlrev_b64 v[108:109], 13, v[108:109]
	v_lshl_add_u64 v[108:109], s[22:23], 0, v[108:109]
	v_lshl_add_u64 v[108:109], v[140:141], 2, v[108:109]
	global_store_dwordx4 v[108:109], v[104:107], off offset:512
	global_store_dwordx4 v[108:109], v[100:103], off offset:528
	s_cbranch_execz .LBB0_906
	s_branch .LBB0_909
.LBB0_905:
.LBB0_906:
	s_and_b64 vcc, exec, s[4:5]
	s_cbranch_vccnz .LBB0_908
	s_waitcnt vmcnt(1)
	v_mov_b64_e32 v[108:109], v[206:207]
	v_mov_b64_e32 v[110:111], v[208:209]
	v_lshlrev_b32_e32 v112, 16, v108
	v_and_b32_e32 v113, 0xffff0000, v108
	v_lshlrev_b32_e32 v108, 16, v109
	v_and_b32_e32 v109, 0xffff0000, v109
	v_pk_add_f32 v[106:107], v[106:107], v[108:109]
	v_lshlrev_b32_e32 v108, 16, v110
	v_and_b32_e32 v109, 0xffff0000, v110
	v_pk_add_f32 v[100:101], v[100:101], v[108:109]
	v_lshlrev_b32_e32 v108, 16, v111
	v_and_b32_e32 v109, 0xffff0000, v111
	v_pk_add_f32 v[104:105], v[104:105], v[112:113]
	v_pk_add_f32 v[102:103], v[102:103], v[108:109]

; __device__ __forceinline__ float sigm(float x) { return __builtin_amdgcn_rcpf(1.f + __expf(-x)); }
;     __device__ __forceinline__ void operator()(const f32x4 (&acc)[2][2][4][2], const Unit& u, int wr, int wc, int fr, int fq) const {
;     ...
;             for (int m = 0; m < 4; ++m) { const int row = row0 + ai * HALF + m * 16;
; #pragma unroll
;                 for (int bj = 0; bj < 2; ++bj) { const int col = col0 + bj * HALF;
;                     float gt[8]; unpack8(*(const u32x4*)(H + (size_t)row * NPAD + C_GATE + g * D + col), gt);
;                     float v[8];
; #pragma unroll
;                     for (int e = 0; e < 4; ++e) { v[e] = sigm(gt[e]) * acc[ai][bj][m][0][e]; v[4 + e] = sigm(gt[4 + e]) * acc[ai][bj][m][1][e]; }
;                     if (u.split) { float* cp = SCTX + ((size_t)u.slot * 512 + (row - u.pm * BM + (u.pm ? 256 : 0))) * D + col;
;                         *(f32x4*)cp = (f32x4){v[0], v[1], v[2], v[3]}; *(f32x4*)(cp + 4) = (f32x4){v[4], v[5], v[6], v[7]}; }
.LBB0_909:
	v_or_b32_e32 v100, 32, v142
	v_mov_b64_e32 v[102:103], s[60:61]
	v_mad_i64_i32 v[102:103], s[22:23], v100, s43, v[102:103]
	v_lshl_add_u64 v[102:103], s[20:21], 1, v[102:103]
	v_lshl_add_u64 v[104:105], v[140:141], 1, v[102:103]
	v_add_co_u32_e32 v102, vcc, 0x5000, v104
	s_nop 1
	v_addc_co_u32_e32 v103, vcc, 0, v105, vcc
	s_and_b64 vcc, exec, s[6:7]
	v_mov_b32_e32 v212, 0x20000
	v_mov_b32_e32 v213, 0
	v_lshl_add_u64 v[212:213], v[210:211], 0, v[212:213]
	global_load_dwordx4 v[206:209], v[212:213], off offset:256
	s_waitcnt vmcnt(9)
	v_mov_b64_e32 v[106:107], v[180:181]
	v_mov_b64_e32 v[108:109], v[182:183]
	v_lshlrev_b32_e32 v101, 16, v106
	v_mul_f32_e32 v101, 0xbfb8aa3b, v101
	v_exp_f32_e32 v101, v101
	v_and_b32_e32 v103, 0xffff0000, v106
	v_lshlrev_b32_e32 v106, 16, v108
	v_lshlrev_b32_e32 v110, 16, v107
	v_add_f32_e32 v101, 1.0, v101
	v_rcp_f32_e32 v102, v101
	v_mul_f32_e32 v101, 0xbfb8aa3b, v106
	v_exp_f32_e32 v101, v101
	v_and_b32_e32 v111, 0xffff0000, v107
	v_and_b32_e32 v107, 0xffff0000, v108
	v_lshlrev_b32_e32 v108, 16, v109
	v_add_f32_e32 v101, 1.0, v101
	v_rcp_f32_e32 v106, v101
	v_mul_f32_e32 v101, 0xbfb8aa3b, v103
	v_exp_f32_e32 v101, v101
	v_and_b32_e32 v109, 0xffff0000, v109
	v_add_f32_e32 v101, 1.0, v101
	v_rcp_f32_e32 v103, v101
	v_mul_f32_e32 v101, 0xbfb8aa3b, v107
	v_exp_f32_e32 v101, v101
	v_pk_mul_f32 v[96:97], v[96:97], v[102:103]
	v_add_f32_e32 v101, 1.0, v101
	v_rcp_f32_e32 v107, v101
	v_mul_f32_e32 v101, 0xbfb8aa3b, v110
	v_exp_f32_e32 v101, v101
	v_pk_mul_f32 v[92:93], v[92:93], v[106:107]
	v_add_f32_e32 v101, 1.0, v101
	v_rcp_f32_e32 v102, v101
	v_mul_f32_e32 v101, 0xbfb8aa3b, v108
	v_exp_f32_e32 v101, v101
	s_nop 0
	v_add_f32_e32 v101, 1.0, v101
	v_rcp_f32_e32 v106, v101
	v_mul_f32_e32 v101, 0xbfb8aa3b, v111
	v_exp_f32_e32 v101, v101
	s_nop 0
	v_add_f32_e32 v101, 1.0, v101
	v_rcp_f32_e32 v103, v101
	v_mul_f32_e32 v101, 0xbfb8aa3b, v109
	v_exp_f32_e32 v101, v101
	v_pk_mul_f32 v[98:99], v[98:99], v[102:103]
	v_add_f32_e32 v101, 1.0, v101
	v_rcp_f32_e32 v107, v101
	s_nop 0
	v_pk_mul_f32 v[94:95], v[94:95], v[106:107]
	s_cbranch_vccnz .LBB0_911
	s_ashr_i32 s9, s8, 31
	s_cmp_eq_u32 s48, 0
	s_cselect_b32 s13, 0, 0x100
	s_sub_i32 s13, s13, s11
	v_add_u32_e32 v102, s13, v100
	s_lshl_b64 s[22:23], s[8:9], 22
	v_ashrrev_i32_e32 v103, 31, v102
	s_add_u32 s22, s28, s22
	s_addc_u32 s23, s29, s23
	v_lshlrev_b64 v[102:103], 13, v[102:103]
	v_lshl_add_u64 v[102:103], s[22:23], 0, v[102:103]
	v_lshl_add_u64 v[102:103], v[140:141], 2, v[102:103]
	s_mov_b64 s[22:23], 0
	global_store_dwordx4 v[102:103], v[96:99], off
	global_store_dwordx4 v[102:103], v[92:95], off offset:16
	s_branch .LBB0_912

;     __device__ __forceinline__ void operator()(const f32x4 (&acc)[2][2][4][2], const Unit& u, int wr, int wc, int fr, int fq) const {
;     ...
;                         if (g > 0) { float pv[8]; unpack8(*(const u32x4*)sp, pv);
; #pragma unroll
;                             for (int e = 0; e < 8; ++e) v[e] += pv[e]; }
.LBB0_912:
	v_ashrrev_i32_e32 v101, 31, v100
	v_lshlrev_b64 v[102:103], 12, v[100:101]
	v_lshl_add_u64 v[102:103], s[38:39], 0, v[102:103]
	s_andn2_b64 vcc, exec, s[22:23]
	v_lshl_add_u64 v[102:103], v[140:141], 1, v[102:103]
	s_cbranch_vccnz .LBB0_916
	s_and_b64 vcc, exec, s[4:5]
	s_cbranch_vccnz .LBB0_915
	s_waitcnt vmcnt(1)
	v_mov_b64_e32 v[106:107], v[202:203]
	v_mov_b64_e32 v[108:109], v[204:205]
	v_lshlrev_b32_e32 v110, 16, v106
	v_and_b32_e32 v111, 0xffff0000, v106
	v_lshlrev_b32_e32 v106, 16, v107
	v_and_b32_e32 v107, 0xffff0000, v107
	v_pk_add_f32 v[98:99], v[98:99], v[106:107]
	v_lshlrev_b32_e32 v106, 16, v108
	v_and_b32_e32 v107, 0xffff0000, v108
	v_pk_add_f32 v[92:93], v[92:93], v[106:107]
	v_lshlrev_b32_e32 v106, 16, v109
	v_and_b32_e32 v107, 0xffff0000, v109
	v_pk_add_f32 v[96:97], v[96:97], v[110:111]
	v_pk_add_f32 v[94:95], v[94:95], v[106:107]

; __device__ __forceinline__ float sigm(float x) { return __builtin_amdgcn_rcpf(1.f + __expf(-x)); }
;     __device__ __forceinline__ void operator()(const f32x4 (&acc)[2][2][4][2], const Unit& u, int wr, int wc, int fr, int fq) const {
;     ...
;                     float gt[8]; unpack8(*(const u32x4*)(H + (size_t)row * NPAD + C_GATE + g * D + col), gt);
;                     float v[8];
; #pragma unroll
;                     for (int e = 0; e < 4; ++e) { v[e] = sigm(gt[e]) * acc[ai][bj][m][0][e]; v[4 + e] = sigm(gt[4 + e]) * acc[ai][bj][m][1][e]; }
;                     if (u.split) { float* cp = SCTX + ((size_t)u.slot * 512 + (row - u.pm * BM + (u.pm ? 256 : 0))) * D + col;
;                         *(f32x4*)cp = (f32x4){v[0], v[1], v[2], v[3]}; *(f32x4*)(cp + 4) = (f32x4){v[4], v[5], v[6], v[7]}; }
;                     else {
;                         bf16_t* sp = SB + (size_t)row * D + col;
;                         if (g > 0) { float pv[8]; unpack8(*(const u32x4*)sp, pv);
; #pragma unroll
;                             for (int e = 0; e < 8; ++e) v[e] += pv[e]; }
.LBB0_916:
	s_mov_b64 s[22:23], 0x5840
	v_lshl_add_u64 v[92:93], v[104:105], 0, s[22:23]
	s_and_b64 vcc, exec, s[6:7]
	v_mov_b32_e32 v212, 0x30000
	v_mov_b32_e32 v213, 0
	v_lshl_add_u64 v[212:213], v[210:211], 0, v[212:213]
	global_load_dwordx4 v[202:205], v[212:213], off
	s_waitcnt vmcnt(9)
	v_mov_b64_e32 v[92:93], v[184:185]
	v_mov_b64_e32 v[94:95], v[186:187]
	v_lshlrev_b32_e32 v98, 16, v93
	v_and_b32_e32 v99, 0xffff0000, v93
	v_lshlrev_b32_e32 v93, 16, v94
	v_mul_f32_e32 v93, 0xbfb8aa3b, v93
	v_exp_f32_e32 v93, v93
	v_lshlrev_b32_e32 v96, 16, v92
	v_and_b32_e32 v97, 0xffff0000, v92
	v_and_b32_e32 v101, 0xffff0000, v94
	v_add_f32_e32 v93, 1.0, v93
	v_mul_f32_e32 v92, 0xbfb8aa3b, v96
	v_rcp_f32_e32 v94, v93
	v_mul_f32_e32 v93, 0xbfb8aa3b, v97
	v_exp_f32_e32 v92, v92
	v_exp_f32_e32 v93, v93
	v_lshlrev_b32_e32 v104, 16, v95
	v_and_b32_e32 v105, 0xffff0000, v95
	v_add_f32_e32 v92, 1.0, v92
	v_add_f32_e32 v93, 1.0, v93
	v_rcp_f32_e32 v92, v92
	v_rcp_f32_e32 v93, v93
	s_nop 0
	v_pk_mul_f32 v[88:89], v[88:89], v[92:93]
	v_mul_f32_e32 v92, 0xbfb8aa3b, v101
	v_exp_f32_e32 v92, v92
	v_mul_f32_e32 v93, 0xbfb8aa3b, v104
	v_exp_f32_e32 v93, v93
	v_add_f32_e32 v92, 1.0, v92
	v_rcp_f32_e32 v95, v92
	v_add_f32_e32 v93, 1.0, v93
	v_mul_f32_e32 v92, 0xbfb8aa3b, v98
	v_exp_f32_e32 v92, v92
	v_pk_mul_f32 v[84:85], v[84:85], v[94:95]
	v_rcp_f32_e32 v94, v93
	v_mul_f32_e32 v93, 0xbfb8aa3b, v99
	v_exp_f32_e32 v93, v93
	v_add_f32_e32 v92, 1.0, v92
	v_rcp_f32_e32 v92, v92
	v_add_f32_e32 v93, 1.0, v93
	v_rcp_f32_e32 v93, v93
	s_nop 0
	v_pk_mul_f32 v[90:91], v[90:91], v[92:93]
	v_mul_f32_e32 v92, 0xbfb8aa3b, v105
	v_exp_f32_e32 v92, v92
	s_nop 0
	v_add_f32_e32 v92, 1.0, v92
	v_rcp_f32_e32 v95, v92
	s_nop 0
	v_pk_mul_f32 v[86:87], v[86:87], v[94:95]
	s_cbranch_vccnz .LBB0_918
	s_ashr_i32 s9, s8, 31
	s_cmp_eq_u32 s48, 0
	s_cselect_b32 s13, 0, 0x100
	s_sub_i32 s13, s13, s11
	v_add_u32_e32 v92, s13, v100
	s_lshl_b64 s[22:23], s[8:9], 22
	v_ashrrev_i32_e32 v93, 31, v92
	s_add_u32 s22, s28, s22
	s_addc_u32 s23, s29, s23
	v_lshlrev_b64 v[92:93], 13, v[92:93]
	v_lshl_add_u64 v[92:93], s[22:23], 0, v[92:93]
	v_lshl_add_u64 v[92:93], v[140:141], 2, v[92:93]
	global_store_dwordx4 v[92:93], v[88:91], off offset:512
	global_store_dwordx4 v[92:93], v[84:87], off offset:528
	s_cbranch_execz .LBB0_919
	s_branch .LBB0_922
.LBB0_918:
.LBB0_919:
	s_and_b64 vcc, exec, s[4:5]
	s_cbranch_vccnz .LBB0_921
	s_waitcnt vmcnt(1)
	v_mov_b64_e32 v[92:93], v[206:207]
	v_mov_b64_e32 v[94:95], v[208:209]
	v_lshlrev_b32_e32 v96, 16, v92
	v_and_b32_e32 v97, 0xffff0000, v92
	v_lshlrev_b32_e32 v92, 16, v93
	v_and_b32_e32 v93, 0xffff0000, v93
	v_pk_add_f32 v[90:91], v[90:91], v[92:93]
	v_lshlrev_b32_e32 v92, 16, v94
	v_and_b32_e32 v93, 0xffff0000, v94
	v_pk_add_f32 v[84:85], v[84:85], v[92:93]
	v_lshlrev_b32_e32 v92, 16, v95
	v_and_b32_e32 v93, 0xffff0000, v95
	v_pk_add_f32 v[88:89], v[88:89], v[96:97]
	v_pk_add_f32 v[86:87], v[86:87], v[92:93]

; __device__ __forceinline__ float sigm(float x) { return __builtin_amdgcn_rcpf(1.f + __expf(-x)); }
;     __device__ __forceinline__ void operator()(const f32x4 (&acc)[2][2][4][2], const Unit& u, int wr, int wc, int fr, int fq) const {
;     ...
;             for (int m = 0; m < 4; ++m) { const int row = row0 + ai * HALF + m * 16;
; #pragma unroll
;                 for (int bj = 0; bj < 2; ++bj) { const int col = col0 + bj * HALF;
;                     float gt[8]; unpack8(*(const u32x4*)(H + (size_t)row * NPAD + C_GATE + g * D + col), gt);
;                     float v[8];
; #pragma unroll
;                     for (int e = 0; e < 4; ++e) { v[e] = sigm(gt[e]) * acc[ai][bj][m][0][e]; v[4 + e] = sigm(gt[4 + e]) * acc[ai][bj][m][1][e]; }
;                     if (u.split) { float* cp = SCTX + ((size_t)u.slot * 512 + (row - u.pm * BM + (u.pm ? 256 : 0))) * D + col;
;                         *(f32x4*)cp = (f32x4){v[0], v[1], v[2], v[3]}; *(f32x4*)(cp + 4) = (f32x4){v[4], v[5], v[6], v[7]}; }
.LBB0_922:
	v_or_b32_e32 v84, 48, v142
	v_mov_b64_e32 v[86:87], s[60:61]
	v_mad_i64_i32 v[86:87], s[22:23], v84, s43, v[86:87]
	v_lshl_add_u64 v[86:87], s[20:21], 1, v[86:87]
	v_lshl_add_u64 v[88:89], v[140:141], 1, v[86:87]
	v_add_co_u32_e32 v86, vcc, 0x5000, v88
	s_nop 1
	v_addc_co_u32_e32 v87, vcc, 0, v89, vcc
	s_and_b64 vcc, exec, s[6:7]
	v_mov_b32_e32 v212, 0x30000
	v_mov_b32_e32 v213, 0
	v_lshl_add_u64 v[212:213], v[210:211], 0, v[212:213]
	global_load_dwordx4 v[206:209], v[212:213], off offset:256
	s_waitcnt vmcnt(9)
	v_mov_b64_e32 v[90:91], v[188:189]
	v_mov_b64_e32 v[92:93], v[190:191]
	v_lshlrev_b32_e32 v85, 16, v90
	v_mul_f32_e32 v85, 0xbfb8aa3b, v85
	v_exp_f32_e32 v85, v85
	v_and_b32_e32 v87, 0xffff0000, v90
	v_lshlrev_b32_e32 v90, 16, v92
	v_lshlrev_b32_e32 v94, 16, v91
	v_add_f32_e32 v85, 1.0, v85
	v_rcp_f32_e32 v86, v85
	v_mul_f32_e32 v85, 0xbfb8aa3b, v90
	v_exp_f32_e32 v85, v85
	v_and_b32_e32 v95, 0xffff0000, v91
	v_and_b32_e32 v91, 0xffff0000, v92
	v_lshlrev_b32_e32 v92, 16, v93
	v_add_f32_e32 v85, 1.0, v85
	v_rcp_f32_e32 v90, v85
	v_mul_f32_e32 v85, 0xbfb8aa3b, v87
	v_exp_f32_e32 v85, v85
	v_and_b32_e32 v93, 0xffff0000, v93
	v_add_f32_e32 v85, 1.0, v85
	v_rcp_f32_e32 v87, v85
	v_mul_f32_e32 v85, 0xbfb8aa3b, v91
	v_exp_f32_e32 v85, v85
	v_pk_mul_f32 v[80:81], v[80:81], v[86:87]
	v_add_f32_e32 v85, 1.0, v85
	v_rcp_f32_e32 v91, v85
	v_mul_f32_e32 v85, 0xbfb8aa3b, v94
	v_exp_f32_e32 v85, v85
	v_pk_mul_f32 v[76:77], v[76:77], v[90:91]
	v_add_f32_e32 v85, 1.0, v85
	v_rcp_f32_e32 v86, v85
	v_mul_f32_e32 v85, 0xbfb8aa3b, v92
	v_exp_f32_e32 v85, v85
	s_nop 0
	v_add_f32_e32 v85, 1.0, v85
	v_rcp_f32_e32 v90, v85
	v_mul_f32_e32 v85, 0xbfb8aa3b, v95
	v_exp_f32_e32 v85, v85
	s_nop 0
	v_add_f32_e32 v85, 1.0, v85
	v_rcp_f32_e32 v87, v85
	v_mul_f32_e32 v85, 0xbfb8aa3b, v93
	v_exp_f32_e32 v85, v85
	v_pk_mul_f32 v[82:83], v[82:83], v[86:87]
	v_add_f32_e32 v85, 1.0, v85
	v_rcp_f32_e32 v91, v85
	s_nop 0
	v_pk_mul_f32 v[78:79], v[78:79], v[90:91]
	s_cbranch_vccnz .LBB0_924
	s_ashr_i32 s9, s8, 31
	s_cmp_eq_u32 s48, 0
	s_cselect_b32 s13, 0, 0x100
	s_sub_i32 s13, s13, s11
	v_add_u32_e32 v86, s13, v84
	s_lshl_b64 s[22:23], s[8:9], 22
	v_ashrrev_i32_e32 v87, 31, v86
	s_add_u32 s22, s28, s22
	s_addc_u32 s23, s29, s23
	v_lshlrev_b64 v[86:87], 13, v[86:87]
	v_lshl_add_u64 v[86:87], s[22:23], 0, v[86:87]
	v_lshl_add_u64 v[86:87], v[140:141], 2, v[86:87]
	s_mov_b64 s[22:23], 0
	global_store_dwordx4 v[86:87], v[80:83], off
	global_store_dwordx4 v[86:87], v[76:79], off offset:16
	s_branch .LBB0_925

;     __device__ __forceinline__ void operator()(const f32x4 (&acc)[2][2][4][2], const Unit& u, int wr, int wc, int fr, int fq) const {
;     ...
;                         if (g > 0) { float pv[8]; unpack8(*(const u32x4*)sp, pv);
; #pragma unroll
;                             for (int e = 0; e < 8; ++e) v[e] += pv[e]; }
.LBB0_925:
	v_ashrrev_i32_e32 v85, 31, v84
	v_lshlrev_b64 v[86:87], 12, v[84:85]
	v_lshl_add_u64 v[86:87], s[38:39], 0, v[86:87]
	s_andn2_b64 vcc, exec, s[22:23]
	v_lshl_add_u64 v[86:87], v[140:141], 1, v[86:87]
	s_cbranch_vccnz .LBB0_929
	s_and_b64 vcc, exec, s[4:5]
	s_cbranch_vccnz .LBB0_928
	s_waitcnt vmcnt(1)
	v_mov_b64_e32 v[90:91], v[202:203]
	v_mov_b64_e32 v[92:93], v[204:205]
	v_lshlrev_b32_e32 v94, 16, v90
	v_and_b32_e32 v95, 0xffff0000, v90
	v_lshlrev_b32_e32 v90, 16, v91
	v_and_b32_e32 v91, 0xffff0000, v91
	v_pk_add_f32 v[82:83], v[82:83], v[90:91]
	v_lshlrev_b32_e32 v90, 16, v92
	v_and_b32_e32 v91, 0xffff0000, v92
	v_pk_add_f32 v[76:77], v[76:77], v[90:91]
	v_lshlrev_b32_e32 v90, 16, v93
	v_and_b32_e32 v91, 0xffff0000, v93
	v_pk_add_f32 v[80:81], v[80:81], v[94:95]
	v_pk_add_f32 v[78:79], v[78:79], v[90:91]

;     __device__ __forceinline__ void operator()(const f32x4 (&acc)[2][2][4][2], const Unit& u, int wr, int wc, int fr, int fq) const {
;     ...
;                         if (g > 0) { float pv[8]; unpack8(*(const u32x4*)sp, pv);
; #pragma unroll
;                             for (int e = 0; e < 8; ++e) v[e] += pv[e]; }
.LBB0_931:
.LBB0_932:
	s_and_b64 vcc, exec, s[4:5]
	s_cbranch_vccnz .LBB0_934
	s_waitcnt vmcnt(0)
	v_mov_b64_e32 v[76:77], v[206:207]
	v_mov_b64_e32 v[78:79], v[208:209]
	v_lshlrev_b32_e32 v80, 16, v76
	v_and_b32_e32 v81, 0xffff0000, v76
	v_lshlrev_b32_e32 v76, 16, v77
	v_and_b32_e32 v77, 0xffff0000, v77
	v_pk_add_f32 v[74:75], v[74:75], v[76:77]
	v_lshlrev_b32_e32 v76, 16, v78
	v_and_b32_e32 v77, 0xffff0000, v78
	v_pk_add_f32 v[68:69], v[68:69], v[76:77]
	v_lshlrev_b32_e32 v76, 16, v79
	v_and_b32_e32 v77, 0xffff0000, v79
	v_pk_add_f32 v[72:73], v[72:73], v[80:81]
	v_pk_add_f32 v[70:71], v[70:71], v[76:77]

; __device__ __forceinline__ float sigm(float x) { return __builtin_amdgcn_rcpf(1.f + __expf(-x)); }
;     __device__ __forceinline__ void operator()(const f32x4 (&acc)[2][2][4][2], const Unit& u, int wr, int wc, int fr, int fq) const {
;     ...
;         for (int ai = 0; ai < 2; ++ai)
; #pragma unroll
;             for (int m = 0; m < 4; ++m) { const int row = row0 + ai * HALF + m * 16;
; #pragma unroll
;                 for (int bj = 0; bj < 2; ++bj) { const int col = col0 + bj * HALF;
;                     float gt[8]; unpack8(*(const u32x4*)(H + (size_t)row * NPAD + C_GATE + g * D + col), gt);
;                     float v[8];
; #pragma unroll
;                     for (int e = 0; e < 4; ++e) { v[e] = sigm(gt[e]) * acc[ai][bj][m][0][e]; v[4 + e] = sigm(gt[4 + e]) * acc[ai][bj][m][1][e]; }
;                     if (u.split) { float* cp = SCTX + ((size_t)u.slot * 512 + (row - u.pm * BM + (u.pm ? 256 : 0))) * D + col;
;                         *(f32x4*)cp = (f32x4){v[0], v[1], v[2], v[3]}; *(f32x4*)(cp + 4) = (f32x4){v[4], v[5], v[6], v[7]}; }
.LBB0_935:
	s_mov_b64 s[22:23], 0x455840
	v_lshl_add_u64 v[216:217], v[214:215], 0, s[22:23]
	global_load_dwordx4 v[164:167], v[216:217], off
	global_load_dwordx4 v[168:171], v[216:217], off offset:256
	s_mov_b64 s[22:23], 0x4df840
	v_lshl_add_u64 v[216:217], v[214:215], 0, s[22:23]
	global_load_dwordx4 v[172:175], v[216:217], off
	global_load_dwordx4 v[176:179], v[216:217], off offset:256
	s_mov_b64 s[22:23], 0x569840
	v_lshl_add_u64 v[216:217], v[214:215], 0, s[22:23]
	global_load_dwordx4 v[180:183], v[216:217], off
	global_load_dwordx4 v[184:187], v[216:217], off offset:256
	s_mov_b64 s[22:23], 0x5f3840
	v_lshl_add_u64 v[216:217], v[214:215], 0, s[22:23]
	global_load_dwordx4 v[188:191], v[216:217], off
	global_load_dwordx4 v[192:195], v[216:217], off offset:256
	v_mov_b32_e32 v212, 0x80000
	v_mov_b32_e32 v213, 0
	v_lshl_add_u64 v[212:213], v[210:211], 0, v[212:213]
	global_load_dwordx4 v[202:205], v[212:213], off
	v_mov_b32_e32 v212, 0x80000
	v_mov_b32_e32 v213, 0
	v_lshl_add_u64 v[212:213], v[210:211], 0, v[212:213]
	global_load_dwordx4 v[206:209], v[212:213], off offset:256
	v_add_u32_e32 v68, 0x80, v142
	v_mov_b64_e32 v[70:71], s[60:61]
	v_mad_i64_i32 v[70:71], s[22:23], v68, s43, v[70:71]
	v_lshl_add_u64 v[70:71], s[20:21], 1, v[70:71]
	v_lshl_add_u64 v[72:73], v[140:141], 1, v[70:71]
	v_add_co_u32_e32 v70, vcc, 0x5000, v72
	s_nop 1
	v_addc_co_u32_e32 v71, vcc, 0, v73, vcc
	s_and_b64 vcc, exec, s[6:7]
	s_waitcnt vmcnt(9)
	v_mov_b64_e32 v[74:75], v[164:165]
	v_mov_b64_e32 v[76:77], v[166:167]
	v_lshlrev_b32_e32 v69, 16, v74
	v_mul_f32_e32 v69, 0xbfb8aa3b, v69
	v_exp_f32_e32 v69, v69
	v_and_b32_e32 v71, 0xffff0000, v74
	v_lshlrev_b32_e32 v74, 16, v76
	v_lshlrev_b32_e32 v78, 16, v75
	v_add_f32_e32 v69, 1.0, v69
	v_rcp_f32_e32 v70, v69
	v_mul_f32_e32 v69, 0xbfb8aa3b, v74
	v_exp_f32_e32 v69, v69
	v_and_b32_e32 v79, 0xffff0000, v75
	v_and_b32_e32 v75, 0xffff0000, v76
	v_lshlrev_b32_e32 v76, 16, v77
	v_add_f32_e32 v69, 1.0, v69
	v_rcp_f32_e32 v74, v69
	v_mul_f32_e32 v69, 0xbfb8aa3b, v71
	v_exp_f32_e32 v69, v69
	v_and_b32_e32 v77, 0xffff0000, v77
	v_add_f32_e32 v69, 1.0, v69
	v_rcp_f32_e32 v71, v69
	v_mul_f32_e32 v69, 0xbfb8aa3b, v75
	v_exp_f32_e32 v69, v69
	v_pk_mul_f32 v[64:65], v[64:65], v[70:71]
	v_add_f32_e32 v69, 1.0, v69
	v_rcp_f32_e32 v75, v69
	v_mul_f32_e32 v69, 0xbfb8aa3b, v78
	v_exp_f32_e32 v69, v69
	v_pk_mul_f32 v[60:61], v[60:61], v[74:75]
	v_add_f32_e32 v69, 1.0, v69
	v_rcp_f32_e32 v70, v69
	v_mul_f32_e32 v69, 0xbfb8aa3b, v76
	v_exp_f32_e32 v69, v69
	s_nop 0
	v_add_f32_e32 v69, 1.0, v69
	v_rcp_f32_e32 v74, v69
	v_mul_f32_e32 v69, 0xbfb8aa3b, v79
	v_exp_f32_e32 v69, v69
	s_nop 0
	v_add_f32_e32 v69, 1.0, v69
	v_rcp_f32_e32 v71, v69
	v_mul_f32_e32 v69, 0xbfb8aa3b, v77
	v_exp_f32_e32 v69, v69
	v_pk_mul_f32 v[66:67], v[66:67], v[70:71]
	v_add_f32_e32 v69, 1.0, v69
	v_rcp_f32_e32 v75, v69
	s_nop 0
	v_pk_mul_f32 v[62:63], v[62:63], v[74:75]
	s_cbranch_vccnz .LBB0_937
	s_ashr_i32 s9, s8, 31
	s_cmp_eq_u32 s48, 0
	s_cselect_b32 s13, 0, 0x100
	s_sub_i32 s13, s13, s11
	v_add_u32_e32 v70, s13, v68
	s_lshl_b64 s[22:23], s[8:9], 22
	v_ashrrev_i32_e32 v71, 31, v70
	s_add_u32 s22, s28, s22
	s_addc_u32 s23, s29, s23
	v_lshlrev_b64 v[70:71], 13, v[70:71]
	v_lshl_add_u64 v[70:71], s[22:23], 0, v[70:71]
	v_lshl_add_u64 v[70:71], v[140:141], 2, v[70:71]
	s_mov_b64 s[22:23], 0
	global_store_dwordx4 v[70:71], v[64:67], off
	global_store_dwordx4 v[70:71], v[60:63], off offset:16
	s_branch .LBB0_938

;     __device__ __forceinline__ void operator()(const f32x4 (&acc)[2][2][4][2], const Unit& u, int wr, int wc, int fr, int fq) const {
;     ...
;                         if (g > 0) { float pv[8]; unpack8(*(const u32x4*)sp, pv);
; #pragma unroll
;                             for (int e = 0; e < 8; ++e) v[e] += pv[e]; }
.LBB0_938:
	v_ashrrev_i32_e32 v69, 31, v68
	v_lshlrev_b64 v[70:71], 12, v[68:69]
	v_lshl_add_u64 v[70:71], s[38:39], 0, v[70:71]
	s_andn2_b64 vcc, exec, s[22:23]
	v_lshl_add_u64 v[70:71], v[140:141], 1, v[70:71]
	s_cbranch_vccnz .LBB0_942
	s_and_b64 vcc, exec, s[4:5]
	s_cbranch_vccnz .LBB0_941
	s_waitcnt vmcnt(1)
	v_mov_b64_e32 v[74:75], v[202:203]
	v_mov_b64_e32 v[76:77], v[204:205]
	v_lshlrev_b32_e32 v78, 16, v74
	v_and_b32_e32 v79, 0xffff0000, v74
	v_lshlrev_b32_e32 v74, 16, v75
	v_and_b32_e32 v75, 0xffff0000, v75
	v_pk_add_f32 v[66:67], v[66:67], v[74:75]
	v_lshlrev_b32_e32 v74, 16, v76
	v_and_b32_e32 v75, 0xffff0000, v76
	v_pk_add_f32 v[60:61], v[60:61], v[74:75]
	v_lshlrev_b32_e32 v74, 16, v77
	v_and_b32_e32 v75, 0xffff0000, v77
	v_pk_add_f32 v[64:65], v[64:65], v[78:79]
	v_pk_add_f32 v[62:63], v[62:63], v[74:75]

; __device__ __forceinline__ float sigm(float x) { return __builtin_amdgcn_rcpf(1.f + __expf(-x)); }
;     __device__ __forceinline__ void operator()(const f32x4 (&acc)[2][2][4][2], const Unit& u, int wr, int wc, int fr, int fq) const {
;     ...
;                     float gt[8]; unpack8(*(const u32x4*)(H + (size_t)row * NPAD + C_GATE + g * D + col), gt);
;                     float v[8];
; #pragma unroll
;                     for (int e = 0; e < 4; ++e) { v[e] = sigm(gt[e]) * acc[ai][bj][m][0][e]; v[4 + e] = sigm(gt[4 + e]) * acc[ai][bj][m][1][e]; }
;                     if (u.split) { float* cp = SCTX + ((size_t)u.slot * 512 + (row - u.pm * BM + (u.pm ? 256 : 0))) * D + col;
;                         *(f32x4*)cp = (f32x4){v[0], v[1], v[2], v[3]}; *(f32x4*)(cp + 4) = (f32x4){v[4], v[5], v[6], v[7]}; }
;                     else {
;                         bf16_t* sp = SB + (size_t)row * D + col;
;                         if (g > 0) { float pv[8]; unpack8(*(const u32x4*)sp, pv);
; #pragma unroll
;                             for (int e = 0; e < 8; ++e) v[e] += pv[e]; }
.LBB0_942:
	s_mov_b64 s[22:23], 0x5840
	v_lshl_add_u64 v[60:61], v[72:73], 0, s[22:23]
	s_and_b64 vcc, exec, s[6:7]
	v_mov_b32_e32 v212, 0x90000
	v_mov_b32_e32 v213, 0
	v_lshl_add_u64 v[212:213], v[210:211], 0, v[212:213]
	global_load_dwordx4 v[202:205], v[212:213], off
	s_waitcnt vmcnt(9)
	v_mov_b64_e32 v[60:61], v[168:169]
	v_mov_b64_e32 v[62:63], v[170:171]
	v_lshlrev_b32_e32 v66, 16, v61
	v_and_b32_e32 v67, 0xffff0000, v61
	v_lshlrev_b32_e32 v61, 16, v62
	v_mul_f32_e32 v61, 0xbfb8aa3b, v61
	v_exp_f32_e32 v61, v61
	v_lshlrev_b32_e32 v64, 16, v60
	v_and_b32_e32 v65, 0xffff0000, v60
	v_and_b32_e32 v69, 0xffff0000, v62
	v_add_f32_e32 v61, 1.0, v61
	v_mul_f32_e32 v60, 0xbfb8aa3b, v64
	v_rcp_f32_e32 v62, v61
	v_mul_f32_e32 v61, 0xbfb8aa3b, v65
	v_exp_f32_e32 v60, v60
	v_exp_f32_e32 v61, v61
	v_lshlrev_b32_e32 v72, 16, v63
	v_and_b32_e32 v73, 0xffff0000, v63
	v_add_f32_e32 v60, 1.0, v60
	v_add_f32_e32 v61, 1.0, v61
	v_rcp_f32_e32 v60, v60
	v_rcp_f32_e32 v61, v61
	s_nop 0
	v_pk_mul_f32 v[56:57], v[56:57], v[60:61]
	v_mul_f32_e32 v60, 0xbfb8aa3b, v69
	v_exp_f32_e32 v60, v60
	v_mul_f32_e32 v61, 0xbfb8aa3b, v72
	v_exp_f32_e32 v61, v61
	v_add_f32_e32 v60, 1.0, v60
	v_rcp_f32_e32 v63, v60
	v_add_f32_e32 v61, 1.0, v61
	v_mul_f32_e32 v60, 0xbfb8aa3b, v66
	v_exp_f32_e32 v60, v60
	v_pk_mul_f32 v[52:53], v[52:53], v[62:63]
	v_rcp_f32_e32 v62, v61
	v_mul_f32_e32 v61, 0xbfb8aa3b, v67
	v_exp_f32_e32 v61, v61
	v_add_f32_e32 v60, 1.0, v60
	v_rcp_f32_e32 v60, v60
	v_add_f32_e32 v61, 1.0, v61
	v_rcp_f32_e32 v61, v61
	s_nop 0
	v_pk_mul_f32 v[58:59], v[58:59], v[60:61]
	v_mul_f32_e32 v60, 0xbfb8aa3b, v73
	v_exp_f32_e32 v60, v60
	s_nop 0
	v_add_f32_e32 v60, 1.0, v60
	v_rcp_f32_e32 v63, v60
	s_nop 0
	v_pk_mul_f32 v[54:55], v[54:55], v[62:63]
	s_cbranch_vccnz .LBB0_944
	s_ashr_i32 s9, s8, 31
	s_cmp_eq_u32 s48, 0
	s_cselect_b32 s13, 0, 0x100
	s_sub_i32 s13, s13, s11
	v_add_u32_e32 v60, s13, v68
	s_lshl_b64 s[22:23], s[8:9], 22
	v_ashrrev_i32_e32 v61, 31, v60
	s_add_u32 s22, s28, s22
	s_addc_u32 s23, s29, s23
	v_lshlrev_b64 v[60:61], 13, v[60:61]
	v_lshl_add_u64 v[60:61], s[22:23], 0, v[60:61]
	v_lshl_add_u64 v[60:61], v[140:141], 2, v[60:61]
	global_store_dwordx4 v[60:61], v[56:59], off offset:512
	global_store_dwordx4 v[60:61], v[52:55], off offset:528
	s_cbranch_execz .LBB0_945
	s_branch .LBB0_948
.LBB0_944:
.LBB0_945:
	s_and_b64 vcc, exec, s[4:5]
	s_cbranch_vccnz .LBB0_947
	s_waitcnt vmcnt(1)
	v_mov_b64_e32 v[60:61], v[206:207]
	v_mov_b64_e32 v[62:63], v[208:209]
	v_lshlrev_b32_e32 v64, 16, v60
	v_and_b32_e32 v65, 0xffff0000, v60
	v_lshlrev_b32_e32 v60, 16, v61
	v_and_b32_e32 v61, 0xffff0000, v61
	v_pk_add_f32 v[58:59], v[58:59], v[60:61]
	v_lshlrev_b32_e32 v60, 16, v62
	v_and_b32_e32 v61, 0xffff0000, v62
	v_pk_add_f32 v[52:53], v[52:53], v[60:61]
	v_lshlrev_b32_e32 v60, 16, v63
	v_and_b32_e32 v61, 0xffff0000, v63
	v_pk_add_f32 v[56:57], v[56:57], v[64:65]
	v_pk_add_f32 v[54:55], v[54:55], v[60:61]

; __device__ __forceinline__ float sigm(float x) { return __builtin_amdgcn_rcpf(1.f + __expf(-x)); }
;     __device__ __forceinline__ void operator()(const f32x4 (&acc)[2][2][4][2], const Unit& u, int wr, int wc, int fr, int fq) const {
;     ...
;             for (int m = 0; m < 4; ++m) { const int row = row0 + ai * HALF + m * 16;
; #pragma unroll
;                 for (int bj = 0; bj < 2; ++bj) { const int col = col0 + bj * HALF;
;                     float gt[8]; unpack8(*(const u32x4*)(H + (size_t)row * NPAD + C_GATE + g * D + col), gt);
;                     float v[8];
; #pragma unroll
;                     for (int e = 0; e < 4; ++e) { v[e] = sigm(gt[e]) * acc[ai][bj][m][0][e]; v[4 + e] = sigm(gt[4 + e]) * acc[ai][bj][m][1][e]; }
;                     if (u.split) { float* cp = SCTX + ((size_t)u.slot * 512 + (row - u.pm * BM + (u.pm ? 256 : 0))) * D + col;
;                         *(f32x4*)cp = (f32x4){v[0], v[1], v[2], v[3]}; *(f32x4*)(cp + 4) = (f32x4){v[4], v[5], v[6], v[7]}; }
.LBB0_948:
	v_add_u32_e32 v52, 0x90, v142
	v_mov_b64_e32 v[54:55], s[60:61]
	v_mad_i64_i32 v[54:55], s[22:23], v52, s43, v[54:55]
	v_lshl_add_u64 v[54:55], s[20:21], 1, v[54:55]
	v_lshl_add_u64 v[56:57], v[140:141], 1, v[54:55]
	v_add_co_u32_e32 v54, vcc, 0x5000, v56
	s_nop 1
	v_addc_co_u32_e32 v55, vcc, 0, v57, vcc
	s_and_b64 vcc, exec, s[6:7]
	v_mov_b32_e32 v212, 0x90000
	v_mov_b32_e32 v213, 0
	v_lshl_add_u64 v[212:213], v[210:211], 0, v[212:213]
	global_load_dwordx4 v[206:209], v[212:213], off offset:256
	s_waitcnt vmcnt(9)
	v_mov_b64_e32 v[58:59], v[172:173]
	v_mov_b64_e32 v[60:61], v[174:175]
	v_lshlrev_b32_e32 v53, 16, v58
	v_mul_f32_e32 v53, 0xbfb8aa3b, v53
	v_exp_f32_e32 v53, v53
	v_and_b32_e32 v55, 0xffff0000, v58
	v_lshlrev_b32_e32 v58, 16, v60
	v_lshlrev_b32_e32 v62, 16, v59
	v_add_f32_e32 v53, 1.0, v53
	v_rcp_f32_e32 v54, v53
	v_mul_f32_e32 v53, 0xbfb8aa3b, v58
	v_exp_f32_e32 v53, v53
	v_and_b32_e32 v63, 0xffff0000, v59
	v_and_b32_e32 v59, 0xffff0000, v60
	v_lshlrev_b32_e32 v60, 16, v61
	v_add_f32_e32 v53, 1.0, v53
	v_rcp_f32_e32 v58, v53
	v_mul_f32_e32 v53, 0xbfb8aa3b, v55
	v_exp_f32_e32 v53, v53
	v_and_b32_e32 v61, 0xffff0000, v61
	v_add_f32_e32 v53, 1.0, v53
	v_rcp_f32_e32 v55, v53
	v_mul_f32_e32 v53, 0xbfb8aa3b, v59
	v_exp_f32_e32 v53, v53
	v_pk_mul_f32 v[48:49], v[48:49], v[54:55]
	v_add_f32_e32 v53, 1.0, v53
	v_rcp_f32_e32 v59, v53
	v_mul_f32_e32 v53, 0xbfb8aa3b, v62
	v_exp_f32_e32 v53, v53
	v_pk_mul_f32 v[44:45], v[44:45], v[58:59]
	v_add_f32_e32 v53, 1.0, v53
	v_rcp_f32_e32 v54, v53
	v_mul_f32_e32 v53, 0xbfb8aa3b, v60
	v_exp_f32_e32 v53, v53
	s_nop 0
	v_add_f32_e32 v53, 1.0, v53
	v_rcp_f32_e32 v58, v53
	v_mul_f32_e32 v53, 0xbfb8aa3b, v63
	v_exp_f32_e32 v53, v53
	s_nop 0
	v_add_f32_e32 v53, 1.0, v53
	v_rcp_f32_e32 v55, v53
	v_mul_f32_e32 v53, 0xbfb8aa3b, v61
	v_exp_f32_e32 v53, v53
	v_pk_mul_f32 v[50:51], v[50:51], v[54:55]
	v_add_f32_e32 v53, 1.0, v53
	v_rcp_f32_e32 v59, v53
	s_nop 0
	v_pk_mul_f32 v[46:47], v[46:47], v[58:59]
	s_cbranch_vccnz .LBB0_950
	s_ashr_i32 s9, s8, 31
	s_cmp_eq_u32 s48, 0
	s_cselect_b32 s13, 0, 0x100
	s_sub_i32 s13, s13, s11
	v_add_u32_e32 v54, s13, v52
	s_lshl_b64 s[22:23], s[8:9], 22
	v_ashrrev_i32_e32 v55, 31, v54
	s_add_u32 s22, s28, s22
	s_addc_u32 s23, s29, s23
	v_lshlrev_b64 v[54:55], 13, v[54:55]
	v_lshl_add_u64 v[54:55], s[22:23], 0, v[54:55]
	v_lshl_add_u64 v[54:55], v[140:141], 2, v[54:55]
	s_mov_b64 s[22:23], 0
	global_store_dwordx4 v[54:55], v[48:51], off
	global_store_dwordx4 v[54:55], v[44:47], off offset:16
	s_branch .LBB0_951

;     __device__ __forceinline__ void operator()(const f32x4 (&acc)[2][2][4][2], const Unit& u, int wr, int wc, int fr, int fq) const {
;     ...
;                         if (g > 0) { float pv[8]; unpack8(*(const u32x4*)sp, pv);
; #pragma unroll
;                             for (int e = 0; e < 8; ++e) v[e] += pv[e]; }
.LBB0_951:
	v_ashrrev_i32_e32 v53, 31, v52
	v_lshlrev_b64 v[54:55], 12, v[52:53]
	v_lshl_add_u64 v[54:55], s[38:39], 0, v[54:55]
	s_andn2_b64 vcc, exec, s[22:23]
	v_lshl_add_u64 v[54:55], v[140:141], 1, v[54:55]
	s_cbranch_vccnz .LBB0_955
	s_and_b64 vcc, exec, s[4:5]
	s_cbranch_vccnz .LBB0_954
	s_waitcnt vmcnt(1)
	v_mov_b64_e32 v[58:59], v[202:203]
	v_mov_b64_e32 v[60:61], v[204:205]
	v_lshlrev_b32_e32 v62, 16, v58
	v_and_b32_e32 v63, 0xffff0000, v58
	v_lshlrev_b32_e32 v58, 16, v59
	v_and_b32_e32 v59, 0xffff0000, v59
	v_pk_add_f32 v[50:51], v[50:51], v[58:59]
	v_lshlrev_b32_e32 v58, 16, v60
	v_and_b32_e32 v59, 0xffff0000, v60
	v_pk_add_f32 v[44:45], v[44:45], v[58:59]
	v_lshlrev_b32_e32 v58, 16, v61
	v_and_b32_e32 v59, 0xffff0000, v61
	v_pk_add_f32 v[48:49], v[48:49], v[62:63]
	v_pk_add_f32 v[46:47], v[46:47], v[58:59]

; __device__ __forceinline__ float sigm(float x) { return __builtin_amdgcn_rcpf(1.f + __expf(-x)); }
;     __device__ __forceinline__ void operator()(const f32x4 (&acc)[2][2][4][2], const Unit& u, int wr, int wc, int fr, int fq) const {
;     ...
;                     float gt[8]; unpack8(*(const u32x4*)(H + (size_t)row * NPAD + C_GATE + g * D + col), gt);
;                     float v[8];
; #pragma unroll
;                     for (int e = 0; e < 4; ++e) { v[e] = sigm(gt[e]) * acc[ai][bj][m][0][e]; v[4 + e] = sigm(gt[4 + e]) * acc[ai][bj][m][1][e]; }
;                     if (u.split) { float* cp = SCTX + ((size_t)u.slot * 512 + (row - u.pm * BM + (u.pm ? 256 : 0))) * D + col;
;                         *(f32x4*)cp = (f32x4){v[0], v[1], v[2], v[3]}; *(f32x4*)(cp + 4) = (f32x4){v[4], v[5], v[6], v[7]}; }
;                     else {
;                         bf16_t* sp = SB + (size_t)row * D + col;
;                         if (g > 0) { float pv[8]; unpack8(*(const u32x4*)sp, pv);
; #pragma unroll
;                             for (int e = 0; e < 8; ++e) v[e] += pv[e]; }
.LBB0_955:
	s_mov_b64 s[22:23], 0x5840
	v_lshl_add_u64 v[44:45], v[56:57], 0, s[22:23]
	s_and_b64 vcc, exec, s[6:7]
	v_mov_b32_e32 v212, 0xa0000
	v_mov_b32_e32 v213, 0
	v_lshl_add_u64 v[212:213], v[210:211], 0, v[212:213]
	global_load_dwordx4 v[202:205], v[212:213], off
	s_waitcnt vmcnt(9)
	v_mov_b64_e32 v[44:45], v[176:177]
	v_mov_b64_e32 v[46:47], v[178:179]
	v_lshlrev_b32_e32 v50, 16, v45
	v_and_b32_e32 v51, 0xffff0000, v45
	v_lshlrev_b32_e32 v45, 16, v46
	v_mul_f32_e32 v45, 0xbfb8aa3b, v45
	v_exp_f32_e32 v45, v45
	v_lshlrev_b32_e32 v48, 16, v44
	v_and_b32_e32 v49, 0xffff0000, v44
	v_and_b32_e32 v53, 0xffff0000, v46
	v_add_f32_e32 v45, 1.0, v45
	v_mul_f32_e32 v44, 0xbfb8aa3b, v48
	v_rcp_f32_e32 v46, v45
	v_mul_f32_e32 v45, 0xbfb8aa3b, v49
	v_exp_f32_e32 v44, v44
	v_exp_f32_e32 v45, v45
	v_lshlrev_b32_e32 v56, 16, v47
	v_and_b32_e32 v57, 0xffff0000, v47
	v_add_f32_e32 v44, 1.0, v44
	v_add_f32_e32 v45, 1.0, v45
	v_rcp_f32_e32 v44, v44
	v_rcp_f32_e32 v45, v45
	s_nop 0
	v_pk_mul_f32 v[40:41], v[40:41], v[44:45]
	v_mul_f32_e32 v44, 0xbfb8aa3b, v53
	v_exp_f32_e32 v44, v44
	v_mul_f32_e32 v45, 0xbfb8aa3b, v56
	v_exp_f32_e32 v45, v45
	v_add_f32_e32 v44, 1.0, v44
	v_rcp_f32_e32 v47, v44
	v_add_f32_e32 v45, 1.0, v45
	v_mul_f32_e32 v44, 0xbfb8aa3b, v50
	v_exp_f32_e32 v44, v44
	v_pk_mul_f32 v[36:37], v[36:37], v[46:47]
	v_rcp_f32_e32 v46, v45
	v_mul_f32_e32 v45, 0xbfb8aa3b, v51
	v_exp_f32_e32 v45, v45
	v_add_f32_e32 v44, 1.0, v44
	v_rcp_f32_e32 v44, v44
	v_add_f32_e32 v45, 1.0, v45
	v_rcp_f32_e32 v45, v45
	s_nop 0
	v_pk_mul_f32 v[42:43], v[42:43], v[44:45]
	v_mul_f32_e32 v44, 0xbfb8aa3b, v57
	v_exp_f32_e32 v44, v44
	s_nop 0
	v_add_f32_e32 v44, 1.0, v44
	v_rcp_f32_e32 v47, v44
	s_nop 0
	v_pk_mul_f32 v[38:39], v[38:39], v[46:47]
	s_cbranch_vccnz .LBB0_957
	s_ashr_i32 s9, s8, 31
	s_cmp_eq_u32 s48, 0
	s_cselect_b32 s13, 0, 0x100
	s_sub_i32 s13, s13, s11
	v_add_u32_e32 v44, s13, v52
	s_lshl_b64 s[22:23], s[8:9], 22
	v_ashrrev_i32_e32 v45, 31, v44
	s_add_u32 s22, s28, s22
	s_addc_u32 s23, s29, s23
	v_lshlrev_b64 v[44:45], 13, v[44:45]
	v_lshl_add_u64 v[44:45], s[22:23], 0, v[44:45]
	v_lshl_add_u64 v[44:45], v[140:141], 2, v[44:45]
	global_store_dwordx4 v[44:45], v[40:43], off offset:512
	global_store_dwordx4 v[44:45], v[36:39], off offset:528
	s_cbranch_execz .LBB0_958
	s_branch .LBB0_961
.LBB0_957:
.LBB0_958:
	s_and_b64 vcc, exec, s[4:5]
	s_cbranch_vccnz .LBB0_960
	s_waitcnt vmcnt(1)
	v_mov_b64_e32 v[44:45], v[206:207]
	v_mov_b64_e32 v[46:47], v[208:209]
	v_lshlrev_b32_e32 v48, 16, v44
	v_and_b32_e32 v49, 0xffff0000, v44
	v_lshlrev_b32_e32 v44, 16, v45
	v_and_b32_e32 v45, 0xffff0000, v45
	v_pk_add_f32 v[42:43], v[42:43], v[44:45]
	v_lshlrev_b32_e32 v44, 16, v46
	v_and_b32_e32 v45, 0xffff0000, v46
	v_pk_add_f32 v[36:37], v[36:37], v[44:45]
	v_lshlrev_b32_e32 v44, 16, v47
	v_and_b32_e32 v45, 0xffff0000, v47
	v_pk_add_f32 v[40:41], v[40:41], v[48:49]
	v_pk_add_f32 v[38:39], v[38:39], v[44:45]

; __device__ __forceinline__ float sigm(float x) { return __builtin_amdgcn_rcpf(1.f + __expf(-x)); }
;     __device__ __forceinline__ void operator()(const f32x4 (&acc)[2][2][4][2], const Unit& u, int wr, int wc, int fr, int fq) const {
;     ...
;             for (int m = 0; m < 4; ++m) { const int row = row0 + ai * HALF + m * 16;
; #pragma unroll
;                 for (int bj = 0; bj < 2; ++bj) { const int col = col0 + bj * HALF;
;                     float gt[8]; unpack8(*(const u32x4*)(H + (size_t)row * NPAD + C_GATE + g * D + col), gt);
;                     float v[8];
; #pragma unroll
;                     for (int e = 0; e < 4; ++e) { v[e] = sigm(gt[e]) * acc[ai][bj][m][0][e]; v[4 + e] = sigm(gt[4 + e]) * acc[ai][bj][m][1][e]; }
;                     if (u.split) { float* cp = SCTX + ((size_t)u.slot * 512 + (row - u.pm * BM + (u.pm ? 256 : 0))) * D + col;
;                         *(f32x4*)cp = (f32x4){v[0], v[1], v[2], v[3]}; *(f32x4*)(cp + 4) = (f32x4){v[4], v[5], v[6], v[7]}; }
.LBB0_961:
	v_add_u32_e32 v36, 0xa0, v142
	v_mov_b64_e32 v[38:39], s[60:61]
	v_mad_i64_i32 v[38:39], s[22:23], v36, s43, v[38:39]
	v_lshl_add_u64 v[38:39], s[20:21], 1, v[38:39]
	v_lshl_add_u64 v[40:41], v[140:141], 1, v[38:39]
	v_add_co_u32_e32 v38, vcc, 0x5000, v40
	s_nop 1
	v_addc_co_u32_e32 v39, vcc, 0, v41, vcc
	s_and_b64 vcc, exec, s[6:7]
	v_mov_b32_e32 v212, 0xa0000
	v_mov_b32_e32 v213, 0
	v_lshl_add_u64 v[212:213], v[210:211], 0, v[212:213]
	global_load_dwordx4 v[206:209], v[212:213], off offset:256
	s_waitcnt vmcnt(9)
	v_mov_b64_e32 v[42:43], v[180:181]
	v_mov_b64_e32 v[44:45], v[182:183]
	v_lshlrev_b32_e32 v37, 16, v42
	v_mul_f32_e32 v37, 0xbfb8aa3b, v37
	v_exp_f32_e32 v37, v37
	v_and_b32_e32 v39, 0xffff0000, v42
	v_lshlrev_b32_e32 v42, 16, v44
	v_lshlrev_b32_e32 v46, 16, v43
	v_add_f32_e32 v37, 1.0, v37
	v_rcp_f32_e32 v38, v37
	v_mul_f32_e32 v37, 0xbfb8aa3b, v42
	v_exp_f32_e32 v37, v37
	v_and_b32_e32 v47, 0xffff0000, v43
	v_and_b32_e32 v43, 0xffff0000, v44
	v_lshlrev_b32_e32 v44, 16, v45
	v_add_f32_e32 v37, 1.0, v37
	v_rcp_f32_e32 v42, v37
	v_mul_f32_e32 v37, 0xbfb8aa3b, v39
	v_exp_f32_e32 v37, v37
	v_and_b32_e32 v45, 0xffff0000, v45
	v_add_f32_e32 v37, 1.0, v37
	v_rcp_f32_e32 v39, v37
	v_mul_f32_e32 v37, 0xbfb8aa3b, v43
	v_exp_f32_e32 v37, v37
	v_pk_mul_f32 v[32:33], v[32:33], v[38:39]
	v_add_f32_e32 v37, 1.0, v37
	v_rcp_f32_e32 v43, v37
	v_mul_f32_e32 v37, 0xbfb8aa3b, v46
	v_exp_f32_e32 v37, v37
	v_pk_mul_f32 v[28:29], v[28:29], v[42:43]
	v_add_f32_e32 v37, 1.0, v37
	v_rcp_f32_e32 v38, v37
	v_mul_f32_e32 v37, 0xbfb8aa3b, v44
	v_exp_f32_e32 v37, v37
	s_nop 0
	v_add_f32_e32 v37, 1.0, v37
	v_rcp_f32_e32 v42, v37
	v_mul_f32_e32 v37, 0xbfb8aa3b, v47
	v_exp_f32_e32 v37, v37
	s_nop 0
	v_add_f32_e32 v37, 1.0, v37
	v_rcp_f32_e32 v39, v37
	v_mul_f32_e32 v37, 0xbfb8aa3b, v45
	v_exp_f32_e32 v37, v37
	v_pk_mul_f32 v[34:35], v[34:35], v[38:39]
	v_add_f32_e32 v37, 1.0, v37
	v_rcp_f32_e32 v43, v37
	s_nop 0
	v_pk_mul_f32 v[30:31], v[30:31], v[42:43]
	s_cbranch_vccnz .LBB0_963
	s_ashr_i32 s9, s8, 31
	s_cmp_eq_u32 s48, 0
	s_cselect_b32 s13, 0, 0x100
	s_sub_i32 s13, s13, s11
	v_add_u32_e32 v38, s13, v36
	s_lshl_b64 s[22:23], s[8:9], 22
	v_ashrrev_i32_e32 v39, 31, v38
	s_add_u32 s22, s28, s22
	s_addc_u32 s23, s29, s23
	v_lshlrev_b64 v[38:39], 13, v[38:39]
	v_lshl_add_u64 v[38:39], s[22:23], 0, v[38:39]
	v_lshl_add_u64 v[38:39], v[140:141], 2, v[38:39]
	s_mov_b64 s[22:23], 0
	global_store_dwordx4 v[38:39], v[32:35], off
	global_store_dwordx4 v[38:39], v[28:31], off offset:16
	s_branch .LBB0_964

;     __device__ __forceinline__ void operator()(const f32x4 (&acc)[2][2][4][2], const Unit& u, int wr, int wc, int fr, int fq) const {
;     ...
;                         if (g > 0) { float pv[8]; unpack8(*(const u32x4*)sp, pv);
; #pragma unroll
;                             for (int e = 0; e < 8; ++e) v[e] += pv[e]; }
.LBB0_964:
	v_ashrrev_i32_e32 v37, 31, v36
	v_lshlrev_b64 v[38:39], 12, v[36:37]
	v_lshl_add_u64 v[38:39], s[38:39], 0, v[38:39]
	s_andn2_b64 vcc, exec, s[22:23]
	v_lshl_add_u64 v[38:39], v[140:141], 1, v[38:39]
	s_cbranch_vccnz .LBB0_968
	s_and_b64 vcc, exec, s[4:5]
	s_cbranch_vccnz .LBB0_967
	s_waitcnt vmcnt(1)
	v_mov_b64_e32 v[42:43], v[202:203]
	v_mov_b64_e32 v[44:45], v[204:205]
	v_lshlrev_b32_e32 v46, 16, v42
	v_and_b32_e32 v47, 0xffff0000, v42
	v_lshlrev_b32_e32 v42, 16, v43
	v_and_b32_e32 v43, 0xffff0000, v43
	v_pk_add_f32 v[34:35], v[34:35], v[42:43]
	v_lshlrev_b32_e32 v42, 16, v44
	v_and_b32_e32 v43, 0xffff0000, v44
	v_pk_add_f32 v[28:29], v[28:29], v[42:43]
	v_lshlrev_b32_e32 v42, 16, v45
	v_and_b32_e32 v43, 0xffff0000, v45
	v_pk_add_f32 v[32:33], v[32:33], v[46:47]
	v_pk_add_f32 v[30:31], v[30:31], v[42:43]

; __device__ __forceinline__ float sigm(float x) { return __builtin_amdgcn_rcpf(1.f + __expf(-x)); }
;     __device__ __forceinline__ void operator()(const f32x4 (&acc)[2][2][4][2], const Unit& u, int wr, int wc, int fr, int fq) const {
;     ...
;                     float gt[8]; unpack8(*(const u32x4*)(H + (size_t)row * NPAD + C_GATE + g * D + col), gt);
;                     float v[8];
; #pragma unroll
;                     for (int e = 0; e < 4; ++e) { v[e] = sigm(gt[e]) * acc[ai][bj][m][0][e]; v[4 + e] = sigm(gt[4 + e]) * acc[ai][bj][m][1][e]; }
;                     if (u.split) { float* cp = SCTX + ((size_t)u.slot * 512 + (row - u.pm * BM + (u.pm ? 256 : 0))) * D + col;
;                         *(f32x4*)cp = (f32x4){v[0], v[1], v[2], v[3]}; *(f32x4*)(cp + 4) = (f32x4){v[4], v[5], v[6], v[7]}; }
;                     else {
;                         bf16_t* sp = SB + (size_t)row * D + col;
;                         if (g > 0) { float pv[8]; unpack8(*(const u32x4*)sp, pv);
; #pragma unroll
;                             for (int e = 0; e < 8; ++e) v[e] += pv[e]; }
.LBB0_968:
	s_mov_b64 s[22:23], 0x5840
	v_lshl_add_u64 v[28:29], v[40:41], 0, s[22:23]
	s_and_b64 vcc, exec, s[6:7]
	v_mov_b32_e32 v212, 0xb0000
	v_mov_b32_e32 v213, 0
	v_lshl_add_u64 v[212:213], v[210:211], 0, v[212:213]
	global_load_dwordx4 v[202:205], v[212:213], off
	s_waitcnt vmcnt(9)
	v_mov_b64_e32 v[28:29], v[184:185]
	v_mov_b64_e32 v[30:31], v[186:187]
	v_lshlrev_b32_e32 v34, 16, v29
	v_and_b32_e32 v35, 0xffff0000, v29
	v_lshlrev_b32_e32 v29, 16, v30
	v_mul_f32_e32 v29, 0xbfb8aa3b, v29
	v_exp_f32_e32 v29, v29
	v_lshlrev_b32_e32 v32, 16, v28
	v_and_b32_e32 v33, 0xffff0000, v28
	v_and_b32_e32 v37, 0xffff0000, v30
	v_add_f32_e32 v29, 1.0, v29
	v_mul_f32_e32 v28, 0xbfb8aa3b, v32
	v_rcp_f32_e32 v30, v29
	v_mul_f32_e32 v29, 0xbfb8aa3b, v33
	v_exp_f32_e32 v28, v28
	v_exp_f32_e32 v29, v29
	v_lshlrev_b32_e32 v40, 16, v31
	v_and_b32_e32 v41, 0xffff0000, v31
	v_add_f32_e32 v28, 1.0, v28
	v_add_f32_e32 v29, 1.0, v29
	v_rcp_f32_e32 v28, v28
	v_rcp_f32_e32 v29, v29
	s_nop 0
	v_pk_mul_f32 v[24:25], v[24:25], v[28:29]
	v_mul_f32_e32 v28, 0xbfb8aa3b, v37
	v_exp_f32_e32 v28, v28
	v_mul_f32_e32 v29, 0xbfb8aa3b, v40
	v_exp_f32_e32 v29, v29
	v_add_f32_e32 v28, 1.0, v28
	v_rcp_f32_e32 v31, v28
	v_add_f32_e32 v29, 1.0, v29
	v_mul_f32_e32 v28, 0xbfb8aa3b, v34
	v_exp_f32_e32 v28, v28
	v_pk_mul_f32 v[20:21], v[20:21], v[30:31]
	v_rcp_f32_e32 v30, v29
	v_mul_f32_e32 v29, 0xbfb8aa3b, v35
	v_exp_f32_e32 v29, v29
	v_add_f32_e32 v28, 1.0, v28
	v_rcp_f32_e32 v28, v28
	v_add_f32_e32 v29, 1.0, v29
	v_rcp_f32_e32 v29, v29
	s_nop 0
	v_pk_mul_f32 v[26:27], v[26:27], v[28:29]
	v_mul_f32_e32 v28, 0xbfb8aa3b, v41
	v_exp_f32_e32 v28, v28
	s_nop 0
	v_add_f32_e32 v28, 1.0, v28
	v_rcp_f32_e32 v31, v28
	s_nop 0
	v_pk_mul_f32 v[22:23], v[22:23], v[30:31]
	s_cbranch_vccnz .LBB0_970
	s_ashr_i32 s9, s8, 31
	s_cmp_eq_u32 s48, 0
	s_cselect_b32 s13, 0, 0x100
	s_sub_i32 s13, s13, s11
	v_add_u32_e32 v28, s13, v36
	s_lshl_b64 s[22:23], s[8:9], 22
	v_ashrrev_i32_e32 v29, 31, v28
	s_add_u32 s22, s28, s22
	s_addc_u32 s23, s29, s23
	v_lshlrev_b64 v[28:29], 13, v[28:29]
	v_lshl_add_u64 v[28:29], s[22:23], 0, v[28:29]
	v_lshl_add_u64 v[28:29], v[140:141], 2, v[28:29]
	global_store_dwordx4 v[28:29], v[24:27], off offset:512
	global_store_dwordx4 v[28:29], v[20:23], off offset:528
	s_cbranch_execz .LBB0_971
	s_branch .LBB0_974
.LBB0_970:
.LBB0_971:
	s_and_b64 vcc, exec, s[4:5]
	s_cbranch_vccnz .LBB0_973
	s_waitcnt vmcnt(1)
	v_mov_b64_e32 v[28:29], v[206:207]
	v_mov_b64_e32 v[30:31], v[208:209]
	v_lshlrev_b32_e32 v32, 16, v28
	v_and_b32_e32 v33, 0xffff0000, v28
	v_lshlrev_b32_e32 v28, 16, v29
	v_and_b32_e32 v29, 0xffff0000, v29
	v_pk_add_f32 v[26:27], v[26:27], v[28:29]
	v_lshlrev_b32_e32 v28, 16, v30
	v_and_b32_e32 v29, 0xffff0000, v30
	v_pk_add_f32 v[20:21], v[20:21], v[28:29]
	v_lshlrev_b32_e32 v28, 16, v31
	v_and_b32_e32 v29, 0xffff0000, v31
	v_pk_add_f32 v[24:25], v[24:25], v[32:33]
	v_pk_add_f32 v[22:23], v[22:23], v[28:29]

; __device__ __forceinline__ float sigm(float x) { return __builtin_amdgcn_rcpf(1.f + __expf(-x)); }
;     __device__ __forceinline__ void operator()(const f32x4 (&acc)[2][2][4][2], const Unit& u, int wr, int wc, int fr, int fq) const {
;     ...
;             for (int m = 0; m < 4; ++m) { const int row = row0 + ai * HALF + m * 16;
; #pragma unroll
;                 for (int bj = 0; bj < 2; ++bj) { const int col = col0 + bj * HALF;
;                     float gt[8]; unpack8(*(const u32x4*)(H + (size_t)row * NPAD + C_GATE + g * D + col), gt);
;                     float v[8];
; #pragma unroll
;                     for (int e = 0; e < 4; ++e) { v[e] = sigm(gt[e]) * acc[ai][bj][m][0][e]; v[4 + e] = sigm(gt[4 + e]) * acc[ai][bj][m][1][e]; }
;                     if (u.split) { float* cp = SCTX + ((size_t)u.slot * 512 + (row - u.pm * BM + (u.pm ? 256 : 0))) * D + col;
;                         *(f32x4*)cp = (f32x4){v[0], v[1], v[2], v[3]}; *(f32x4*)(cp + 4) = (f32x4){v[4], v[5], v[6], v[7]}; }
.LBB0_974:
	v_add_u32_e32 v20, 0xb0, v142
	v_mov_b64_e32 v[22:23], s[60:61]
	v_mad_i64_i32 v[22:23], s[22:23], v20, s43, v[22:23]
	v_lshl_add_u64 v[22:23], s[20:21], 1, v[22:23]
	v_lshl_add_u64 v[24:25], v[140:141], 1, v[22:23]
	v_add_co_u32_e32 v22, vcc, 0x5000, v24
	s_nop 1
	v_addc_co_u32_e32 v23, vcc, 0, v25, vcc
	s_and_b64 vcc, exec, s[6:7]
	v_mov_b32_e32 v212, 0xb0000
	v_mov_b32_e32 v213, 0
	v_lshl_add_u64 v[212:213], v[210:211], 0, v[212:213]
	global_load_dwordx4 v[206:209], v[212:213], off offset:256
	s_waitcnt vmcnt(9)
	v_mov_b64_e32 v[26:27], v[188:189]
	v_mov_b64_e32 v[28:29], v[190:191]
	v_lshlrev_b32_e32 v21, 16, v26
	v_mul_f32_e32 v21, 0xbfb8aa3b, v21
	v_exp_f32_e32 v21, v21
	v_and_b32_e32 v23, 0xffff0000, v26
	v_lshlrev_b32_e32 v26, 16, v28
	v_lshlrev_b32_e32 v30, 16, v27
	v_add_f32_e32 v21, 1.0, v21
	v_rcp_f32_e32 v22, v21
	v_mul_f32_e32 v21, 0xbfb8aa3b, v26
	v_exp_f32_e32 v21, v21
	v_and_b32_e32 v31, 0xffff0000, v27
	v_and_b32_e32 v27, 0xffff0000, v28
	v_lshlrev_b32_e32 v28, 16, v29
	v_add_f32_e32 v21, 1.0, v21
	v_rcp_f32_e32 v26, v21
	v_mul_f32_e32 v21, 0xbfb8aa3b, v23
	v_exp_f32_e32 v21, v21
	v_and_b32_e32 v29, 0xffff0000, v29
	v_add_f32_e32 v21, 1.0, v21
	v_rcp_f32_e32 v23, v21
	v_mul_f32_e32 v21, 0xbfb8aa3b, v27
	v_exp_f32_e32 v21, v21
	v_pk_mul_f32 v[16:17], v[16:17], v[22:23]
	v_add_f32_e32 v21, 1.0, v21
	v_rcp_f32_e32 v27, v21
	v_mul_f32_e32 v21, 0xbfb8aa3b, v30
	v_exp_f32_e32 v21, v21
	v_pk_mul_f32 v[12:13], v[12:13], v[26:27]
	v_add_f32_e32 v21, 1.0, v21
	v_rcp_f32_e32 v22, v21
	v_mul_f32_e32 v21, 0xbfb8aa3b, v28
	v_exp_f32_e32 v21, v21
	s_nop 0
	v_add_f32_e32 v21, 1.0, v21
	v_rcp_f32_e32 v26, v21
	v_mul_f32_e32 v21, 0xbfb8aa3b, v31
	v_exp_f32_e32 v21, v21
	s_nop 0
	v_add_f32_e32 v21, 1.0, v21
	v_rcp_f32_e32 v23, v21
	v_mul_f32_e32 v21, 0xbfb8aa3b, v29
	v_exp_f32_e32 v21, v21
	v_pk_mul_f32 v[18:19], v[18:19], v[22:23]
	v_add_f32_e32 v21, 1.0, v21
	v_rcp_f32_e32 v27, v21
	s_nop 0
	v_pk_mul_f32 v[14:15], v[14:15], v[26:27]
	s_cbranch_vccnz .LBB0_976
	s_ashr_i32 s9, s8, 31
	s_cmp_eq_u32 s48, 0
	s_cselect_b32 s13, 0, 0x100
	s_sub_i32 s13, s13, s11
	v_add_u32_e32 v22, s13, v20
	s_lshl_b64 s[20:21], s[8:9], 22
	v_ashrrev_i32_e32 v23, 31, v22
	s_add_u32 s20, s28, s20
	s_addc_u32 s21, s29, s21
	v_lshlrev_b64 v[22:23], 13, v[22:23]
	v_lshl_add_u64 v[22:23], s[20:21], 0, v[22:23]
	v_lshl_add_u64 v[22:23], v[140:141], 2, v[22:23]
	s_mov_b64 s[20:21], 0
	global_store_dwordx4 v[22:23], v[16:19], off
	global_store_dwordx4 v[22:23], v[12:15], off offset:16
	s_branch .LBB0_977

;     __device__ __forceinline__ void operator()(const f32x4 (&acc)[2][2][4][2], const Unit& u, int wr, int wc, int fr, int fq) const {
;     ...
;                         if (g > 0) { float pv[8]; unpack8(*(const u32x4*)sp, pv);
; #pragma unroll
;                             for (int e = 0; e < 8; ++e) v[e] += pv[e]; }
.LBB0_977:
	v_ashrrev_i32_e32 v21, 31, v20
	v_lshlrev_b64 v[22:23], 12, v[20:21]
	v_lshl_add_u64 v[22:23], s[38:39], 0, v[22:23]
	s_andn2_b64 vcc, exec, s[20:21]
	v_lshl_add_u64 v[22:23], v[140:141], 1, v[22:23]
	s_cbranch_vccnz .LBB0_981
	s_and_b64 vcc, exec, s[4:5]
	s_cbranch_vccnz .LBB0_980
	s_waitcnt vmcnt(1)
	v_mov_b64_e32 v[26:27], v[202:203]
	v_mov_b64_e32 v[28:29], v[204:205]
	v_lshlrev_b32_e32 v30, 16, v26
	v_and_b32_e32 v31, 0xffff0000, v26
	v_lshlrev_b32_e32 v26, 16, v27
	v_and_b32_e32 v27, 0xffff0000, v27
	v_pk_add_f32 v[18:19], v[18:19], v[26:27]
	v_lshlrev_b32_e32 v26, 16, v28
	v_and_b32_e32 v27, 0xffff0000, v28
	v_pk_add_f32 v[12:13], v[12:13], v[26:27]
	v_lshlrev_b32_e32 v26, 16, v29
	v_and_b32_e32 v27, 0xffff0000, v29
	v_pk_add_f32 v[16:17], v[16:17], v[30:31]
	v_pk_add_f32 v[14:15], v[14:15], v[26:27]

;     __device__ __forceinline__ void operator()(const f32x4 (&acc)[2][2][4][2], const Unit& u, int wr, int wc, int fr, int fq) const {
;     ...
;                         if (g > 0) { float pv[8]; unpack8(*(const u32x4*)sp, pv);
; #pragma unroll
;                             for (int e = 0; e < 8; ++e) v[e] += pv[e]; }
.LBB0_983:
.LBB0_984:
	s_and_b64 vcc, exec, s[4:5]
	s_cbranch_vccnz .LBB0_859
	s_waitcnt vmcnt(0)
	v_mov_b64_e32 v[12:13], v[206:207]
	v_mov_b64_e32 v[14:15], v[208:209]
	v_lshlrev_b32_e32 v16, 16, v12
	v_and_b32_e32 v17, 0xffff0000, v12
	v_lshlrev_b32_e32 v12, 16, v13
	v_and_b32_e32 v13, 0xffff0000, v13
	v_pk_add_f32 v[10:11], v[10:11], v[12:13]
	v_lshlrev_b32_e32 v12, 16, v14
	v_and_b32_e32 v13, 0xffff0000, v14
	v_pk_add_f32 v[4:5], v[4:5], v[12:13]
	v_lshlrev_b32_e32 v12, 16, v15
	v_and_b32_e32 v13, 0xffff0000, v15
	v_pk_add_f32 v[8:9], v[8:9], v[16:17]
	v_pk_add_f32 v[6:7], v[6:7], v[12:13]
	s_branch .LBB0_859

; __device__ __forceinline__ float bflo(unsigned u) { return __uint_as_float(u << 16); }
; __device__ __forceinline__ float bfhi(unsigned u) { return __uint_as_float(u & 0xffff0000u); }
; __device__ __forceinline__ void ln_rows(const Params& P, const float* gam, const float* bet, const float* modU, int shidx, bool writeU, bool writeOut, int nsplit, bool skipctx) {
;     ...
;         for (int j = 0; j < 8; ++j) { const int c = ((j >> 1) * 64 + lane) * 8 + (j & 1) * 4;
;             if (!pf) {
;                 f32x4 a = *(const f32x4*)(X + (size_t)r * D + c) * ALPHA; const float* pp = (const float*)(P.ws + WS_SCTX) + ((size_t)b * 256 + p) * D + c;
;                 for (int q = 0; q < nsplit; ++q) a += *(const f32x4*)(pp + (size_t)q * 512 * D);
;                 v[j] = a; }
;             else { const unsigned t0 = (j & 1) ? ct[j >> 1].z : ct[j >> 1].x, t1 = (j & 1) ? ct[j >> 1].w : ct[j >> 1].y;
;                 v[j] = cx[j] * ALPHA + (f32x4){bflo(t0), bfhi(t0), bflo(t1), bfhi(t1)}; }
.LBB0_1166:
	s_or_b64 exec, exec, s[8:9]
	s_and_saveexec_b64 s[8:9], s[20:21]
	s_xor_b64 s[8:9], exec, s[8:9]
	s_mov_b32 s46, 0x3fb504f3
	v_lshlrev_b32_e32 v116, 16, v180
	v_and_b32_e32 v117, 0xffff0000, v180
	v_lshlrev_b32_e32 v118, 16, v179
	v_and_b32_e32 v119, 0xffff0000, v179
	v_pk_fma_f32 v[118:119], v[122:123], s[46:47], v[118:119] op_sel_hi:[1,0,1]
	v_pk_fma_f32 v[116:117], v[120:121], s[46:47], v[116:117] op_sel_hi:[1,0,1]
	s_or_saveexec_b64 s[8:9], s[8:9]
	v_mul_hi_i32 v1, v178, s78
	v_lshrrev_b32_e32 v120, 31, v1
	v_ashrrev_i32_e32 v1, 11, v1
	v_add_u32_e32 v186, v1, v120
	s_movk_i32 s10, 0xef00
	v_mad_i32_i24 v188, v186, s10, v178
	v_ashrrev_i32_e32 v179, 31, v178
	v_lshlrev_b64 v[120:121], 13, v[178:179]
	v_ashrrev_i32_e32 v187, 31, v186
	v_ashrrev_i32_e32 v189, 31, v188
	v_lshl_add_u64 v[180:181], s[36:37], 0, v[120:121]
	v_lshlrev_b64 v[190:191], 21, v[186:187]
	v_lshlrev_b64 v[192:193], 13, v[188:189]
	s_mov_b32 s44, 0x2800000
	s_mov_b32 s45, 0x2c00000
	s_xor_b64 exec, exec, s[8:9]
	s_cbranch_execz .LBB0_1172
	v_lshl_add_u64 v[116:117], v[180:181], 0, v[2:3]
	global_load_dwordx4 v[116:119], v[116:117], off
	s_andn2_b64 vcc, exec, s[70:71]
	s_waitcnt vmcnt(0)
	v_pk_mul_f32 v[116:117], v[116:117], s[46:47] op_sel_hi:[1,0]
	v_pk_mul_f32 v[118:119], v[118:119], s[46:47] op_sel_hi:[1,0]
	s_cbranch_vccnz .LBB0_1172
	v_lshl_add_u64 v[120:121], v[190:191], 0, v[192:193]
	v_lshl_add_u64 v[120:121], v[156:157], 0, v[120:121]
	s_mov_b32 s10, s54
	s_cmp_lg_u32 s54, 8
	s_cbranch_scc1 .LBB0_1171
	global_load_dwordx4 v[234:237], v[120:121], off
	v_lshl_add_u64 v[248:249], v[120:121], 0, s[76:77]
	global_load_dwordx4 v[238:241], v[248:249], off
	v_lshl_add_u64 v[248:249], v[248:249], 0, s[76:77]
	global_load_dwordx4 v[244:247], v[248:249], off
	v_lshl_add_u64 v[248:249], v[248:249], 0, s[76:77]
	global_load_dwordx4 v[212:215], v[248:249], off
	s_waitcnt vmcnt(3)
	v_pk_add_f32 v[118:119], v[118:119], v[236:237]
	v_pk_add_f32 v[116:117], v[116:117], v[234:235]
	v_lshl_add_u64 v[248:249], v[248:249], 0, s[76:77]
	global_load_dwordx4 v[234:237], v[248:249], off
	s_waitcnt vmcnt(3)
	v_pk_add_f32 v[118:119], v[118:119], v[240:241]
	v_pk_add_f32 v[116:117], v[116:117], v[238:239]
	v_lshl_add_u64 v[248:249], v[248:249], 0, s[76:77]
	global_load_dwordx4 v[238:241], v[248:249], off
	s_waitcnt vmcnt(3)
	v_pk_add_f32 v[118:119], v[118:119], v[246:247]
	v_pk_add_f32 v[116:117], v[116:117], v[244:245]
	v_lshl_add_u64 v[248:249], v[248:249], 0, s[76:77]
	global_load_dwordx4 v[244:247], v[248:249], off
	s_waitcnt vmcnt(3)
	v_pk_add_f32 v[118:119], v[118:119], v[214:215]
	v_pk_add_f32 v[116:117], v[116:117], v[212:213]
	v_lshl_add_u64 v[248:249], v[248:249], 0, s[76:77]
	global_load_dwordx4 v[212:215], v[248:249], off
	s_waitcnt vmcnt(3)
	v_pk_add_f32 v[118:119], v[118:119], v[236:237]
	v_pk_add_f32 v[116:117], v[116:117], v[234:235]
	s_waitcnt vmcnt(2)
	v_pk_add_f32 v[118:119], v[118:119], v[240:241]
	v_pk_add_f32 v[116:117], v[116:117], v[238:239]
	s_waitcnt vmcnt(1)
	v_pk_add_f32 v[118:119], v[118:119], v[246:247]
	v_pk_add_f32 v[116:117], v[116:117], v[244:245]
	s_waitcnt vmcnt(0)
	v_pk_add_f32 v[118:119], v[118:119], v[214:215]
	v_pk_add_f32 v[116:117], v[116:117], v[212:213]
	s_mov_b32 s10, 0
	v_lshl_add_u64 v[120:121], v[248:249], 0, s[76:77]
	s_branch .Lln1_done_1

; __device__ __forceinline__ void ln_rows(const Params& P, const float* gam, const float* bet, const float* modU, int shidx, bool writeU, bool writeOut, int nsplit, bool skipctx) {
;     ...
;         for (int j = 0; j < 8; ++j) { const int c = ((j >> 1) * 64 + lane) * 8 + (j & 1) * 4;
;             if (!pf) {
;                 f32x4 a = *(const f32x4*)(X + (size_t)r * D + c) * ALPHA; const float* pp = (const float*)(P.ws + WS_SCTX) + ((size_t)b * 256 + p) * D + c;
;                 for (int q = 0; q < nsplit; ++q) a += *(const f32x4*)(pp + (size_t)q * 512 * D);
;                 v[j] = a; }
.Lln1_done_1:
.LBB0_1172:
	s_or_b64 exec, exec, s[8:9]
	s_and_saveexec_b64 s[8:9], s[20:21]
	s_xor_b64 s[8:9], exec, s[8:9]
	v_lshlrev_b32_e32 v120, 16, v210
	v_and_b32_e32 v121, 0xffff0000, v210
	v_lshlrev_b32_e32 v122, 16, v209
	v_and_b32_e32 v123, 0xffff0000, v209
	v_pk_fma_f32 v[122:123], v[126:127], s[46:47], v[122:123] op_sel_hi:[1,0,1]
	v_pk_fma_f32 v[120:121], v[124:125], s[46:47], v[120:121] op_sel_hi:[1,0,1]
	s_andn2_saveexec_b64 s[8:9], s[8:9]
	s_cbranch_execz .LBB0_1178
	v_lshl_add_u64 v[120:121], v[180:181], 0, v[2:3]
	global_load_dwordx4 v[120:123], v[120:121], off offset:16
	s_andn2_b64 vcc, exec, s[70:71]
	s_waitcnt vmcnt(0)
	v_pk_mul_f32 v[120:121], v[120:121], s[46:47] op_sel_hi:[1,0]
	v_pk_mul_f32 v[122:123], v[122:123], s[46:47] op_sel_hi:[1,0]
	s_cbranch_vccnz .LBB0_1178
	v_lshl_add_u64 v[124:125], v[190:191], 0, v[192:193]
	v_lshl_add_u64 v[124:125], v[158:159], 0, v[124:125]
	s_mov_b32 s10, s54
	s_cmp_lg_u32 s54, 8
	s_cbranch_scc1 .LBB0_1177
	global_load_dwordx4 v[234:237], v[124:125], off
	v_lshl_add_u64 v[248:249], v[124:125], 0, s[76:77]
	global_load_dwordx4 v[238:241], v[248:249], off
	v_lshl_add_u64 v[248:249], v[248:249], 0, s[76:77]
	global_load_dwordx4 v[244:247], v[248:249], off
	v_lshl_add_u64 v[248:249], v[248:249], 0, s[76:77]
	global_load_dwordx4 v[210:213], v[248:249], off
	s_waitcnt vmcnt(3)
	v_pk_add_f32 v[122:123], v[122:123], v[236:237]
	v_pk_add_f32 v[120:121], v[120:121], v[234:235]
	v_lshl_add_u64 v[248:249], v[248:249], 0, s[76:77]
	global_load_dwordx4 v[234:237], v[248:249], off
	s_waitcnt vmcnt(3)
	v_pk_add_f32 v[122:123], v[122:123], v[240:241]
	v_pk_add_f32 v[120:121], v[120:121], v[238:239]
	v_lshl_add_u64 v[248:249], v[248:249], 0, s[76:77]
	global_load_dwordx4 v[238:241], v[248:249], off
	s_waitcnt vmcnt(3)
	v_pk_add_f32 v[122:123], v[122:123], v[246:247]
	v_pk_add_f32 v[120:121], v[120:121], v[244:245]
	v_lshl_add_u64 v[248:249], v[248:249], 0, s[76:77]
	global_load_dwordx4 v[244:247], v[248:249], off
	s_waitcnt vmcnt(3)
	v_pk_add_f32 v[122:123], v[122:123], v[212:213]
	v_pk_add_f32 v[120:121], v[120:121], v[210:211]
	v_lshl_add_u64 v[248:249], v[248:249], 0, s[76:77]
	global_load_dwordx4 v[210:213], v[248:249], off
	s_waitcnt vmcnt(3)
	v_pk_add_f32 v[122:123], v[122:123], v[236:237]
	v_pk_add_f32 v[120:121], v[120:121], v[234:235]
	s_waitcnt vmcnt(2)
	v_pk_add_f32 v[122:123], v[122:123], v[240:241]
	v_pk_add_f32 v[120:121], v[120:121], v[238:239]
	s_waitcnt vmcnt(1)
	v_pk_add_f32 v[122:123], v[122:123], v[246:247]
	v_pk_add_f32 v[120:121], v[120:121], v[244:245]
	s_waitcnt vmcnt(0)
	v_pk_add_f32 v[122:123], v[122:123], v[212:213]
	v_pk_add_f32 v[120:121], v[120:121], v[210:211]
	s_mov_b32 s10, 0
	v_lshl_add_u64 v[124:125], v[248:249], 0, s[76:77]
	s_branch .Lln1_done_2

; __device__ __forceinline__ void ln_rows(const Params& P, const float* gam, const float* bet, const float* modU, int shidx, bool writeU, bool writeOut, int nsplit, bool skipctx) {
;     ...
;         for (int j = 0; j < 8; ++j) { const int c = ((j >> 1) * 64 + lane) * 8 + (j & 1) * 4;
;             if (!pf) {
;                 f32x4 a = *(const f32x4*)(X + (size_t)r * D + c) * ALPHA; const float* pp = (const float*)(P.ws + WS_SCTX) + ((size_t)b * 256 + p) * D + c;
;                 for (int q = 0; q < nsplit; ++q) a += *(const f32x4*)(pp + (size_t)q * 512 * D);
;                 v[j] = a; }
.Lln1_done_2:
.LBB0_1178:
	s_or_b64 exec, exec, s[8:9]
	s_and_saveexec_b64 s[8:9], s[20:21]
	s_xor_b64 s[8:9], exec, s[8:9]
	v_lshlrev_b32_e32 v124, 16, v208
	v_and_b32_e32 v125, 0xffff0000, v208
	v_lshlrev_b32_e32 v126, 16, v207
	v_and_b32_e32 v127, 0xffff0000, v207
	v_pk_fma_f32 v[126:127], v[130:131], s[46:47], v[126:127] op_sel_hi:[1,0,1]
	v_pk_fma_f32 v[124:125], v[128:129], s[46:47], v[124:125] op_sel_hi:[1,0,1]
	s_andn2_saveexec_b64 s[8:9], s[8:9]
	s_cbranch_execz .LBB0_1184
	v_lshl_add_u64 v[124:125], v[180:181], 0, v[2:3]
	global_load_dwordx4 v[124:127], v[124:125], off offset:2048
	s_andn2_b64 vcc, exec, s[70:71]
	s_waitcnt vmcnt(0)
	v_pk_mul_f32 v[124:125], v[124:125], s[46:47] op_sel_hi:[1,0]
	v_pk_mul_f32 v[126:127], v[126:127], s[46:47] op_sel_hi:[1,0]
	s_cbranch_vccnz .LBB0_1184
	v_lshl_add_u64 v[128:129], v[190:191], 0, v[192:193]
	v_lshl_add_u64 v[128:129], v[160:161], 0, v[128:129]
	s_mov_b32 s10, s54
	s_cmp_lg_u32 s54, 8
	s_cbranch_scc1 .LBB0_1183
	global_load_dwordx4 v[234:237], v[128:129], off
	v_lshl_add_u64 v[248:249], v[128:129], 0, s[76:77]
	global_load_dwordx4 v[238:241], v[248:249], off
	v_lshl_add_u64 v[248:249], v[248:249], 0, s[76:77]
	global_load_dwordx4 v[244:247], v[248:249], off
	v_lshl_add_u64 v[248:249], v[248:249], 0, s[76:77]
	global_load_dwordx4 v[208:211], v[248:249], off
	s_waitcnt vmcnt(3)
	v_pk_add_f32 v[126:127], v[126:127], v[236:237]
	v_pk_add_f32 v[124:125], v[124:125], v[234:235]
	v_lshl_add_u64 v[248:249], v[248:249], 0, s[76:77]
	global_load_dwordx4 v[234:237], v[248:249], off
	s_waitcnt vmcnt(3)
	v_pk_add_f32 v[126:127], v[126:127], v[240:241]
	v_pk_add_f32 v[124:125], v[124:125], v[238:239]
	v_lshl_add_u64 v[248:249], v[248:249], 0, s[76:77]
	global_load_dwordx4 v[238:241], v[248:249], off
	s_waitcnt vmcnt(3)
	v_pk_add_f32 v[126:127], v[126:127], v[246:247]
	v_pk_add_f32 v[124:125], v[124:125], v[244:245]
	v_lshl_add_u64 v[248:249], v[248:249], 0, s[76:77]
	global_load_dwordx4 v[244:247], v[248:249], off
	s_waitcnt vmcnt(3)
	v_pk_add_f32 v[126:127], v[126:127], v[210:211]
	v_pk_add_f32 v[124:125], v[124:125], v[208:209]
	v_lshl_add_u64 v[248:249], v[248:249], 0, s[76:77]
	global_load_dwordx4 v[208:211], v[248:249], off
	s_waitcnt vmcnt(3)
	v_pk_add_f32 v[126:127], v[126:127], v[236:237]
	v_pk_add_f32 v[124:125], v[124:125], v[234:235]
	s_waitcnt vmcnt(2)
	v_pk_add_f32 v[126:127], v[126:127], v[240:241]
	v_pk_add_f32 v[124:125], v[124:125], v[238:239]
	s_waitcnt vmcnt(1)
	v_pk_add_f32 v[126:127], v[126:127], v[246:247]
	v_pk_add_f32 v[124:125], v[124:125], v[244:245]
	s_waitcnt vmcnt(0)
	v_pk_add_f32 v[126:127], v[126:127], v[210:211]
	v_pk_add_f32 v[124:125], v[124:125], v[208:209]
	s_mov_b32 s10, 0
	v_lshl_add_u64 v[128:129], v[248:249], 0, s[76:77]
	s_branch .Lln1_done_3

; __device__ __forceinline__ void ln_rows(const Params& P, const float* gam, const float* bet, const float* modU, int shidx, bool writeU, bool writeOut, int nsplit, bool skipctx) {
;     ...
;         for (int j = 0; j < 8; ++j) { const int c = ((j >> 1) * 64 + lane) * 8 + (j & 1) * 4;
;             if (!pf) {
;                 f32x4 a = *(const f32x4*)(X + (size_t)r * D + c) * ALPHA; const float* pp = (const float*)(P.ws + WS_SCTX) + ((size_t)b * 256 + p) * D + c;
;                 for (int q = 0; q < nsplit; ++q) a += *(const f32x4*)(pp + (size_t)q * 512 * D);
;                 v[j] = a; }
.Lln1_done_3:
.LBB0_1184:
	s_or_b64 exec, exec, s[8:9]
	s_and_saveexec_b64 s[8:9], s[20:21]
	s_xor_b64 s[8:9], exec, s[8:9]
	v_lshlrev_b32_e32 v128, 16, v206
	v_and_b32_e32 v129, 0xffff0000, v206
	v_lshlrev_b32_e32 v130, 16, v205
	v_and_b32_e32 v131, 0xffff0000, v205
	v_pk_fma_f32 v[130:131], v[134:135], s[46:47], v[130:131] op_sel_hi:[1,0,1]
	v_pk_fma_f32 v[128:129], v[132:133], s[46:47], v[128:129] op_sel_hi:[1,0,1]
	s_andn2_saveexec_b64 s[8:9], s[8:9]
	s_cbranch_execz .LBB0_1190
	v_lshl_add_u64 v[128:129], v[180:181], 0, v[2:3]
	global_load_dwordx4 v[128:131], v[128:129], off offset:2064
	s_andn2_b64 vcc, exec, s[70:71]
	s_waitcnt vmcnt(0)
	v_pk_mul_f32 v[128:129], v[128:129], s[46:47] op_sel_hi:[1,0]
	v_pk_mul_f32 v[130:131], v[130:131], s[46:47] op_sel_hi:[1,0]
	s_cbranch_vccnz .LBB0_1190
	v_lshl_add_u64 v[132:133], v[190:191], 0, v[192:193]
	v_lshl_add_u64 v[132:133], v[162:163], 0, v[132:133]
	s_mov_b32 s10, s54
	s_cmp_lg_u32 s54, 8
	s_cbranch_scc1 .LBB0_1189
	global_load_dwordx4 v[234:237], v[132:133], off
	v_lshl_add_u64 v[248:249], v[132:133], 0, s[76:77]
	global_load_dwordx4 v[238:241], v[248:249], off
	v_lshl_add_u64 v[248:249], v[248:249], 0, s[76:77]
	global_load_dwordx4 v[244:247], v[248:249], off
	v_lshl_add_u64 v[248:249], v[248:249], 0, s[76:77]
	global_load_dwordx4 v[206:209], v[248:249], off
	s_waitcnt vmcnt(3)
	v_pk_add_f32 v[130:131], v[130:131], v[236:237]
	v_pk_add_f32 v[128:129], v[128:129], v[234:235]
	v_lshl_add_u64 v[248:249], v[248:249], 0, s[76:77]
	global_load_dwordx4 v[234:237], v[248:249], off
	s_waitcnt vmcnt(3)
	v_pk_add_f32 v[130:131], v[130:131], v[240:241]
	v_pk_add_f32 v[128:129], v[128:129], v[238:239]
	v_lshl_add_u64 v[248:249], v[248:249], 0, s[76:77]
	global_load_dwordx4 v[238:241], v[248:249], off
	s_waitcnt vmcnt(3)
	v_pk_add_f32 v[130:131], v[130:131], v[246:247]
	v_pk_add_f32 v[128:129], v[128:129], v[244:245]
	v_lshl_add_u64 v[248:249], v[248:249], 0, s[76:77]
	global_load_dwordx4 v[244:247], v[248:249], off
	s_waitcnt vmcnt(3)
	v_pk_add_f32 v[130:131], v[130:131], v[208:209]
	v_pk_add_f32 v[128:129], v[128:129], v[206:207]
	v_lshl_add_u64 v[248:249], v[248:249], 0, s[76:77]
	global_load_dwordx4 v[206:209], v[248:249], off
	s_waitcnt vmcnt(3)
	v_pk_add_f32 v[130:131], v[130:131], v[236:237]
	v_pk_add_f32 v[128:129], v[128:129], v[234:235]
	s_waitcnt vmcnt(2)
	v_pk_add_f32 v[130:131], v[130:131], v[240:241]
	v_pk_add_f32 v[128:129], v[128:129], v[238:239]
	s_waitcnt vmcnt(1)
	v_pk_add_f32 v[130:131], v[130:131], v[246:247]
	v_pk_add_f32 v[128:129], v[128:129], v[244:245]
	s_waitcnt vmcnt(0)
	v_pk_add_f32 v[130:131], v[130:131], v[208:209]
	v_pk_add_f32 v[128:129], v[128:129], v[206:207]
	s_mov_b32 s10, 0
	v_lshl_add_u64 v[132:133], v[248:249], 0, s[76:77]
	s_branch .Lln1_done_4

; __device__ __forceinline__ void ln_rows(const Params& P, const float* gam, const float* bet, const float* modU, int shidx, bool writeU, bool writeOut, int nsplit, bool skipctx) {
;     ...
;         for (int j = 0; j < 8; ++j) { const int c = ((j >> 1) * 64 + lane) * 8 + (j & 1) * 4;
;             if (!pf) {
;                 f32x4 a = *(const f32x4*)(X + (size_t)r * D + c) * ALPHA; const float* pp = (const float*)(P.ws + WS_SCTX) + ((size_t)b * 256 + p) * D + c;
;                 for (int q = 0; q < nsplit; ++q) a += *(const f32x4*)(pp + (size_t)q * 512 * D);
;                 v[j] = a; }
.Lln1_done_4:
.LBB0_1190:
	s_or_b64 exec, exec, s[8:9]
	s_and_saveexec_b64 s[8:9], s[20:21]
	s_xor_b64 s[8:9], exec, s[8:9]
	v_lshlrev_b32_e32 v132, 16, v204
	v_and_b32_e32 v133, 0xffff0000, v204
	v_lshlrev_b32_e32 v134, 16, v203
	v_and_b32_e32 v135, 0xffff0000, v203
	v_pk_fma_f32 v[134:135], v[142:143], s[46:47], v[134:135] op_sel_hi:[1,0,1]
	v_pk_fma_f32 v[132:133], v[140:141], s[46:47], v[132:133] op_sel_hi:[1,0,1]
	s_andn2_saveexec_b64 s[8:9], s[8:9]
	s_cbranch_execz .LBB0_1196
	v_mov_b32_e32 v149, v3
	v_lshl_add_u64 v[132:133], v[180:181], 0, v[148:149]
	global_load_dwordx4 v[132:135], v[132:133], off
	s_andn2_b64 vcc, exec, s[70:71]
	s_waitcnt vmcnt(0)
	v_pk_mul_f32 v[132:133], v[132:133], s[46:47] op_sel_hi:[1,0]
	v_pk_mul_f32 v[134:135], v[134:135], s[46:47] op_sel_hi:[1,0]
	s_cbranch_vccnz .LBB0_1196
	v_lshl_add_u64 v[140:141], v[190:191], 0, v[192:193]
	v_lshl_add_u64 v[140:141], v[164:165], 0, v[140:141]
	s_mov_b32 s10, s54
	s_cmp_lg_u32 s54, 8
	s_cbranch_scc1 .LBB0_1195
	global_load_dwordx4 v[234:237], v[140:141], off
	v_lshl_add_u64 v[248:249], v[140:141], 0, s[76:77]
	global_load_dwordx4 v[238:241], v[248:249], off
	v_lshl_add_u64 v[248:249], v[248:249], 0, s[76:77]
	global_load_dwordx4 v[244:247], v[248:249], off
	v_lshl_add_u64 v[248:249], v[248:249], 0, s[76:77]
	global_load_dwordx4 v[204:207], v[248:249], off
	s_waitcnt vmcnt(3)
	v_pk_add_f32 v[134:135], v[134:135], v[236:237]
	v_pk_add_f32 v[132:133], v[132:133], v[234:235]
	v_lshl_add_u64 v[248:249], v[248:249], 0, s[76:77]
	global_load_dwordx4 v[234:237], v[248:249], off
	s_waitcnt vmcnt(3)
	v_pk_add_f32 v[134:135], v[134:135], v[240:241]
	v_pk_add_f32 v[132:133], v[132:133], v[238:239]
	v_lshl_add_u64 v[248:249], v[248:249], 0, s[76:77]
	global_load_dwordx4 v[238:241], v[248:249], off
	s_waitcnt vmcnt(3)
	v_pk_add_f32 v[134:135], v[134:135], v[246:247]
	v_pk_add_f32 v[132:133], v[132:133], v[244:245]
	v_lshl_add_u64 v[248:249], v[248:249], 0, s[76:77]
	global_load_dwordx4 v[244:247], v[248:249], off
	s_waitcnt vmcnt(3)
	v_pk_add_f32 v[134:135], v[134:135], v[206:207]
	v_pk_add_f32 v[132:133], v[132:133], v[204:205]
	v_lshl_add_u64 v[248:249], v[248:249], 0, s[76:77]
	global_load_dwordx4 v[204:207], v[248:249], off
	s_waitcnt vmcnt(3)
	v_pk_add_f32 v[134:135], v[134:135], v[236:237]
	v_pk_add_f32 v[132:133], v[132:133], v[234:235]
	s_waitcnt vmcnt(2)
	v_pk_add_f32 v[134:135], v[134:135], v[240:241]
	v_pk_add_f32 v[132:133], v[132:133], v[238:239]
	s_waitcnt vmcnt(1)
	v_pk_add_f32 v[134:135], v[134:135], v[246:247]
	v_pk_add_f32 v[132:133], v[132:133], v[244:245]
	s_waitcnt vmcnt(0)
	v_pk_add_f32 v[134:135], v[134:135], v[206:207]
	v_pk_add_f32 v[132:133], v[132:133], v[204:205]
	s_mov_b32 s10, 0
	v_lshl_add_u64 v[140:141], v[248:249], 0, s[76:77]
	s_branch .Lln1_done_5

; __device__ __forceinline__ void ln_rows(const Params& P, const float* gam, const float* bet, const float* modU, int shidx, bool writeU, bool writeOut, int nsplit, bool skipctx) {
;     ...
;         for (int j = 0; j < 8; ++j) { const int c = ((j >> 1) * 64 + lane) * 8 + (j & 1) * 4;
;             if (!pf) {
;                 f32x4 a = *(const f32x4*)(X + (size_t)r * D + c) * ALPHA; const float* pp = (const float*)(P.ws + WS_SCTX) + ((size_t)b * 256 + p) * D + c;
;                 for (int q = 0; q < nsplit; ++q) a += *(const f32x4*)(pp + (size_t)q * 512 * D);
;                 v[j] = a; }
.Lln1_done_5:
.LBB0_1196:
	s_or_b64 exec, exec, s[8:9]
	s_and_saveexec_b64 s[8:9], s[20:21]
	s_xor_b64 s[8:9], exec, s[8:9]
	v_lshlrev_b32_e32 v140, 16, v202
	v_and_b32_e32 v141, 0xffff0000, v202
	v_lshlrev_b32_e32 v142, 16, v173
	v_and_b32_e32 v143, 0xffff0000, v173
	v_pk_fma_f32 v[142:143], v[138:139], s[46:47], v[142:143] op_sel_hi:[1,0,1]
	v_pk_fma_f32 v[140:141], v[136:137], s[46:47], v[140:141] op_sel_hi:[1,0,1]
	s_andn2_saveexec_b64 s[8:9], s[8:9]
	s_cbranch_execz .LBB0_1202
	v_mov_b32_e32 v173, v3
	v_lshl_add_u64 v[136:137], v[180:181], 0, v[172:173]
	global_load_dwordx4 v[136:139], v[136:137], off
	s_andn2_b64 vcc, exec, s[70:71]
	s_waitcnt vmcnt(0)
	v_pk_mul_f32 v[140:141], v[136:137], s[46:47] op_sel_hi:[1,0]
	v_pk_mul_f32 v[142:143], v[138:139], s[46:47] op_sel_hi:[1,0]
	s_cbranch_vccnz .LBB0_1202
	v_lshl_add_u64 v[136:137], v[190:191], 0, v[192:193]
	v_lshl_add_u64 v[136:137], v[166:167], 0, v[136:137]
	s_mov_b32 s10, s54
	s_cmp_lg_u32 s54, 8
	s_cbranch_scc1 .LBB0_1201
	global_load_dwordx4 v[234:237], v[136:137], off
	v_lshl_add_u64 v[248:249], v[136:137], 0, s[76:77]
	global_load_dwordx4 v[238:241], v[248:249], off
	v_lshl_add_u64 v[248:249], v[248:249], 0, s[76:77]
	global_load_dwordx4 v[244:247], v[248:249], off
	v_lshl_add_u64 v[248:249], v[248:249], 0, s[76:77]
	global_load_dwordx4 v[202:205], v[248:249], off
	s_waitcnt vmcnt(3)
	v_pk_add_f32 v[142:143], v[142:143], v[236:237]
	v_pk_add_f32 v[140:141], v[140:141], v[234:235]
	v_lshl_add_u64 v[248:249], v[248:249], 0, s[76:77]
	global_load_dwordx4 v[234:237], v[248:249], off
	s_waitcnt vmcnt(3)
	v_pk_add_f32 v[142:143], v[142:143], v[240:241]
	v_pk_add_f32 v[140:141], v[140:141], v[238:239]
	v_lshl_add_u64 v[248:249], v[248:249], 0, s[76:77]
	global_load_dwordx4 v[238:241], v[248:249], off
	s_waitcnt vmcnt(3)
	v_pk_add_f32 v[142:143], v[142:143], v[246:247]
	v_pk_add_f32 v[140:141], v[140:141], v[244:245]
	v_lshl_add_u64 v[248:249], v[248:249], 0, s[76:77]
	global_load_dwordx4 v[244:247], v[248:249], off
	s_waitcnt vmcnt(3)
	v_pk_add_f32 v[142:143], v[142:143], v[204:205]
	v_pk_add_f32 v[140:141], v[140:141], v[202:203]
	v_lshl_add_u64 v[248:249], v[248:249], 0, s[76:77]
	global_load_dwordx4 v[202:205], v[248:249], off
	s_waitcnt vmcnt(3)
	v_pk_add_f32 v[142:143], v[142:143], v[236:237]
	v_pk_add_f32 v[140:141], v[140:141], v[234:235]
	s_waitcnt vmcnt(2)
	v_pk_add_f32 v[142:143], v[142:143], v[240:241]
	v_pk_add_f32 v[140:141], v[140:141], v[238:239]
	s_waitcnt vmcnt(1)
	v_pk_add_f32 v[142:143], v[142:143], v[246:247]
	v_pk_add_f32 v[140:141], v[140:141], v[244:245]
	s_waitcnt vmcnt(0)
	v_pk_add_f32 v[142:143], v[142:143], v[204:205]
	v_pk_add_f32 v[140:141], v[140:141], v[202:203]
	s_mov_b32 s10, 0
	v_lshl_add_u64 v[136:137], v[248:249], 0, s[76:77]
	s_branch .Lln1_done_6

; __device__ __forceinline__ void ln_rows(const Params& P, const float* gam, const float* bet, const float* modU, int shidx, bool writeU, bool writeOut, int nsplit, bool skipctx) {
;     ...
;         for (int j = 0; j < 8; ++j) { const int c = ((j >> 1) * 64 + lane) * 8 + (j & 1) * 4;
;             if (!pf) {
;                 f32x4 a = *(const f32x4*)(X + (size_t)r * D + c) * ALPHA; const float* pp = (const float*)(P.ws + WS_SCTX) + ((size_t)b * 256 + p) * D + c;
;                 for (int q = 0; q < nsplit; ++q) a += *(const f32x4*)(pp + (size_t)q * 512 * D);
;                 v[j] = a; }
.Lln1_done_6:
.LBB0_1202:
	s_or_b64 exec, exec, s[8:9]
	s_and_saveexec_b64 s[8:9], s[20:21]
	s_xor_b64 s[8:9], exec, s[8:9]
	v_lshlrev_b32_e32 v136, 16, v195
	v_and_b32_e32 v137, 0xffff0000, v195
	v_lshlrev_b32_e32 v138, 16, v194
	v_and_b32_e32 v139, 0xffff0000, v194
	v_pk_fma_f32 v[138:139], v[146:147], s[46:47], v[138:139] op_sel_hi:[1,0,1]
	v_pk_fma_f32 v[136:137], v[144:145], s[46:47], v[136:137] op_sel_hi:[1,0,1]
	s_andn2_saveexec_b64 s[8:9], s[8:9]
	s_cbranch_execz .LBB0_1208
	v_mov_b32_e32 v151, v3
	v_lshl_add_u64 v[136:137], v[180:181], 0, v[150:151]
	global_load_dwordx4 v[136:139], v[136:137], off
	s_andn2_b64 vcc, exec, s[70:71]
	s_waitcnt vmcnt(0)
	v_pk_mul_f32 v[136:137], v[136:137], s[46:47] op_sel_hi:[1,0]
	v_pk_mul_f32 v[138:139], v[138:139], s[46:47] op_sel_hi:[1,0]
	s_cbranch_vccnz .LBB0_1208
	v_lshl_add_u64 v[144:145], v[190:191], 0, v[192:193]
	v_lshl_add_u64 v[144:145], v[168:169], 0, v[144:145]
	s_mov_b32 s10, s54
	s_cmp_lg_u32 s54, 8
	s_cbranch_scc1 .LBB0_1207
	global_load_dwordx4 v[234:237], v[144:145], off
	v_lshl_add_u64 v[248:249], v[144:145], 0, s[76:77]
	global_load_dwordx4 v[238:241], v[248:249], off
	v_lshl_add_u64 v[248:249], v[248:249], 0, s[76:77]
	global_load_dwordx4 v[244:247], v[248:249], off
	v_lshl_add_u64 v[248:249], v[248:249], 0, s[76:77]
	global_load_dwordx4 v[202:205], v[248:249], off
	s_waitcnt vmcnt(3)
	v_pk_add_f32 v[138:139], v[138:139], v[236:237]
	v_pk_add_f32 v[136:137], v[136:137], v[234:235]
	v_lshl_add_u64 v[248:249], v[248:249], 0, s[76:77]
	global_load_dwordx4 v[234:237], v[248:249], off
	s_waitcnt vmcnt(3)
	v_pk_add_f32 v[138:139], v[138:139], v[240:241]
	v_pk_add_f32 v[136:137], v[136:137], v[238:239]
	v_lshl_add_u64 v[248:249], v[248:249], 0, s[76:77]
	global_load_dwordx4 v[238:241], v[248:249], off
	s_waitcnt vmcnt(3)
	v_pk_add_f32 v[138:139], v[138:139], v[246:247]
	v_pk_add_f32 v[136:137], v[136:137], v[244:245]
	v_lshl_add_u64 v[248:249], v[248:249], 0, s[76:77]
	global_load_dwordx4 v[244:247], v[248:249], off
	s_waitcnt vmcnt(3)
	v_pk_add_f32 v[138:139], v[138:139], v[204:205]
	v_pk_add_f32 v[136:137], v[136:137], v[202:203]
	v_lshl_add_u64 v[248:249], v[248:249], 0, s[76:77]
	global_load_dwordx4 v[202:205], v[248:249], off
	s_waitcnt vmcnt(3)
	v_pk_add_f32 v[138:139], v[138:139], v[236:237]
	v_pk_add_f32 v[136:137], v[136:137], v[234:235]
	s_waitcnt vmcnt(2)
	v_pk_add_f32 v[138:139], v[138:139], v[240:241]
	v_pk_add_f32 v[136:137], v[136:137], v[238:239]
	s_waitcnt vmcnt(1)
	v_pk_add_f32 v[138:139], v[138:139], v[246:247]
	v_pk_add_f32 v[136:137], v[136:137], v[244:245]
	s_waitcnt vmcnt(0)
	v_pk_add_f32 v[138:139], v[138:139], v[204:205]
	v_pk_add_f32 v[136:137], v[136:137], v[202:203]
	s_mov_b32 s10, 0
	v_lshl_add_u64 v[144:145], v[248:249], 0, s[76:77]
	s_branch .Lln1_done_7

; __device__ __forceinline__ unsigned xcc_id() { return (unsigned)__builtin_amdgcn_s_getreg((3 << 11) | 20) & 0xFu; }
; __device__ __forceinline__ void ln_rows(const Params& P, const float* gam, const float* bet, const float* modU, int shidx, bool writeU, bool writeOut, int nsplit, bool skipctx) {
;     ...
;         for (int j = 0; j < 8; ++j) { const int c = ((j >> 1) * 64 + lane) * 8 + (j & 1) * 4;
;             if (!pf) {
;                 f32x4 a = *(const f32x4*)(X + (size_t)r * D + c) * ALPHA; const float* pp = (const float*)(P.ws + WS_SCTX) + ((size_t)b * 256 + p) * D + c;
;                 for (int q = 0; q < nsplit; ++q) a += *(const f32x4*)(pp + (size_t)q * 512 * D);
;                 v[j] = a; }
; __device__ __forceinline__ void gbar_impl(unsigned* bar, unsigned& gen, unsigned nloc, unsigned nx) {
;     asm volatile("s_waitcnt vmcnt(0)" ::: "memory");
;     __syncthreads();
;     gen += 1u;
;     if (threadIdx.x == 0) {
;         __builtin_amdgcn_s_waitcnt(0);
;         const unsigned x = xcc_id();
;         const unsigned old = __hip_atomic_fetch_add(bar + XB_SUB(x), 1u, __ATOMIC_RELAXED, __HIP_MEMORY_SCOPE_AGENT);
.Lln1_done_7:
.LBB0_1208:
	s_or_b64 exec, exec, s[8:9]
	s_and_saveexec_b64 s[8:9], s[20:21]
	s_xor_b64 s[8:9], exec, s[8:9]
	v_lshlrev_b32_e32 v144, 16, v177
	v_and_b32_e32 v145, 0xffff0000, v177
	v_lshlrev_b32_e32 v146, 16, v175
	v_and_b32_e32 v147, 0xffff0000, v175
	v_pk_fma_f32 v[146:147], v[184:185], s[46:47], v[146:147] op_sel_hi:[1,0,1]
	v_pk_fma_f32 v[144:145], v[182:183], s[46:47], v[144:145] op_sel_hi:[1,0,1]
	s_andn2_saveexec_b64 s[8:9], s[8:9]
	s_cbranch_execz .LBB0_1161
	v_mov_b32_e32 v175, v3
	v_lshl_add_u64 v[144:145], v[180:181], 0, v[174:175]
	global_load_dwordx4 v[144:147], v[144:145], off
	s_andn2_b64 vcc, exec, s[70:71]
	s_waitcnt vmcnt(0)
	v_pk_mul_f32 v[144:145], v[144:145], s[46:47] op_sel_hi:[1,0]
	v_pk_mul_f32 v[146:147], v[146:147], s[46:47] op_sel_hi:[1,0]
	s_cbranch_vccnz .LBB0_1161
	v_lshl_add_u64 v[182:183], v[190:191], 0, v[192:193]
	v_lshl_add_u64 v[182:183], v[170:171], 0, v[182:183]
	s_mov_b32 s10, s54
	s_cmp_lg_u32 s54, 8
	s_cbranch_scc1 .LBB0_1213
	global_load_dwordx4 v[234:237], v[182:183], off
	v_lshl_add_u64 v[248:249], v[182:183], 0, s[76:77]
	global_load_dwordx4 v[238:241], v[248:249], off
	v_lshl_add_u64 v[248:249], v[248:249], 0, s[76:77]
	global_load_dwordx4 v[244:247], v[248:249], off
	v_lshl_add_u64 v[248:249], v[248:249], 0, s[76:77]
	global_load_dwordx4 v[190:193], v[248:249], off
	s_waitcnt vmcnt(3)
	v_pk_add_f32 v[146:147], v[146:147], v[236:237]
	v_pk_add_f32 v[144:145], v[144:145], v[234:235]
	v_lshl_add_u64 v[248:249], v[248:249], 0, s[76:77]
	global_load_dwordx4 v[234:237], v[248:249], off
	s_waitcnt vmcnt(3)
	v_pk_add_f32 v[146:147], v[146:147], v[240:241]
	v_pk_add_f32 v[144:145], v[144:145], v[238:239]
	v_lshl_add_u64 v[248:249], v[248:249], 0, s[76:77]
	global_load_dwordx4 v[238:241], v[248:249], off
	s_waitcnt vmcnt(3)
	v_pk_add_f32 v[146:147], v[146:147], v[246:247]
	v_pk_add_f32 v[144:145], v[144:145], v[244:245]
	v_lshl_add_u64 v[248:249], v[248:249], 0, s[76:77]
	global_load_dwordx4 v[244:247], v[248:249], off
	s_waitcnt vmcnt(3)
	v_pk_add_f32 v[146:147], v[146:147], v[192:193]
	v_pk_add_f32 v[144:145], v[144:145], v[190:191]
	v_lshl_add_u64 v[248:249], v[248:249], 0, s[76:77]
	global_load_dwordx4 v[190:193], v[248:249], off
	s_waitcnt vmcnt(3)
	v_pk_add_f32 v[146:147], v[146:147], v[236:237]
	v_pk_add_f32 v[144:145], v[144:145], v[234:235]
	s_waitcnt vmcnt(2)
	v_pk_add_f32 v[146:147], v[146:147], v[240:241]
	v_pk_add_f32 v[144:145], v[144:145], v[238:239]
	s_waitcnt vmcnt(1)
	v_pk_add_f32 v[146:147], v[146:147], v[246:247]
	v_pk_add_f32 v[144:145], v[144:145], v[244:245]
	s_waitcnt vmcnt(0)
	v_pk_add_f32 v[146:147], v[146:147], v[192:193]
	v_pk_add_f32 v[144:145], v[144:145], v[190:191]
	s_mov_b32 s10, 0
	v_lshl_add_u64 v[182:183], v[248:249], 0, s[76:77]
	s_branch .Lln1_done_8
.LBB0_1213:
	global_load_dwordx4 v[190:193], v[182:183], off
	s_add_i32 s10, s10, -1
	v_lshl_add_u64 v[182:183], v[182:183], 0, s[76:77]
	s_cmp_lg_u32 s10, 0
	s_waitcnt vmcnt(0)
	v_pk_add_f32 v[146:147], v[146:147], v[192:193]
	v_pk_add_f32 v[144:145], v[144:145], v[190:191]
	s_cbranch_scc1 .LBB0_1213
.Lln1_done_8:
	s_branch .LBB0_1161
.LBB0_1214:
	s_or_b64 exec, exec, s[12:13]
	s_waitcnt vmcnt(0)
	s_barrier
	s_mov_b64 s[6:7], exec
	v_readlane_b32 s8, v253, 12
	v_readlane_b32 s9, v253, 13
	s_and_b64 s[8:9], s[6:7], s[8:9]
	s_mov_b64 exec, s[8:9]
	s_cbranch_execz .LBB0_1232
	s_mov_b64 s[8:9], exec
	v_mbcnt_lo_u32_b32 v0, s8, 0
	v_mbcnt_hi_u32_b32 v0, s9, v0
	s_waitcnt vmcnt(0) expcnt(0) lgkmcnt(0)
	s_getreg_b32 s10, hwreg(HW_REG_XCC_ID, 0, 4)
	v_cmp_eq_u32_e32 vcc, 0, v0
	s_and_saveexec_b64 s[12:13], vcc
	s_cbranch_execz .LBB0_1217
	s_lshl_b32 s10, s10, 8
	s_and_b32 s10, s10, 0xf00
	v_readlane_b32 s14, v252, 40
	v_readlane_b32 s15, v252, 41
	s_add_u32 s10, s14, s10
	s_addc_u32 s11, s15, 0
	s_bcnt1_i32_b64 s8, s[8:9]
	v_mov_b32_e32 v1, s8
	global_atomic_add v1, v221, v1, s[10:11] sc0

; __device__ __forceinline__ void ln_rows(const Params& P, const float* gam, const float* bet, const float* modU, int shidx, bool writeU, bool writeOut, int nsplit, bool skipctx) {
;     ...
;         for (int j = 0; j < 8; ++j) { const int c = ((j >> 1) * 64 + lane) * 8 + (j & 1) * 4;
;             if (!pf) {
;                 f32x4 a = *(const f32x4*)(X + (size_t)r * D + c) * ALPHA; const float* pp = (const float*)(P.ws + WS_SCTX) + ((size_t)b * 256 + p) * D + c;
;                 for (int q = 0; q < nsplit; ++q) a += *(const f32x4*)(pp + (size_t)q * 512 * D);
;                 v[j] = a; }
.LBB0_1410:
	s_or_b64 exec, exec, s[4:5]
	s_and_saveexec_b64 s[4:5], s[18:19]
	s_xor_b64 s[4:5], exec, s[4:5]
	v_lshlrev_b32_e32 v116, 16, v163
	v_and_b32_e32 v117, 0xffff0000, v163
	v_lshlrev_b32_e32 v118, 16, v162
	v_and_b32_e32 v119, 0xffff0000, v162
	v_pk_fma_f32 v[118:119], v[122:123], s[46:47], v[118:119] op_sel_hi:[1,0,1]
	v_pk_fma_f32 v[116:117], v[120:121], s[46:47], v[116:117] op_sel_hi:[1,0,1]
	s_or_saveexec_b64 s[6:7], s[4:5]
	v_mul_hi_i32 v1, v164, s78
	v_lshrrev_b32_e32 v120, 31, v1
	v_ashrrev_i32_e32 v1, 11, v1
	v_add_u32_e32 v168, v1, v120
	s_movk_i32 s4, 0xef00
	v_ashrrev_i32_e32 v165, 31, v164
	v_mad_i32_i24 v166, v168, s4, v164
	v_lshlrev_b64 v[120:121], 13, v[164:165]
	v_ashrrev_i32_e32 v169, 31, v168
	v_lshl_add_u64 v[162:163], s[26:27], 0, v[120:121]
	v_ashrrev_i32_e32 v167, 31, v166
	v_lshlrev_b64 v[120:121], 21, v[168:169]
	v_lshl_add_u64 v[120:121], s[28:29], 0, v[120:121]
	v_lshlrev_b64 v[122:123], 13, v[166:167]
	v_cndmask_b32_e64 v1, 0, 1, s[70:71]
	v_lshl_add_u64 v[174:175], v[120:121], 0, v[122:123]
	v_cmp_ne_u32_e64 s[4:5], 1, v1
	s_xor_b64 exec, exec, s[6:7]
	s_cbranch_execz .LBB0_1415
	v_lshl_add_u64 v[116:117], v[162:163], 0, v[2:3]
	global_load_dwordx4 v[116:119], v[116:117], off
	s_and_b64 vcc, exec, s[4:5]
	s_waitcnt vmcnt(0)
	v_pk_mul_f32 v[116:117], v[116:117], s[46:47] op_sel_hi:[1,0]
	v_pk_mul_f32 v[118:119], v[118:119], s[46:47] op_sel_hi:[1,0]
	s_cbranch_vccnz .LBB0_1415
	v_lshl_add_u64 v[120:121], v[174:175], 0, v[2:3]
	global_load_dwordx4 v[202:205], v[120:121], off
	v_add_co_u32_e32 v248, vcc, 0x400000, v120
	s_nop 1
	v_addc_co_u32_e32 v249, vcc, 0, v121, vcc
	global_load_dwordx4 v[206:209], v[248:249], off
	v_add_co_u32_e32 v248, vcc, 0x800000, v120
	s_nop 1
	v_addc_co_u32_e32 v249, vcc, 0, v121, vcc
	global_load_dwordx4 v[210:213], v[248:249], off
	v_add_co_u32_e32 v248, vcc, 0xc00000, v120
	s_nop 1
	v_addc_co_u32_e32 v249, vcc, 0, v121, vcc
	global_load_dwordx4 v[214:217], v[248:249], off
	v_add_co_u32_e32 v248, vcc, 0x1000000, v120
	s_nop 1
	v_addc_co_u32_e32 v249, vcc, 0, v121, vcc
	global_load_dwordx4 v[234:237], v[248:249], off
	v_add_co_u32_e32 v248, vcc, 0x1400000, v120
	s_nop 1
	v_addc_co_u32_e32 v249, vcc, 0, v121, vcc
	global_load_dwordx4 v[238:241], v[248:249], off
	v_add_co_u32_e32 v248, vcc, 0x1800000, v120
	s_nop 1
	v_addc_co_u32_e32 v249, vcc, 0, v121, vcc
	global_load_dwordx4 v[244:247], v[248:249], off
	s_waitcnt vmcnt(6)
	v_pk_add_f32 v[116:117], v[116:117], v[202:203]
	v_pk_add_f32 v[118:119], v[118:119], v[204:205]
	v_add_co_u32_e32 v248, vcc, 0x1c00000, v120
	s_nop 1
	v_addc_co_u32_e32 v249, vcc, 0, v121, vcc
	global_load_dwordx4 v[202:205], v[248:249], off
	s_waitcnt vmcnt(6)
	v_pk_add_f32 v[116:117], v[116:117], v[206:207]
	v_pk_add_f32 v[118:119], v[118:119], v[208:209]
	v_add_co_u32_e32 v248, vcc, 0x2000000, v120
	s_nop 1
	v_addc_co_u32_e32 v249, vcc, 0, v121, vcc
	global_load_dwordx4 v[206:209], v[248:249], off
	s_waitcnt vmcnt(6)
	v_pk_add_f32 v[116:117], v[116:117], v[210:211]
	v_pk_add_f32 v[118:119], v[118:119], v[212:213]
	v_add_co_u32_e32 v248, vcc, 0x2400000, v120
	s_nop 1
	v_addc_co_u32_e32 v249, vcc, 0, v121, vcc
	global_load_dwordx4 v[210:213], v[248:249], off
	s_waitcnt vmcnt(6)
	v_pk_add_f32 v[116:117], v[116:117], v[214:215]
	v_pk_add_f32 v[118:119], v[118:119], v[216:217]
	v_add_co_u32_e32 v248, vcc, 0x2800000, v120
	s_nop 1
	v_addc_co_u32_e32 v249, vcc, 0, v121, vcc
	global_load_dwordx4 v[214:217], v[248:249], off
	s_waitcnt vmcnt(6)
	v_pk_add_f32 v[116:117], v[116:117], v[234:235]
	v_pk_add_f32 v[118:119], v[118:119], v[236:237]
	v_add_co_u32_e32 v248, vcc, 0x2c00000, v120
	s_nop 1
	v_addc_co_u32_e32 v249, vcc, 0, v121, vcc
	global_load_dwordx4 v[234:237], v[248:249], off
	s_waitcnt vmcnt(6)
	v_pk_add_f32 v[116:117], v[116:117], v[238:239]
	v_pk_add_f32 v[118:119], v[118:119], v[240:241]
	v_add_co_u32_e32 v248, vcc, 0x3000000, v120
	s_nop 1
	v_addc_co_u32_e32 v249, vcc, 0, v121, vcc
	global_load_dwordx4 v[238:241], v[248:249], off
	s_waitcnt vmcnt(6)
	v_pk_add_f32 v[116:117], v[116:117], v[244:245]
	v_pk_add_f32 v[118:119], v[118:119], v[246:247]
	v_add_co_u32_e32 v248, vcc, 0x3400000, v120
	s_nop 1
	v_addc_co_u32_e32 v249, vcc, 0, v121, vcc
	global_load_dwordx4 v[244:247], v[248:249], off
	s_waitcnt vmcnt(6)
	v_pk_add_f32 v[116:117], v[116:117], v[202:203]
	v_pk_add_f32 v[118:119], v[118:119], v[204:205]
	v_add_co_u32_e32 v248, vcc, 0x3800000, v120
	s_nop 1
	v_addc_co_u32_e32 v249, vcc, 0, v121, vcc
	global_load_dwordx4 v[202:205], v[248:249], off
	s_waitcnt vmcnt(6)
	v_pk_add_f32 v[116:117], v[116:117], v[206:207]
	v_pk_add_f32 v[118:119], v[118:119], v[208:209]
	v_add_co_u32_e32 v248, vcc, 0x3c00000, v120
	s_nop 1
	v_addc_co_u32_e32 v249, vcc, 0, v121, vcc
	global_load_dwordx4 v[206:209], v[248:249], off
	s_waitcnt vmcnt(6)
	v_pk_add_f32 v[116:117], v[116:117], v[210:211]
	v_pk_add_f32 v[118:119], v[118:119], v[212:213]
	s_waitcnt vmcnt(5)
	v_pk_add_f32 v[116:117], v[116:117], v[214:215]
	v_pk_add_f32 v[118:119], v[118:119], v[216:217]
	s_waitcnt vmcnt(4)
	v_pk_add_f32 v[116:117], v[116:117], v[234:235]
	v_pk_add_f32 v[118:119], v[118:119], v[236:237]
	s_waitcnt vmcnt(3)
	v_pk_add_f32 v[116:117], v[116:117], v[238:239]
	v_pk_add_f32 v[118:119], v[118:119], v[240:241]
	s_waitcnt vmcnt(2)
	v_pk_add_f32 v[116:117], v[116:117], v[244:245]
	v_pk_add_f32 v[118:119], v[118:119], v[246:247]
	s_waitcnt vmcnt(1)
	v_pk_add_f32 v[116:117], v[116:117], v[202:203]
	v_pk_add_f32 v[118:119], v[118:119], v[204:205]
	s_waitcnt vmcnt(0)
	v_pk_add_f32 v[116:117], v[116:117], v[206:207]
	v_pk_add_f32 v[118:119], v[118:119], v[208:209]
	s_mov_b32 s20, 0x1400000
	s_mov_b32 s20, 0x1c00000
	s_mov_b32 s20, 0x3000000
	s_mov_b32 s20, 0x3400000
	s_mov_b32 s20, 0x3800000
; __device__ __forceinline__ void ln_rows(const Params& P, const float* gam, const float* bet, const float* modU, int shidx, bool writeU, bool writeOut, int nsplit, bool skipctx) {
;     ...
;         for (int j = 0; j < 8; ++j) { const int c = ((j >> 1) * 64 + lane) * 8 + (j & 1) * 4;
;             if (!pf) {
;                 f32x4 a = *(const f32x4*)(X + (size_t)r * D + c) * ALPHA; const float* pp = (const float*)(P.ws + WS_SCTX) + ((size_t)b * 256 + p) * D + c;
;                 for (int q = 0; q < nsplit; ++q) a += *(const f32x4*)(pp + (size_t)q * 512 * D);
;                 v[j] = a; }
.LBB0_1415:
	s_or_b64 exec, exec, s[6:7]
	s_and_saveexec_b64 s[6:7], s[18:19]
	s_xor_b64 s[6:7], exec, s[6:7]
	v_lshlrev_b32_e32 v120, 16, v185
	v_and_b32_e32 v121, 0xffff0000, v185
	v_lshlrev_b32_e32 v122, 16, v184
	v_and_b32_e32 v123, 0xffff0000, v184
	v_pk_fma_f32 v[122:123], v[126:127], s[46:47], v[122:123] op_sel_hi:[1,0,1]
	v_pk_fma_f32 v[120:121], v[124:125], s[46:47], v[120:121] op_sel_hi:[1,0,1]
	s_andn2_saveexec_b64 s[6:7], s[6:7]
	s_cbranch_execz .LBB0_1420
	v_lshl_add_u64 v[120:121], v[162:163], 0, v[2:3]
	global_load_dwordx4 v[120:123], v[120:121], off offset:16
	s_and_b64 vcc, exec, s[4:5]
	s_waitcnt vmcnt(0)
	v_pk_mul_f32 v[120:121], v[120:121], s[46:47] op_sel_hi:[1,0]
	v_pk_mul_f32 v[122:123], v[122:123], s[46:47] op_sel_hi:[1,0]
	s_cbranch_vccnz .LBB0_1420
	v_lshl_add_u64 v[124:125], v[174:175], 0, v[2:3]
	global_load_dwordx4 v[202:205], v[124:125], off offset:16
	v_add_co_u32_e32 v248, vcc, 0x400000, v124
	s_nop 1
	v_addc_co_u32_e32 v249, vcc, 0, v125, vcc
	global_load_dwordx4 v[206:209], v[248:249], off offset:16
	v_add_co_u32_e32 v248, vcc, 0x800000, v124
	s_nop 1
	v_addc_co_u32_e32 v249, vcc, 0, v125, vcc
	global_load_dwordx4 v[210:213], v[248:249], off offset:16
	v_add_co_u32_e32 v248, vcc, 0xc00000, v124
	s_nop 1
	v_addc_co_u32_e32 v249, vcc, 0, v125, vcc
	global_load_dwordx4 v[214:217], v[248:249], off offset:16
	v_add_co_u32_e32 v248, vcc, 0x1000000, v124
	s_nop 1
	v_addc_co_u32_e32 v249, vcc, 0, v125, vcc
	global_load_dwordx4 v[234:237], v[248:249], off offset:16
	v_add_co_u32_e32 v248, vcc, 0x1400000, v124
	s_nop 1
	v_addc_co_u32_e32 v249, vcc, 0, v125, vcc
	global_load_dwordx4 v[238:241], v[248:249], off offset:16
	v_add_co_u32_e32 v248, vcc, 0x1800000, v124
	s_nop 1
	v_addc_co_u32_e32 v249, vcc, 0, v125, vcc
	global_load_dwordx4 v[244:247], v[248:249], off offset:16
	s_waitcnt vmcnt(6)
	v_pk_add_f32 v[120:121], v[120:121], v[202:203]
	v_pk_add_f32 v[122:123], v[122:123], v[204:205]
	v_add_co_u32_e32 v248, vcc, 0x1c00000, v124
	s_nop 1
	v_addc_co_u32_e32 v249, vcc, 0, v125, vcc
	global_load_dwordx4 v[202:205], v[248:249], off offset:16
	s_waitcnt vmcnt(6)
	v_pk_add_f32 v[120:121], v[120:121], v[206:207]
	v_pk_add_f32 v[122:123], v[122:123], v[208:209]
	v_add_co_u32_e32 v248, vcc, 0x2000000, v124
	s_nop 1
	v_addc_co_u32_e32 v249, vcc, 0, v125, vcc
	global_load_dwordx4 v[206:209], v[248:249], off offset:16
	s_waitcnt vmcnt(6)
	v_pk_add_f32 v[120:121], v[120:121], v[210:211]
	v_pk_add_f32 v[122:123], v[122:123], v[212:213]
	v_add_co_u32_e32 v248, vcc, 0x2400000, v124
	s_nop 1
	v_addc_co_u32_e32 v249, vcc, 0, v125, vcc
	global_load_dwordx4 v[210:213], v[248:249], off offset:16
	s_waitcnt vmcnt(6)
	v_pk_add_f32 v[120:121], v[120:121], v[214:215]
	v_pk_add_f32 v[122:123], v[122:123], v[216:217]
	v_add_co_u32_e32 v248, vcc, 0x2800000, v124
	s_nop 1
	v_addc_co_u32_e32 v249, vcc, 0, v125, vcc
	global_load_dwordx4 v[214:217], v[248:249], off offset:16
	s_waitcnt vmcnt(6)
	v_pk_add_f32 v[120:121], v[120:121], v[234:235]
	v_pk_add_f32 v[122:123], v[122:123], v[236:237]
	v_add_co_u32_e32 v248, vcc, 0x2c00000, v124
	s_nop 1
	v_addc_co_u32_e32 v249, vcc, 0, v125, vcc
	global_load_dwordx4 v[234:237], v[248:249], off offset:16
	s_waitcnt vmcnt(6)
	v_pk_add_f32 v[120:121], v[120:121], v[238:239]
	v_pk_add_f32 v[122:123], v[122:123], v[240:241]
	v_add_co_u32_e32 v248, vcc, 0x3000000, v124
	s_nop 1
	v_addc_co_u32_e32 v249, vcc, 0, v125, vcc
	global_load_dwordx4 v[238:241], v[248:249], off offset:16
	s_waitcnt vmcnt(6)
	v_pk_add_f32 v[120:121], v[120:121], v[244:245]
	v_pk_add_f32 v[122:123], v[122:123], v[246:247]
	v_add_co_u32_e32 v248, vcc, 0x3400000, v124
	s_nop 1
	v_addc_co_u32_e32 v249, vcc, 0, v125, vcc
	global_load_dwordx4 v[244:247], v[248:249], off offset:16
	s_waitcnt vmcnt(6)
	v_pk_add_f32 v[120:121], v[120:121], v[202:203]
	v_pk_add_f32 v[122:123], v[122:123], v[204:205]
	v_add_co_u32_e32 v248, vcc, 0x3800000, v124
	s_nop 1
	v_addc_co_u32_e32 v249, vcc, 0, v125, vcc
	global_load_dwordx4 v[202:205], v[248:249], off offset:16
	s_waitcnt vmcnt(6)
	v_pk_add_f32 v[120:121], v[120:121], v[206:207]
	v_pk_add_f32 v[122:123], v[122:123], v[208:209]
	v_add_co_u32_e32 v248, vcc, 0x3c00000, v124
	s_nop 1
	v_addc_co_u32_e32 v249, vcc, 0, v125, vcc
	global_load_dwordx4 v[206:209], v[248:249], off offset:16
	s_waitcnt vmcnt(6)
	v_pk_add_f32 v[120:121], v[120:121], v[210:211]
	v_pk_add_f32 v[122:123], v[122:123], v[212:213]
	s_waitcnt vmcnt(5)
	v_pk_add_f32 v[120:121], v[120:121], v[214:215]
	v_pk_add_f32 v[122:123], v[122:123], v[216:217]
	s_waitcnt vmcnt(4)
	v_pk_add_f32 v[120:121], v[120:121], v[234:235]
	v_pk_add_f32 v[122:123], v[122:123], v[236:237]
	s_waitcnt vmcnt(3)
	v_pk_add_f32 v[120:121], v[120:121], v[238:239]
	v_pk_add_f32 v[122:123], v[122:123], v[240:241]
	s_waitcnt vmcnt(2)
	v_pk_add_f32 v[120:121], v[120:121], v[244:245]
	v_pk_add_f32 v[122:123], v[122:123], v[246:247]
	s_waitcnt vmcnt(1)
	v_pk_add_f32 v[120:121], v[120:121], v[202:203]
	v_pk_add_f32 v[122:123], v[122:123], v[204:205]
	s_waitcnt vmcnt(0)
	v_pk_add_f32 v[120:121], v[120:121], v[206:207]
	v_pk_add_f32 v[122:123], v[122:123], v[208:209]
	s_mov_b32 s20, 0x1400000
	s_mov_b32 s20, 0x1c00000
	s_mov_b32 s20, 0x3000000
	s_mov_b32 s20, 0x3400000
	s_mov_b32 s20, 0x3800000
; __device__ __forceinline__ void ln_rows(const Params& P, const float* gam, const float* bet, const float* modU, int shidx, bool writeU, bool writeOut, int nsplit, bool skipctx) {
;     ...
;         for (int j = 0; j < 8; ++j) { const int c = ((j >> 1) * 64 + lane) * 8 + (j & 1) * 4;
;             if (!pf) {
;                 f32x4 a = *(const f32x4*)(X + (size_t)r * D + c) * ALPHA; const float* pp = (const float*)(P.ws + WS_SCTX) + ((size_t)b * 256 + p) * D + c;
;                 for (int q = 0; q < nsplit; ++q) a += *(const f32x4*)(pp + (size_t)q * 512 * D);
;                 v[j] = a; }
.LBB0_1420:
	s_or_b64 exec, exec, s[6:7]
	s_and_saveexec_b64 s[6:7], s[18:19]
	s_xor_b64 s[6:7], exec, s[6:7]
	v_lshlrev_b32_e32 v124, 16, v183
	v_and_b32_e32 v125, 0xffff0000, v183
	v_lshlrev_b32_e32 v126, 16, v182
	v_and_b32_e32 v127, 0xffff0000, v182
	v_pk_fma_f32 v[126:127], v[130:131], s[46:47], v[126:127] op_sel_hi:[1,0,1]
	v_pk_fma_f32 v[124:125], v[128:129], s[46:47], v[124:125] op_sel_hi:[1,0,1]
	s_andn2_saveexec_b64 s[6:7], s[6:7]
	s_cbranch_execz .LBB0_1425
	v_lshl_add_u64 v[124:125], v[162:163], 0, v[2:3]
	global_load_dwordx4 v[124:127], v[124:125], off offset:2048
	s_and_b64 vcc, exec, s[4:5]
	s_waitcnt vmcnt(0)
	v_pk_mul_f32 v[124:125], v[124:125], s[46:47] op_sel_hi:[1,0]
	v_pk_mul_f32 v[126:127], v[126:127], s[46:47] op_sel_hi:[1,0]
	s_cbranch_vccnz .LBB0_1425
	v_lshl_add_u64 v[128:129], v[174:175], 0, v[2:3]
	global_load_dwordx4 v[202:205], v[128:129], off offset:2048
	v_add_co_u32_e32 v248, vcc, 0x400000, v128
	s_nop 1
	v_addc_co_u32_e32 v249, vcc, 0, v129, vcc
	global_load_dwordx4 v[206:209], v[248:249], off offset:2048
	v_add_co_u32_e32 v248, vcc, 0x800000, v128
	s_nop 1
	v_addc_co_u32_e32 v249, vcc, 0, v129, vcc
	global_load_dwordx4 v[210:213], v[248:249], off offset:2048
	v_add_co_u32_e32 v248, vcc, 0xc00000, v128
	s_nop 1
	v_addc_co_u32_e32 v249, vcc, 0, v129, vcc
	global_load_dwordx4 v[214:217], v[248:249], off offset:2048
	v_add_co_u32_e32 v248, vcc, 0x1000000, v128
	s_nop 1
	v_addc_co_u32_e32 v249, vcc, 0, v129, vcc
	global_load_dwordx4 v[234:237], v[248:249], off offset:2048
	v_add_co_u32_e32 v248, vcc, 0x1400000, v128
	s_nop 1
	v_addc_co_u32_e32 v249, vcc, 0, v129, vcc
	global_load_dwordx4 v[238:241], v[248:249], off offset:2048
	v_add_co_u32_e32 v248, vcc, 0x1800000, v128
	s_nop 1
	v_addc_co_u32_e32 v249, vcc, 0, v129, vcc
	global_load_dwordx4 v[244:247], v[248:249], off offset:2048
	s_waitcnt vmcnt(6)
	v_pk_add_f32 v[124:125], v[124:125], v[202:203]
	v_pk_add_f32 v[126:127], v[126:127], v[204:205]
	v_add_co_u32_e32 v248, vcc, 0x1c00000, v128
	s_nop 1
	v_addc_co_u32_e32 v249, vcc, 0, v129, vcc
	global_load_dwordx4 v[202:205], v[248:249], off offset:2048
	s_waitcnt vmcnt(6)
	v_pk_add_f32 v[124:125], v[124:125], v[206:207]
	v_pk_add_f32 v[126:127], v[126:127], v[208:209]
	v_add_co_u32_e32 v248, vcc, 0x2000000, v128
	s_nop 1
	v_addc_co_u32_e32 v249, vcc, 0, v129, vcc
	global_load_dwordx4 v[206:209], v[248:249], off offset:2048
	s_waitcnt vmcnt(6)
	v_pk_add_f32 v[124:125], v[124:125], v[210:211]
	v_pk_add_f32 v[126:127], v[126:127], v[212:213]
	v_add_co_u32_e32 v248, vcc, 0x2400000, v128
	s_nop 1
	v_addc_co_u32_e32 v249, vcc, 0, v129, vcc
	global_load_dwordx4 v[210:213], v[248:249], off offset:2048
	s_waitcnt vmcnt(6)
	v_pk_add_f32 v[124:125], v[124:125], v[214:215]
	v_pk_add_f32 v[126:127], v[126:127], v[216:217]
	v_add_co_u32_e32 v248, vcc, 0x2800000, v128
	s_nop 1
	v_addc_co_u32_e32 v249, vcc, 0, v129, vcc
	global_load_dwordx4 v[214:217], v[248:249], off offset:2048
	s_waitcnt vmcnt(6)
	v_pk_add_f32 v[124:125], v[124:125], v[234:235]
	v_pk_add_f32 v[126:127], v[126:127], v[236:237]
	v_add_co_u32_e32 v248, vcc, 0x2c00000, v128
	s_nop 1
	v_addc_co_u32_e32 v249, vcc, 0, v129, vcc
	global_load_dwordx4 v[234:237], v[248:249], off offset:2048
	s_waitcnt vmcnt(6)
	v_pk_add_f32 v[124:125], v[124:125], v[238:239]
	v_pk_add_f32 v[126:127], v[126:127], v[240:241]
	v_add_co_u32_e32 v248, vcc, 0x3000000, v128
	s_nop 1
	v_addc_co_u32_e32 v249, vcc, 0, v129, vcc
	global_load_dwordx4 v[238:241], v[248:249], off offset:2048
	s_waitcnt vmcnt(6)
	v_pk_add_f32 v[124:125], v[124:125], v[244:245]
	v_pk_add_f32 v[126:127], v[126:127], v[246:247]
	v_add_co_u32_e32 v248, vcc, 0x3400000, v128
	s_nop 1
	v_addc_co_u32_e32 v249, vcc, 0, v129, vcc
	global_load_dwordx4 v[244:247], v[248:249], off offset:2048
	s_waitcnt vmcnt(6)
	v_pk_add_f32 v[124:125], v[124:125], v[202:203]
	v_pk_add_f32 v[126:127], v[126:127], v[204:205]
	v_add_co_u32_e32 v248, vcc, 0x3800000, v128
	s_nop 1
	v_addc_co_u32_e32 v249, vcc, 0, v129, vcc
	global_load_dwordx4 v[202:205], v[248:249], off offset:2048
	s_waitcnt vmcnt(6)
	v_pk_add_f32 v[124:125], v[124:125], v[206:207]
	v_pk_add_f32 v[126:127], v[126:127], v[208:209]
	v_add_co_u32_e32 v248, vcc, 0x3c00000, v128
	s_nop 1
	v_addc_co_u32_e32 v249, vcc, 0, v129, vcc
	global_load_dwordx4 v[206:209], v[248:249], off offset:2048
	s_waitcnt vmcnt(6)
	v_pk_add_f32 v[124:125], v[124:125], v[210:211]
	v_pk_add_f32 v[126:127], v[126:127], v[212:213]
	s_waitcnt vmcnt(5)
	v_pk_add_f32 v[124:125], v[124:125], v[214:215]
	v_pk_add_f32 v[126:127], v[126:127], v[216:217]
	s_waitcnt vmcnt(4)
	v_pk_add_f32 v[124:125], v[124:125], v[234:235]
	v_pk_add_f32 v[126:127], v[126:127], v[236:237]
	s_waitcnt vmcnt(3)
	v_pk_add_f32 v[124:125], v[124:125], v[238:239]
	v_pk_add_f32 v[126:127], v[126:127], v[240:241]
	s_waitcnt vmcnt(2)
	v_pk_add_f32 v[124:125], v[124:125], v[244:245]
	v_pk_add_f32 v[126:127], v[126:127], v[246:247]
	s_waitcnt vmcnt(1)
	v_pk_add_f32 v[124:125], v[124:125], v[202:203]
	v_pk_add_f32 v[126:127], v[126:127], v[204:205]
	s_waitcnt vmcnt(0)
	v_pk_add_f32 v[124:125], v[124:125], v[206:207]
	v_pk_add_f32 v[126:127], v[126:127], v[208:209]
	s_mov_b32 s20, 0x1400000
	s_mov_b32 s20, 0x1c00000
	s_mov_b32 s20, 0x3000000
	s_mov_b32 s20, 0x3400000
	s_mov_b32 s20, 0x3800000
; __device__ __forceinline__ void ln_rows(const Params& P, const float* gam, const float* bet, const float* modU, int shidx, bool writeU, bool writeOut, int nsplit, bool skipctx) {
;     ...
;         for (int j = 0; j < 8; ++j) { const int c = ((j >> 1) * 64 + lane) * 8 + (j & 1) * 4;
;             if (!pf) {
;                 f32x4 a = *(const f32x4*)(X + (size_t)r * D + c) * ALPHA; const float* pp = (const float*)(P.ws + WS_SCTX) + ((size_t)b * 256 + p) * D + c;
;                 for (int q = 0; q < nsplit; ++q) a += *(const f32x4*)(pp + (size_t)q * 512 * D);
;                 v[j] = a; }
.LBB0_1425:
	s_or_b64 exec, exec, s[6:7]
	s_and_saveexec_b64 s[6:7], s[18:19]
	s_xor_b64 s[6:7], exec, s[6:7]
	v_lshlrev_b32_e32 v128, 16, v181
	v_and_b32_e32 v129, 0xffff0000, v181
	v_lshlrev_b32_e32 v130, 16, v180
	v_and_b32_e32 v131, 0xffff0000, v180
	v_pk_fma_f32 v[130:131], v[134:135], s[46:47], v[130:131] op_sel_hi:[1,0,1]
	v_pk_fma_f32 v[128:129], v[132:133], s[46:47], v[128:129] op_sel_hi:[1,0,1]
	s_andn2_saveexec_b64 s[6:7], s[6:7]
	s_cbranch_execz .LBB0_1430
	v_lshl_add_u64 v[128:129], v[162:163], 0, v[2:3]
	global_load_dwordx4 v[128:131], v[128:129], off offset:2064
	s_and_b64 vcc, exec, s[4:5]
	s_waitcnt vmcnt(0)
	v_pk_mul_f32 v[128:129], v[128:129], s[46:47] op_sel_hi:[1,0]
	v_pk_mul_f32 v[130:131], v[130:131], s[46:47] op_sel_hi:[1,0]
	s_cbranch_vccnz .LBB0_1430
	v_lshl_add_u64 v[132:133], v[174:175], 0, v[2:3]
	global_load_dwordx4 v[202:205], v[132:133], off offset:2064
	v_add_co_u32_e32 v248, vcc, 0x400000, v132
	s_nop 1
	v_addc_co_u32_e32 v249, vcc, 0, v133, vcc
	global_load_dwordx4 v[206:209], v[248:249], off offset:2064
	v_add_co_u32_e32 v248, vcc, 0x800000, v132
	s_nop 1
	v_addc_co_u32_e32 v249, vcc, 0, v133, vcc
	global_load_dwordx4 v[210:213], v[248:249], off offset:2064
	v_add_co_u32_e32 v248, vcc, 0xc00000, v132
	s_nop 1
	v_addc_co_u32_e32 v249, vcc, 0, v133, vcc
	global_load_dwordx4 v[214:217], v[248:249], off offset:2064
	v_add_co_u32_e32 v248, vcc, 0x1000000, v132
	s_nop 1
	v_addc_co_u32_e32 v249, vcc, 0, v133, vcc
	global_load_dwordx4 v[234:237], v[248:249], off offset:2064
	v_add_co_u32_e32 v248, vcc, 0x1400000, v132
	s_nop 1
	v_addc_co_u32_e32 v249, vcc, 0, v133, vcc
	global_load_dwordx4 v[238:241], v[248:249], off offset:2064
	v_add_co_u32_e32 v248, vcc, 0x1800000, v132
	s_nop 1
	v_addc_co_u32_e32 v249, vcc, 0, v133, vcc
	global_load_dwordx4 v[244:247], v[248:249], off offset:2064
	s_waitcnt vmcnt(6)
	v_pk_add_f32 v[128:129], v[128:129], v[202:203]
	v_pk_add_f32 v[130:131], v[130:131], v[204:205]
	v_add_co_u32_e32 v248, vcc, 0x1c00000, v132
	s_nop 1
	v_addc_co_u32_e32 v249, vcc, 0, v133, vcc
	global_load_dwordx4 v[202:205], v[248:249], off offset:2064
	s_waitcnt vmcnt(6)
	v_pk_add_f32 v[128:129], v[128:129], v[206:207]
	v_pk_add_f32 v[130:131], v[130:131], v[208:209]
	v_add_co_u32_e32 v248, vcc, 0x2000000, v132
	s_nop 1
	v_addc_co_u32_e32 v249, vcc, 0, v133, vcc
	global_load_dwordx4 v[206:209], v[248:249], off offset:2064
	s_waitcnt vmcnt(6)
	v_pk_add_f32 v[128:129], v[128:129], v[210:211]
	v_pk_add_f32 v[130:131], v[130:131], v[212:213]
	v_add_co_u32_e32 v248, vcc, 0x2400000, v132
	s_nop 1
	v_addc_co_u32_e32 v249, vcc, 0, v133, vcc
	global_load_dwordx4 v[210:213], v[248:249], off offset:2064
	s_waitcnt vmcnt(6)
	v_pk_add_f32 v[128:129], v[128:129], v[214:215]
	v_pk_add_f32 v[130:131], v[130:131], v[216:217]
	v_add_co_u32_e32 v248, vcc, 0x2800000, v132
	s_nop 1
	v_addc_co_u32_e32 v249, vcc, 0, v133, vcc
	global_load_dwordx4 v[214:217], v[248:249], off offset:2064
	s_waitcnt vmcnt(6)
	v_pk_add_f32 v[128:129], v[128:129], v[234:235]
	v_pk_add_f32 v[130:131], v[130:131], v[236:237]
	v_add_co_u32_e32 v248, vcc, 0x2c00000, v132
	s_nop 1
	v_addc_co_u32_e32 v249, vcc, 0, v133, vcc
	global_load_dwordx4 v[234:237], v[248:249], off offset:2064
	s_waitcnt vmcnt(6)
	v_pk_add_f32 v[128:129], v[128:129], v[238:239]
	v_pk_add_f32 v[130:131], v[130:131], v[240:241]
	v_add_co_u32_e32 v248, vcc, 0x3000000, v132
	s_nop 1
	v_addc_co_u32_e32 v249, vcc, 0, v133, vcc
	global_load_dwordx4 v[238:241], v[248:249], off offset:2064
	s_waitcnt vmcnt(6)
	v_pk_add_f32 v[128:129], v[128:129], v[244:245]
	v_pk_add_f32 v[130:131], v[130:131], v[246:247]
	v_add_co_u32_e32 v248, vcc, 0x3400000, v132
	s_nop 1
	v_addc_co_u32_e32 v249, vcc, 0, v133, vcc
	global_load_dwordx4 v[244:247], v[248:249], off offset:2064
	s_waitcnt vmcnt(6)
	v_pk_add_f32 v[128:129], v[128:129], v[202:203]
	v_pk_add_f32 v[130:131], v[130:131], v[204:205]
	v_add_co_u32_e32 v248, vcc, 0x3800000, v132
	s_nop 1
	v_addc_co_u32_e32 v249, vcc, 0, v133, vcc
	global_load_dwordx4 v[202:205], v[248:249], off offset:2064
	s_waitcnt vmcnt(6)
	v_pk_add_f32 v[128:129], v[128:129], v[206:207]
	v_pk_add_f32 v[130:131], v[130:131], v[208:209]
	v_add_co_u32_e32 v248, vcc, 0x3c00000, v132
	s_nop 1
	v_addc_co_u32_e32 v249, vcc, 0, v133, vcc
	global_load_dwordx4 v[206:209], v[248:249], off offset:2064
	s_waitcnt vmcnt(6)
	v_pk_add_f32 v[128:129], v[128:129], v[210:211]
	v_pk_add_f32 v[130:131], v[130:131], v[212:213]
	s_waitcnt vmcnt(5)
	v_pk_add_f32 v[128:129], v[128:129], v[214:215]
	v_pk_add_f32 v[130:131], v[130:131], v[216:217]
	s_waitcnt vmcnt(4)
	v_pk_add_f32 v[128:129], v[128:129], v[234:235]
	v_pk_add_f32 v[130:131], v[130:131], v[236:237]
	s_waitcnt vmcnt(3)
	v_pk_add_f32 v[128:129], v[128:129], v[238:239]
	v_pk_add_f32 v[130:131], v[130:131], v[240:241]
	s_waitcnt vmcnt(2)
	v_pk_add_f32 v[128:129], v[128:129], v[244:245]
	v_pk_add_f32 v[130:131], v[130:131], v[246:247]
	s_waitcnt vmcnt(1)
	v_pk_add_f32 v[128:129], v[128:129], v[202:203]
	v_pk_add_f32 v[130:131], v[130:131], v[204:205]
	s_waitcnt vmcnt(0)
	v_pk_add_f32 v[128:129], v[128:129], v[206:207]
	v_pk_add_f32 v[130:131], v[130:131], v[208:209]
	s_mov_b32 s20, 0x1400000
	s_mov_b32 s20, 0x1c00000
	s_mov_b32 s20, 0x3000000
	s_mov_b32 s20, 0x3400000
	s_mov_b32 s20, 0x3800000
; __device__ __forceinline__ float bflo(unsigned u) { return __uint_as_float(u << 16); }
; __device__ __forceinline__ float bfhi(unsigned u) { return __uint_as_float(u & 0xffff0000u); }
; __device__ __forceinline__ void ln_rows(const Params& P, const float* gam, const float* bet, const float* modU, int shidx, bool writeU, bool writeOut, int nsplit, bool skipctx) {
;     ...
;         for (int j = 0; j < 8; ++j) { const int c = ((j >> 1) * 64 + lane) * 8 + (j & 1) * 4;
;             if (!pf) {
;                 f32x4 a = *(const f32x4*)(X + (size_t)r * D + c) * ALPHA; const float* pp = (const float*)(P.ws + WS_SCTX) + ((size_t)b * 256 + p) * D + c;
;                 for (int q = 0; q < nsplit; ++q) a += *(const f32x4*)(pp + (size_t)q * 512 * D);
;                 v[j] = a; }
;             else { const unsigned t0 = (j & 1) ? ct[j >> 1].z : ct[j >> 1].x, t1 = (j & 1) ? ct[j >> 1].w : ct[j >> 1].y;
;                 v[j] = cx[j] * ALPHA + (f32x4){bflo(t0), bfhi(t0), bflo(t1), bfhi(t1)}; }
.LBB0_1430:
	s_or_b64 exec, exec, s[6:7]
	s_and_saveexec_b64 s[6:7], s[18:19]
	s_xor_b64 s[6:7], exec, s[6:7]
	v_lshlrev_b32_e32 v132, 16, v179
	v_and_b32_e32 v133, 0xffff0000, v179
	v_lshlrev_b32_e32 v134, 16, v178
	v_and_b32_e32 v135, 0xffff0000, v178
	v_pk_fma_f32 v[134:135], v[138:139], s[46:47], v[134:135] op_sel_hi:[1,0,1]
	v_pk_fma_f32 v[132:133], v[136:137], s[46:47], v[132:133] op_sel_hi:[1,0,1]
	s_andn2_saveexec_b64 s[6:7], s[6:7]
	s_cbranch_execz .LBB0_1435
	v_mov_b32_e32 v151, v3
	v_lshl_add_u64 v[132:133], v[162:163], 0, v[150:151]
	global_load_dwordx4 v[132:135], v[132:133], off
	s_and_b64 vcc, exec, s[4:5]
	s_waitcnt vmcnt(0)
	v_pk_mul_f32 v[132:133], v[132:133], s[46:47] op_sel_hi:[1,0]
	v_pk_mul_f32 v[134:135], v[134:135], s[46:47] op_sel_hi:[1,0]
	s_cbranch_vccnz .LBB0_1435
	v_lshl_add_u64 v[136:137], v[174:175], 0, v[150:151]
	global_load_dwordx4 v[202:205], v[136:137], off
	v_add_co_u32_e32 v248, vcc, 0x400000, v136
	s_nop 1
	v_addc_co_u32_e32 v249, vcc, 0, v137, vcc
	global_load_dwordx4 v[206:209], v[248:249], off
	v_add_co_u32_e32 v248, vcc, 0x800000, v136
	s_nop 1
	v_addc_co_u32_e32 v249, vcc, 0, v137, vcc
	global_load_dwordx4 v[210:213], v[248:249], off
	v_add_co_u32_e32 v248, vcc, 0xc00000, v136
	s_nop 1
	v_addc_co_u32_e32 v249, vcc, 0, v137, vcc
	global_load_dwordx4 v[214:217], v[248:249], off
	v_add_co_u32_e32 v248, vcc, 0x1000000, v136
	s_nop 1
	v_addc_co_u32_e32 v249, vcc, 0, v137, vcc
	global_load_dwordx4 v[234:237], v[248:249], off
	v_add_co_u32_e32 v248, vcc, 0x1400000, v136
	s_nop 1
	v_addc_co_u32_e32 v249, vcc, 0, v137, vcc
	global_load_dwordx4 v[238:241], v[248:249], off
	v_add_co_u32_e32 v248, vcc, 0x1800000, v136
	s_nop 1
	v_addc_co_u32_e32 v249, vcc, 0, v137, vcc
	global_load_dwordx4 v[244:247], v[248:249], off
	s_waitcnt vmcnt(6)
	v_pk_add_f32 v[132:133], v[132:133], v[202:203]
	v_pk_add_f32 v[134:135], v[134:135], v[204:205]
	v_add_co_u32_e32 v248, vcc, 0x1c00000, v136
	s_nop 1
	v_addc_co_u32_e32 v249, vcc, 0, v137, vcc
	global_load_dwordx4 v[202:205], v[248:249], off
	s_waitcnt vmcnt(6)
	v_pk_add_f32 v[132:133], v[132:133], v[206:207]
	v_pk_add_f32 v[134:135], v[134:135], v[208:209]
	v_add_co_u32_e32 v248, vcc, 0x2000000, v136
	s_nop 1
	v_addc_co_u32_e32 v249, vcc, 0, v137, vcc
	global_load_dwordx4 v[206:209], v[248:249], off
	s_waitcnt vmcnt(6)
	v_pk_add_f32 v[132:133], v[132:133], v[210:211]
	v_pk_add_f32 v[134:135], v[134:135], v[212:213]
	v_add_co_u32_e32 v248, vcc, 0x2400000, v136
	s_nop 1
	v_addc_co_u32_e32 v249, vcc, 0, v137, vcc
	global_load_dwordx4 v[210:213], v[248:249], off
	s_waitcnt vmcnt(6)
	v_pk_add_f32 v[132:133], v[132:133], v[214:215]
	v_pk_add_f32 v[134:135], v[134:135], v[216:217]
	v_add_co_u32_e32 v248, vcc, 0x2800000, v136
	s_nop 1
	v_addc_co_u32_e32 v249, vcc, 0, v137, vcc
	global_load_dwordx4 v[214:217], v[248:249], off
	s_waitcnt vmcnt(6)
	v_pk_add_f32 v[132:133], v[132:133], v[234:235]
	v_pk_add_f32 v[134:135], v[134:135], v[236:237]
	v_add_co_u32_e32 v248, vcc, 0x2c00000, v136
	s_nop 1
	v_addc_co_u32_e32 v249, vcc, 0, v137, vcc
	global_load_dwordx4 v[234:237], v[248:249], off
	s_waitcnt vmcnt(6)
	v_pk_add_f32 v[132:133], v[132:133], v[238:239]
	v_pk_add_f32 v[134:135], v[134:135], v[240:241]
	v_add_co_u32_e32 v248, vcc, 0x3000000, v136
	s_nop 1
	v_addc_co_u32_e32 v249, vcc, 0, v137, vcc
	global_load_dwordx4 v[238:241], v[248:249], off
	s_waitcnt vmcnt(6)
	v_pk_add_f32 v[132:133], v[132:133], v[244:245]
	v_pk_add_f32 v[134:135], v[134:135], v[246:247]
	v_add_co_u32_e32 v248, vcc, 0x3400000, v136
	s_nop 1
	v_addc_co_u32_e32 v249, vcc, 0, v137, vcc
	global_load_dwordx4 v[244:247], v[248:249], off
	s_waitcnt vmcnt(6)
	v_pk_add_f32 v[132:133], v[132:133], v[202:203]
	v_pk_add_f32 v[134:135], v[134:135], v[204:205]
	v_add_co_u32_e32 v248, vcc, 0x3800000, v136
	s_nop 1
	v_addc_co_u32_e32 v249, vcc, 0, v137, vcc
	global_load_dwordx4 v[202:205], v[248:249], off
	s_waitcnt vmcnt(6)
	v_pk_add_f32 v[132:133], v[132:133], v[206:207]
	v_pk_add_f32 v[134:135], v[134:135], v[208:209]
	v_add_co_u32_e32 v248, vcc, 0x3c00000, v136
	s_nop 1
	v_addc_co_u32_e32 v249, vcc, 0, v137, vcc
	global_load_dwordx4 v[206:209], v[248:249], off
	s_waitcnt vmcnt(6)
	v_pk_add_f32 v[132:133], v[132:133], v[210:211]
	v_pk_add_f32 v[134:135], v[134:135], v[212:213]
	s_waitcnt vmcnt(5)
	v_pk_add_f32 v[132:133], v[132:133], v[214:215]
	v_pk_add_f32 v[134:135], v[134:135], v[216:217]
	s_waitcnt vmcnt(4)
	v_pk_add_f32 v[132:133], v[132:133], v[234:235]
	v_pk_add_f32 v[134:135], v[134:135], v[236:237]
	s_waitcnt vmcnt(3)
	v_pk_add_f32 v[132:133], v[132:133], v[238:239]
	v_pk_add_f32 v[134:135], v[134:135], v[240:241]
	s_waitcnt vmcnt(2)
	v_pk_add_f32 v[132:133], v[132:133], v[244:245]
	v_pk_add_f32 v[134:135], v[134:135], v[246:247]
	s_waitcnt vmcnt(1)
	v_pk_add_f32 v[132:133], v[132:133], v[202:203]
	v_pk_add_f32 v[134:135], v[134:135], v[204:205]
	s_waitcnt vmcnt(0)
	v_pk_add_f32 v[132:133], v[132:133], v[206:207]
	v_pk_add_f32 v[134:135], v[134:135], v[208:209]
	s_mov_b32 s20, 0x1400000
	s_mov_b32 s20, 0x1c00000
	s_mov_b32 s20, 0x3000000
	s_mov_b32 s20, 0x3400000
	s_mov_b32 s20, 0x3800000
; __device__ __forceinline__ float bflo(unsigned u) { return __uint_as_float(u << 16); }
; __device__ __forceinline__ float bfhi(unsigned u) { return __uint_as_float(u & 0xffff0000u); }
; __device__ __forceinline__ void ln_rows(const Params& P, const float* gam, const float* bet, const float* modU, int shidx, bool writeU, bool writeOut, int nsplit, bool skipctx) {
;     ...
;         for (int j = 0; j < 8; ++j) { const int c = ((j >> 1) * 64 + lane) * 8 + (j & 1) * 4;
;             if (!pf) {
;                 f32x4 a = *(const f32x4*)(X + (size_t)r * D + c) * ALPHA; const float* pp = (const float*)(P.ws + WS_SCTX) + ((size_t)b * 256 + p) * D + c;
;                 for (int q = 0; q < nsplit; ++q) a += *(const f32x4*)(pp + (size_t)q * 512 * D);
;                 v[j] = a; }
;             else { const unsigned t0 = (j & 1) ? ct[j >> 1].z : ct[j >> 1].x, t1 = (j & 1) ? ct[j >> 1].w : ct[j >> 1].y;
;                 v[j] = cx[j] * ALPHA + (f32x4){bflo(t0), bfhi(t0), bflo(t1), bfhi(t1)}; }
.LBB0_1435:
	s_or_b64 exec, exec, s[6:7]
	s_and_saveexec_b64 s[6:7], s[18:19]
	s_xor_b64 s[6:7], exec, s[6:7]
	v_lshlrev_b32_e32 v136, 16, v177
	v_and_b32_e32 v137, 0xffff0000, v177
	v_lshlrev_b32_e32 v138, 16, v176
	v_and_b32_e32 v139, 0xffff0000, v176
	v_pk_fma_f32 v[138:139], v[142:143], s[46:47], v[138:139] op_sel_hi:[1,0,1]
	v_pk_fma_f32 v[136:137], v[140:141], s[46:47], v[136:137] op_sel_hi:[1,0,1]
	s_andn2_saveexec_b64 s[6:7], s[6:7]
	s_cbranch_execz .LBB0_1440
	v_lshlrev_b32_e32 v140, 2, v154
	v_mov_b32_e32 v141, v3
	v_lshl_add_u64 v[136:137], v[162:163], 0, v[140:141]
	global_load_dwordx4 v[136:139], v[136:137], off
	s_and_b64 vcc, exec, s[4:5]
	s_waitcnt vmcnt(0)
	v_pk_mul_f32 v[136:137], v[136:137], s[46:47] op_sel_hi:[1,0]
	v_pk_mul_f32 v[138:139], v[138:139], s[46:47] op_sel_hi:[1,0]
	s_cbranch_vccnz .LBB0_1440
	v_lshl_add_u64 v[140:141], v[174:175], 0, v[140:141]
	global_load_dwordx4 v[202:205], v[140:141], off
	v_add_co_u32_e32 v248, vcc, 0x400000, v140
	s_nop 1
	v_addc_co_u32_e32 v249, vcc, 0, v141, vcc
	global_load_dwordx4 v[206:209], v[248:249], off
	v_add_co_u32_e32 v248, vcc, 0x800000, v140
	s_nop 1
	v_addc_co_u32_e32 v249, vcc, 0, v141, vcc
	global_load_dwordx4 v[210:213], v[248:249], off
	v_add_co_u32_e32 v248, vcc, 0xc00000, v140
	s_nop 1
	v_addc_co_u32_e32 v249, vcc, 0, v141, vcc
	global_load_dwordx4 v[214:217], v[248:249], off
	v_add_co_u32_e32 v248, vcc, 0x1000000, v140
	s_nop 1
	v_addc_co_u32_e32 v249, vcc, 0, v141, vcc
	global_load_dwordx4 v[234:237], v[248:249], off
	v_add_co_u32_e32 v248, vcc, 0x1400000, v140
	s_nop 1
	v_addc_co_u32_e32 v249, vcc, 0, v141, vcc
	global_load_dwordx4 v[238:241], v[248:249], off
	v_add_co_u32_e32 v248, vcc, 0x1800000, v140
	s_nop 1
	v_addc_co_u32_e32 v249, vcc, 0, v141, vcc
	global_load_dwordx4 v[244:247], v[248:249], off
	s_waitcnt vmcnt(6)
	v_pk_add_f32 v[136:137], v[136:137], v[202:203]
	v_pk_add_f32 v[138:139], v[138:139], v[204:205]
	v_add_co_u32_e32 v248, vcc, 0x1c00000, v140
	s_nop 1
	v_addc_co_u32_e32 v249, vcc, 0, v141, vcc
	global_load_dwordx4 v[202:205], v[248:249], off
	s_waitcnt vmcnt(6)
	v_pk_add_f32 v[136:137], v[136:137], v[206:207]
	v_pk_add_f32 v[138:139], v[138:139], v[208:209]
	v_add_co_u32_e32 v248, vcc, 0x2000000, v140
	s_nop 1
	v_addc_co_u32_e32 v249, vcc, 0, v141, vcc
	global_load_dwordx4 v[206:209], v[248:249], off
	s_waitcnt vmcnt(6)
	v_pk_add_f32 v[136:137], v[136:137], v[210:211]
	v_pk_add_f32 v[138:139], v[138:139], v[212:213]
	v_add_co_u32_e32 v248, vcc, 0x2400000, v140
	s_nop 1
	v_addc_co_u32_e32 v249, vcc, 0, v141, vcc
	global_load_dwordx4 v[210:213], v[248:249], off
	s_waitcnt vmcnt(6)
	v_pk_add_f32 v[136:137], v[136:137], v[214:215]
	v_pk_add_f32 v[138:139], v[138:139], v[216:217]
	v_add_co_u32_e32 v248, vcc, 0x2800000, v140
	s_nop 1
	v_addc_co_u32_e32 v249, vcc, 0, v141, vcc
	global_load_dwordx4 v[214:217], v[248:249], off
	s_waitcnt vmcnt(6)
	v_pk_add_f32 v[136:137], v[136:137], v[234:235]
	v_pk_add_f32 v[138:139], v[138:139], v[236:237]
	v_add_co_u32_e32 v248, vcc, 0x2c00000, v140
	s_nop 1
	v_addc_co_u32_e32 v249, vcc, 0, v141, vcc
	global_load_dwordx4 v[234:237], v[248:249], off
	s_waitcnt vmcnt(6)
	v_pk_add_f32 v[136:137], v[136:137], v[238:239]
	v_pk_add_f32 v[138:139], v[138:139], v[240:241]
	v_add_co_u32_e32 v248, vcc, 0x3000000, v140
	s_nop 1
	v_addc_co_u32_e32 v249, vcc, 0, v141, vcc
	global_load_dwordx4 v[238:241], v[248:249], off
	s_waitcnt vmcnt(6)
	v_pk_add_f32 v[136:137], v[136:137], v[244:245]
	v_pk_add_f32 v[138:139], v[138:139], v[246:247]
	v_add_co_u32_e32 v248, vcc, 0x3400000, v140
	s_nop 1
	v_addc_co_u32_e32 v249, vcc, 0, v141, vcc
	global_load_dwordx4 v[244:247], v[248:249], off
	s_waitcnt vmcnt(6)
	v_pk_add_f32 v[136:137], v[136:137], v[202:203]
	v_pk_add_f32 v[138:139], v[138:139], v[204:205]
	v_add_co_u32_e32 v248, vcc, 0x3800000, v140
	s_nop 1
	v_addc_co_u32_e32 v249, vcc, 0, v141, vcc
	global_load_dwordx4 v[202:205], v[248:249], off
	s_waitcnt vmcnt(6)
	v_pk_add_f32 v[136:137], v[136:137], v[206:207]
	v_pk_add_f32 v[138:139], v[138:139], v[208:209]
	v_add_co_u32_e32 v248, vcc, 0x3c00000, v140
	s_nop 1
	v_addc_co_u32_e32 v249, vcc, 0, v141, vcc
	global_load_dwordx4 v[206:209], v[248:249], off
	s_waitcnt vmcnt(6)
	v_pk_add_f32 v[136:137], v[136:137], v[210:211]
	v_pk_add_f32 v[138:139], v[138:139], v[212:213]
	s_waitcnt vmcnt(5)
	v_pk_add_f32 v[136:137], v[136:137], v[214:215]
	v_pk_add_f32 v[138:139], v[138:139], v[216:217]
	s_waitcnt vmcnt(4)
	v_pk_add_f32 v[136:137], v[136:137], v[234:235]
	v_pk_add_f32 v[138:139], v[138:139], v[236:237]
	s_waitcnt vmcnt(3)
	v_pk_add_f32 v[136:137], v[136:137], v[238:239]
	v_pk_add_f32 v[138:139], v[138:139], v[240:241]
	s_waitcnt vmcnt(2)
	v_pk_add_f32 v[136:137], v[136:137], v[244:245]
	v_pk_add_f32 v[138:139], v[138:139], v[246:247]
	s_waitcnt vmcnt(1)
	v_pk_add_f32 v[136:137], v[136:137], v[202:203]
	v_pk_add_f32 v[138:139], v[138:139], v[204:205]
	s_waitcnt vmcnt(0)
	v_pk_add_f32 v[136:137], v[136:137], v[206:207]
	v_pk_add_f32 v[138:139], v[138:139], v[208:209]
	s_mov_b32 s20, 0x1400000
	s_mov_b32 s20, 0x1c00000
	s_mov_b32 s20, 0x3000000
	s_mov_b32 s20, 0x3400000
	s_mov_b32 s20, 0x3800000
; __device__ __forceinline__ float bflo(unsigned u) { return __uint_as_float(u << 16); }
; __device__ __forceinline__ float bfhi(unsigned u) { return __uint_as_float(u & 0xffff0000u); }
; __device__ __forceinline__ void ln_rows(const Params& P, const float* gam, const float* bet, const float* modU, int shidx, bool writeU, bool writeOut, int nsplit, bool skipctx) {
;     ...
;         for (int j = 0; j < 8; ++j) { const int c = ((j >> 1) * 64 + lane) * 8 + (j & 1) * 4;
;             if (!pf) {
;                 f32x4 a = *(const f32x4*)(X + (size_t)r * D + c) * ALPHA; const float* pp = (const float*)(P.ws + WS_SCTX) + ((size_t)b * 256 + p) * D + c;
;                 for (int q = 0; q < nsplit; ++q) a += *(const f32x4*)(pp + (size_t)q * 512 * D);
;                 v[j] = a; }
;             else { const unsigned t0 = (j & 1) ? ct[j >> 1].z : ct[j >> 1].x, t1 = (j & 1) ? ct[j >> 1].w : ct[j >> 1].y;
;                 v[j] = cx[j] * ALPHA + (f32x4){bflo(t0), bfhi(t0), bflo(t1), bfhi(t1)}; }
.LBB0_1440:
	s_or_b64 exec, exec, s[6:7]
	s_and_saveexec_b64 s[6:7], s[18:19]
	s_xor_b64 s[6:7], exec, s[6:7]
	v_lshlrev_b32_e32 v140, 16, v161
	v_and_b32_e32 v141, 0xffff0000, v161
	v_lshlrev_b32_e32 v142, 16, v157
	v_and_b32_e32 v143, 0xffff0000, v157
	v_pk_fma_f32 v[142:143], v[146:147], s[46:47], v[142:143] op_sel_hi:[1,0,1]
	v_pk_fma_f32 v[140:141], v[144:145], s[46:47], v[140:141] op_sel_hi:[1,0,1]
	s_andn2_saveexec_b64 s[6:7], s[6:7]
	s_cbranch_execz .LBB0_1445
	v_mov_b32_e32 v153, v3
	v_lshl_add_u64 v[140:141], v[162:163], 0, v[152:153]
	global_load_dwordx4 v[140:143], v[140:141], off
	s_and_b64 vcc, exec, s[4:5]
	s_waitcnt vmcnt(0)
	v_pk_mul_f32 v[140:141], v[140:141], s[46:47] op_sel_hi:[1,0]
	v_pk_mul_f32 v[142:143], v[142:143], s[46:47] op_sel_hi:[1,0]
	s_cbranch_vccnz .LBB0_1445
	v_lshl_add_u64 v[144:145], v[174:175], 0, v[152:153]
	global_load_dwordx4 v[202:205], v[144:145], off
	v_add_co_u32_e32 v248, vcc, 0x400000, v144
	s_nop 1
	v_addc_co_u32_e32 v249, vcc, 0, v145, vcc
	global_load_dwordx4 v[206:209], v[248:249], off
	v_add_co_u32_e32 v248, vcc, 0x800000, v144
	s_nop 1
	v_addc_co_u32_e32 v249, vcc, 0, v145, vcc
	global_load_dwordx4 v[210:213], v[248:249], off
	v_add_co_u32_e32 v248, vcc, 0xc00000, v144
	s_nop 1
	v_addc_co_u32_e32 v249, vcc, 0, v145, vcc
	global_load_dwordx4 v[214:217], v[248:249], off
	v_add_co_u32_e32 v248, vcc, 0x1000000, v144
	s_nop 1
	v_addc_co_u32_e32 v249, vcc, 0, v145, vcc
	global_load_dwordx4 v[234:237], v[248:249], off
	v_add_co_u32_e32 v248, vcc, 0x1400000, v144
	s_nop 1
	v_addc_co_u32_e32 v249, vcc, 0, v145, vcc
	global_load_dwordx4 v[238:241], v[248:249], off
	v_add_co_u32_e32 v248, vcc, 0x1800000, v144
	s_nop 1
	v_addc_co_u32_e32 v249, vcc, 0, v145, vcc
	global_load_dwordx4 v[244:247], v[248:249], off
	s_waitcnt vmcnt(6)
	v_pk_add_f32 v[140:141], v[140:141], v[202:203]
	v_pk_add_f32 v[142:143], v[142:143], v[204:205]
	v_add_co_u32_e32 v248, vcc, 0x1c00000, v144
	s_nop 1
	v_addc_co_u32_e32 v249, vcc, 0, v145, vcc
	global_load_dwordx4 v[202:205], v[248:249], off
	s_waitcnt vmcnt(6)
	v_pk_add_f32 v[140:141], v[140:141], v[206:207]
	v_pk_add_f32 v[142:143], v[142:143], v[208:209]
	v_add_co_u32_e32 v248, vcc, 0x2000000, v144
	s_nop 1
	v_addc_co_u32_e32 v249, vcc, 0, v145, vcc
	global_load_dwordx4 v[206:209], v[248:249], off
	s_waitcnt vmcnt(6)
	v_pk_add_f32 v[140:141], v[140:141], v[210:211]
	v_pk_add_f32 v[142:143], v[142:143], v[212:213]
	v_add_co_u32_e32 v248, vcc, 0x2400000, v144
	s_nop 1
	v_addc_co_u32_e32 v249, vcc, 0, v145, vcc
	global_load_dwordx4 v[210:213], v[248:249], off
	s_waitcnt vmcnt(6)
	v_pk_add_f32 v[140:141], v[140:141], v[214:215]
	v_pk_add_f32 v[142:143], v[142:143], v[216:217]
	v_add_co_u32_e32 v248, vcc, 0x2800000, v144
	s_nop 1
	v_addc_co_u32_e32 v249, vcc, 0, v145, vcc
	global_load_dwordx4 v[214:217], v[248:249], off
	s_waitcnt vmcnt(6)
	v_pk_add_f32 v[140:141], v[140:141], v[234:235]
	v_pk_add_f32 v[142:143], v[142:143], v[236:237]
	v_add_co_u32_e32 v248, vcc, 0x2c00000, v144
	s_nop 1
	v_addc_co_u32_e32 v249, vcc, 0, v145, vcc
	global_load_dwordx4 v[234:237], v[248:249], off
	s_waitcnt vmcnt(6)
	v_pk_add_f32 v[140:141], v[140:141], v[238:239]
	v_pk_add_f32 v[142:143], v[142:143], v[240:241]
	v_add_co_u32_e32 v248, vcc, 0x3000000, v144
	s_nop 1
	v_addc_co_u32_e32 v249, vcc, 0, v145, vcc
	global_load_dwordx4 v[238:241], v[248:249], off
	s_waitcnt vmcnt(6)
	v_pk_add_f32 v[140:141], v[140:141], v[244:245]
	v_pk_add_f32 v[142:143], v[142:143], v[246:247]
	v_add_co_u32_e32 v248, vcc, 0x3400000, v144
	s_nop 1
	v_addc_co_u32_e32 v249, vcc, 0, v145, vcc
	global_load_dwordx4 v[244:247], v[248:249], off
	s_waitcnt vmcnt(6)
	v_pk_add_f32 v[140:141], v[140:141], v[202:203]
	v_pk_add_f32 v[142:143], v[142:143], v[204:205]
	v_add_co_u32_e32 v248, vcc, 0x3800000, v144
	s_nop 1
	v_addc_co_u32_e32 v249, vcc, 0, v145, vcc
	global_load_dwordx4 v[202:205], v[248:249], off
	s_waitcnt vmcnt(6)
	v_pk_add_f32 v[140:141], v[140:141], v[206:207]
	v_pk_add_f32 v[142:143], v[142:143], v[208:209]
	v_add_co_u32_e32 v248, vcc, 0x3c00000, v144
	s_nop 1
	v_addc_co_u32_e32 v249, vcc, 0, v145, vcc
	global_load_dwordx4 v[206:209], v[248:249], off
	s_waitcnt vmcnt(6)
	v_pk_add_f32 v[140:141], v[140:141], v[210:211]
	v_pk_add_f32 v[142:143], v[142:143], v[212:213]
	s_waitcnt vmcnt(5)
	v_pk_add_f32 v[140:141], v[140:141], v[214:215]
	v_pk_add_f32 v[142:143], v[142:143], v[216:217]
	s_waitcnt vmcnt(4)
	v_pk_add_f32 v[140:141], v[140:141], v[234:235]
	v_pk_add_f32 v[142:143], v[142:143], v[236:237]
	s_waitcnt vmcnt(3)
	v_pk_add_f32 v[140:141], v[140:141], v[238:239]
	v_pk_add_f32 v[142:143], v[142:143], v[240:241]
	s_waitcnt vmcnt(2)
	v_pk_add_f32 v[140:141], v[140:141], v[244:245]
	v_pk_add_f32 v[142:143], v[142:143], v[246:247]
	s_waitcnt vmcnt(1)
	v_pk_add_f32 v[140:141], v[140:141], v[202:203]
	v_pk_add_f32 v[142:143], v[142:143], v[204:205]
	s_waitcnt vmcnt(0)
	v_pk_add_f32 v[140:141], v[140:141], v[206:207]
	v_pk_add_f32 v[142:143], v[142:143], v[208:209]
	s_mov_b32 s20, 0x1400000
	s_mov_b32 s20, 0x1c00000
	s_mov_b32 s20, 0x3000000
	s_mov_b32 s20, 0x3400000
	s_mov_b32 s20, 0x3800000
; __device__ __forceinline__ float bflo(unsigned u) { return __uint_as_float(u << 16); }
; __device__ __forceinline__ float bfhi(unsigned u) { return __uint_as_float(u & 0xffff0000u); }
; __device__ __forceinline__ void ln_rows(const Params& P, const float* gam, const float* bet, const float* modU, int shidx, bool writeU, bool writeOut, int nsplit, bool skipctx) {
;     ...
;         for (int j = 0; j < 8; ++j) { const int c = ((j >> 1) * 64 + lane) * 8 + (j & 1) * 4;
;             if (!pf) {
;                 f32x4 a = *(const f32x4*)(X + (size_t)r * D + c) * ALPHA; const float* pp = (const float*)(P.ws + WS_SCTX) + ((size_t)b * 256 + p) * D + c;
;                 for (int q = 0; q < nsplit; ++q) a += *(const f32x4*)(pp + (size_t)q * 512 * D);
;                 v[j] = a; }
;             else { const unsigned t0 = (j & 1) ? ct[j >> 1].z : ct[j >> 1].x, t1 = (j & 1) ? ct[j >> 1].w : ct[j >> 1].y;
;                 v[j] = cx[j] * ALPHA + (f32x4){bflo(t0), bfhi(t0), bflo(t1), bfhi(t1)}; }
.LBB0_1445:
	s_or_b64 exec, exec, s[6:7]
	s_and_saveexec_b64 s[6:7], s[18:19]
	s_xor_b64 s[6:7], exec, s[6:7]
	v_lshlrev_b32_e32 v144, 16, v155
	v_and_b32_e32 v145, 0xffff0000, v155
	v_lshlrev_b32_e32 v146, 16, v149
	v_and_b32_e32 v147, 0xffff0000, v149
	v_pk_fma_f32 v[146:147], v[172:173], s[46:47], v[146:147] op_sel_hi:[1,0,1]
	v_pk_fma_f32 v[144:145], v[170:171], s[46:47], v[144:145] op_sel_hi:[1,0,1]
	s_andn2_saveexec_b64 s[6:7], s[6:7]
	s_cbranch_execz .LBB0_1450
	v_lshlrev_b32_e32 v170, 2, v156
	v_mov_b32_e32 v171, v3
	v_lshl_add_u64 v[144:145], v[162:163], 0, v[170:171]
	global_load_dwordx4 v[144:147], v[144:145], off
	s_and_b64 vcc, exec, s[4:5]
	s_waitcnt vmcnt(0)
	v_pk_mul_f32 v[144:145], v[144:145], s[46:47] op_sel_hi:[1,0]
	v_pk_mul_f32 v[146:147], v[146:147], s[46:47] op_sel_hi:[1,0]
	s_cbranch_vccnz .LBB0_1450
	v_lshl_add_u64 v[170:171], v[174:175], 0, v[170:171]
	global_load_dwordx4 v[202:205], v[170:171], off
	v_add_co_u32_e32 v248, vcc, 0x400000, v170
	s_nop 1
	v_addc_co_u32_e32 v249, vcc, 0, v171, vcc
	global_load_dwordx4 v[206:209], v[248:249], off
	v_add_co_u32_e32 v248, vcc, 0x800000, v170
	s_nop 1
	v_addc_co_u32_e32 v249, vcc, 0, v171, vcc
	global_load_dwordx4 v[210:213], v[248:249], off
	v_add_co_u32_e32 v248, vcc, 0xc00000, v170
	s_nop 1
	v_addc_co_u32_e32 v249, vcc, 0, v171, vcc
	global_load_dwordx4 v[214:217], v[248:249], off
	v_add_co_u32_e32 v248, vcc, 0x1000000, v170
	s_nop 1
	v_addc_co_u32_e32 v249, vcc, 0, v171, vcc
	global_load_dwordx4 v[234:237], v[248:249], off
	v_add_co_u32_e32 v248, vcc, 0x1400000, v170
	s_nop 1
	v_addc_co_u32_e32 v249, vcc, 0, v171, vcc
	global_load_dwordx4 v[238:241], v[248:249], off
	v_add_co_u32_e32 v248, vcc, 0x1800000, v170
	s_nop 1
	v_addc_co_u32_e32 v249, vcc, 0, v171, vcc
	global_load_dwordx4 v[244:247], v[248:249], off
	s_waitcnt vmcnt(6)
	v_pk_add_f32 v[144:145], v[144:145], v[202:203]
	v_pk_add_f32 v[146:147], v[146:147], v[204:205]
	v_add_co_u32_e32 v248, vcc, 0x1c00000, v170
	s_nop 1
	v_addc_co_u32_e32 v249, vcc, 0, v171, vcc
	global_load_dwordx4 v[202:205], v[248:249], off
	s_waitcnt vmcnt(6)
	v_pk_add_f32 v[144:145], v[144:145], v[206:207]
	v_pk_add_f32 v[146:147], v[146:147], v[208:209]
	v_add_co_u32_e32 v248, vcc, 0x2000000, v170
	s_nop 1
	v_addc_co_u32_e32 v249, vcc, 0, v171, vcc
	global_load_dwordx4 v[206:209], v[248:249], off
	s_waitcnt vmcnt(6)
	v_pk_add_f32 v[144:145], v[144:145], v[210:211]
	v_pk_add_f32 v[146:147], v[146:147], v[212:213]
	v_add_co_u32_e32 v248, vcc, 0x2400000, v170
	s_nop 1
	v_addc_co_u32_e32 v249, vcc, 0, v171, vcc
	global_load_dwordx4 v[210:213], v[248:249], off
	s_waitcnt vmcnt(6)
	v_pk_add_f32 v[144:145], v[144:145], v[214:215]
	v_pk_add_f32 v[146:147], v[146:147], v[216:217]
	v_add_co_u32_e32 v248, vcc, 0x2800000, v170
	s_nop 1
	v_addc_co_u32_e32 v249, vcc, 0, v171, vcc
	global_load_dwordx4 v[214:217], v[248:249], off
	s_waitcnt vmcnt(6)
	v_pk_add_f32 v[144:145], v[144:145], v[234:235]
	v_pk_add_f32 v[146:147], v[146:147], v[236:237]
	v_add_co_u32_e32 v248, vcc, 0x2c00000, v170
	s_nop 1
	v_addc_co_u32_e32 v249, vcc, 0, v171, vcc
	global_load_dwordx4 v[234:237], v[248:249], off
	s_waitcnt vmcnt(6)
	v_pk_add_f32 v[144:145], v[144:145], v[238:239]
	v_pk_add_f32 v[146:147], v[146:147], v[240:241]
	v_add_co_u32_e32 v248, vcc, 0x3000000, v170
	s_nop 1
	v_addc_co_u32_e32 v249, vcc, 0, v171, vcc
	global_load_dwordx4 v[238:241], v[248:249], off
	s_waitcnt vmcnt(6)
	v_pk_add_f32 v[144:145], v[144:145], v[244:245]
	v_pk_add_f32 v[146:147], v[146:147], v[246:247]
	v_add_co_u32_e32 v248, vcc, 0x3400000, v170
	s_nop 1
	v_addc_co_u32_e32 v249, vcc, 0, v171, vcc
	global_load_dwordx4 v[244:247], v[248:249], off
	s_waitcnt vmcnt(6)
	v_pk_add_f32 v[144:145], v[144:145], v[202:203]
	v_pk_add_f32 v[146:147], v[146:147], v[204:205]
	v_add_co_u32_e32 v248, vcc, 0x3800000, v170
	s_nop 1
	v_addc_co_u32_e32 v249, vcc, 0, v171, vcc
	global_load_dwordx4 v[202:205], v[248:249], off
	s_waitcnt vmcnt(6)
	v_pk_add_f32 v[144:145], v[144:145], v[206:207]
	v_pk_add_f32 v[146:147], v[146:147], v[208:209]
	v_add_co_u32_e32 v248, vcc, 0x3c00000, v170
	s_nop 1
	v_addc_co_u32_e32 v249, vcc, 0, v171, vcc
	global_load_dwordx4 v[206:209], v[248:249], off
	s_waitcnt vmcnt(6)
	v_pk_add_f32 v[144:145], v[144:145], v[210:211]
	v_pk_add_f32 v[146:147], v[146:147], v[212:213]
	s_waitcnt vmcnt(5)
	v_pk_add_f32 v[144:145], v[144:145], v[214:215]
	v_pk_add_f32 v[146:147], v[146:147], v[216:217]
	s_waitcnt vmcnt(4)
	v_pk_add_f32 v[144:145], v[144:145], v[234:235]
	v_pk_add_f32 v[146:147], v[146:147], v[236:237]
	s_waitcnt vmcnt(3)
	v_pk_add_f32 v[144:145], v[144:145], v[238:239]
	v_pk_add_f32 v[146:147], v[146:147], v[240:241]
	s_waitcnt vmcnt(2)
	v_pk_add_f32 v[144:145], v[144:145], v[244:245]
	v_pk_add_f32 v[146:147], v[146:147], v[246:247]
	s_waitcnt vmcnt(1)
	v_pk_add_f32 v[144:145], v[144:145], v[202:203]
	v_pk_add_f32 v[146:147], v[146:147], v[204:205]
	s_waitcnt vmcnt(0)
	v_pk_add_f32 v[144:145], v[144:145], v[206:207]
	v_pk_add_f32 v[146:147], v[146:147], v[208:209]
	s_mov_b32 s4, 0x1400000
	s_mov_b32 s4, 0x1c00000
	s_mov_b32 s4, 0x3000000
	s_mov_b32 s4, 0x3400000
	s_mov_b32 s4, 0x3800000
